# mem_item QK/PV rewritten with pipelined LDS reads; EpiGate pipelined; ret_out epilogue batched; ret_state batched
# speedup vs baseline: 1.0213x; 1.0048x over previous
.LBB0_76:
	v_or_b32_e32 v95, s42, v66
	v_mov_b64_e32 v[100:101], s[26:27]
	s_mul_i32 s15, s43, 0x4200
	v_mad_u64_u32 v[98:99], s[8:9], v95, s83, v[100:101]
	v_add_u32_e32 v99, s15, v99
	s_lshl_b32 s34, s36, 1
	s_mov_b32 s35, s37
	v_lshl_add_u64 v[98:99], v[98:99], 0, s[34:35]
	v_lshl_add_u64 v[120:121], v[98:99], 0, v[96:97]
	s_mov_b64 s[4:5], s[0:1]
	s_mov_b64 s[0:1], s[96:97]
	s_mov_b64 s[96:97], s[38:39]
	s_mov_b64 s[38:39], s[94:95]
	s_mov_b64 s[94:95], s[92:93]
	s_mov_b64 s[92:93], s[56:57]
	s_mov_b64 s[56:57], s[54:55]
	s_mov_b64 s[54:55], s[52:53]
	s_mov_b64 s[52:53], s[50:51]
	s_mov_b64 s[50:51], s[48:49]
	s_mov_b64 s[48:49], s[46:47]
	s_mov_b64 s[46:47], s[78:79]
	s_mov_b64 s[78:79], s[76:77]
	s_mov_b64 s[76:77], s[74:75]
	s_mov_b64 s[74:75], s[44:45]
	s_mov_b64 s[44:45], s[70:71]
	s_mov_b64 s[70:71], s[68:69]
	s_mov_b64 s[68:69], s[66:67]
	s_mov_b64 s[66:67], s[64:65]
	s_mov_b64 s[64:65], s[62:63]
	s_mov_b64 s[62:63], s[60:61]
	s_mov_b64 s[60:61], s[72:73]
	s_mov_b64 s[72:73], s[18:19]
	s_movk_i32 s18, 0x1000
	s_lshl_b32 s36, s36, 2
	s_mov_b64 s[22:23], 0x1000
	v_lshl_add_u64 v[98:99], v[88:89], 0, s[36:37]
	v_lshl_add_u64 v[134:135], v[120:121], 0, s[22:23]
	global_load_dwordx4 v[230:233], v[98:99], off
	global_load_dwordx4 v[234:237], v[98:99], off offset:64
	global_load_dwordx2 v[182:183], v[134:135], off
	global_load_dwordx2 v[184:185], v[134:135], off offset:32
	ds_read2st64_b32 v[238:239], v103 offset1:2
	ds_read2st64_b32 v[240:241], v103 offset0:4 offset1:6
	ds_read2st64_b32 v[242:243], v103 offset0:8 offset1:10
	ds_read2st64_b32 v[244:245], v103 offset0:12 offset1:14
	v_or_b32_e32 v95, s42, v74
	v_mad_u64_u32 v[136:137], s[8:9], v95, s83, v[100:101]
	v_add_u32_e32 v137, s15, v137
	v_lshl_add_u64 v[136:137], v[136:137], 0, s[34:35]
	v_lshl_add_u64 v[136:137], v[136:137], 0, v[96:97]
	v_lshl_add_u64 v[136:137], v[136:137], 0, s[22:23]
	global_load_dwordx2 v[186:187], v[136:137], off
	global_load_dwordx2 v[188:189], v[136:137], off offset:32
	v_or_b32_e32 v95, s42, v76
	v_mad_u64_u32 v[138:139], s[8:9], v95, s83, v[100:101]
	v_add_u32_e32 v139, s15, v139
	v_lshl_add_u64 v[138:139], v[138:139], 0, s[34:35]
	v_lshl_add_u64 v[138:139], v[138:139], 0, v[96:97]
	v_lshl_add_u64 v[138:139], v[138:139], 0, s[22:23]
	global_load_dwordx2 v[190:191], v[138:139], off
	global_load_dwordx2 v[192:193], v[138:139], off offset:32
	v_or_b32_e32 v95, s42, v78
	v_mad_u64_u32 v[140:141], s[8:9], v95, s83, v[100:101]
	v_add_u32_e32 v141, s15, v141
	v_lshl_add_u64 v[140:141], v[140:141], 0, s[34:35]
	v_lshl_add_u64 v[140:141], v[140:141], 0, v[96:97]
	v_lshl_add_u64 v[140:141], v[140:141], 0, s[22:23]
	global_load_dwordx2 v[210:211], v[140:141], off
	global_load_dwordx2 v[212:213], v[140:141], off offset:32
	v_or_b32_e32 v95, s42, v80
	v_mad_u64_u32 v[142:143], s[8:9], v95, s83, v[100:101]
	v_add_u32_e32 v143, s15, v143
	v_lshl_add_u64 v[142:143], v[142:143], 0, s[34:35]
	v_lshl_add_u64 v[142:143], v[142:143], 0, v[96:97]
	v_lshl_add_u64 v[142:143], v[142:143], 0, s[22:23]
	global_load_dwordx2 v[214:215], v[142:143], off
	global_load_dwordx2 v[216:217], v[142:143], off offset:32
	v_or_b32_e32 v95, s42, v82
	v_mad_u64_u32 v[144:145], s[8:9], v95, s83, v[100:101]
	v_add_u32_e32 v145, s15, v145
	v_lshl_add_u64 v[144:145], v[144:145], 0, s[34:35]
	v_lshl_add_u64 v[144:145], v[144:145], 0, v[96:97]
	v_lshl_add_u64 v[144:145], v[144:145], 0, s[22:23]
	global_load_dwordx2 v[218:219], v[144:145], off
	global_load_dwordx2 v[220:221], v[144:145], off offset:32
	v_or_b32_e32 v95, s42, v84
	v_mad_u64_u32 v[148:149], s[8:9], v95, s83, v[100:101]
	v_add_u32_e32 v149, s15, v149
	v_lshl_add_u64 v[148:149], v[148:149], 0, s[34:35]
	v_lshl_add_u64 v[148:149], v[148:149], 0, v[96:97]
	v_lshl_add_u64 v[148:149], v[148:149], 0, s[22:23]
	global_load_dwordx2 v[222:223], v[148:149], off
	global_load_dwordx2 v[224:225], v[148:149], off offset:32
	v_or_b32_e32 v95, s42, v86
	v_mad_u64_u32 v[150:151], s[8:9], v95, s83, v[100:101]
	v_add_u32_e32 v151, s15, v151
	v_lshl_add_u64 v[150:151], v[150:151], 0, s[34:35]
	v_lshl_add_u64 v[150:151], v[150:151], 0, v[96:97]
	v_lshl_add_u64 v[150:151], v[150:151], 0, s[22:23]
	global_load_dwordx2 v[226:227], v[150:151], off
	global_load_dwordx2 v[228:229], v[150:151], off offset:32
	ds_read2st64_b32 v[122:123], v105 offset1:2
	ds_read2st64_b32 v[124:125], v105 offset0:4 offset1:6
	ds_read2st64_b32 v[126:127], v105 offset0:8 offset1:10
	ds_read2st64_b32 v[128:129], v105 offset0:12 offset1:14
	s_waitcnt lgkmcnt(4)
	v_add_f32_e32 v95, 0, v238
	v_add_f32_e32 v95, v95, v239
	v_add_f32_e32 v95, v95, v240
	v_add_f32_e32 v95, v95, v241
	v_add_f32_e32 v95, v95, v242
	v_add_f32_e32 v95, v95, v243
	v_add_f32_e32 v95, v95, v244
	v_add_f32_e32 v95, v95, v245
	v_fmamk_f32 v95, v95, 0x3b800000, v196
	v_mul_f32_e32 v119, 0x4b800000, v95
	v_cmp_gt_f32_e32 vcc, s84, v95
	s_nop 1
	v_cndmask_b32_e32 v95, v95, v119, vcc
	v_rsq_f32_e32 v95, v95
	s_nop 0
	v_mul_f32_e32 v119, 0x45800000, v95
	v_cndmask_b32_e32 v95, v95, v119, vcc
	v_mul_f32_e32 v64, v64, v95
	v_mul_f32_e32 v63, v63, v95
	v_mul_f32_e32 v62, v62, v95
	v_mul_f32_e32 v65, v65, v95
	v_mul_f32_e32 v60, v60, v95
	v_mul_f32_e32 v59, v59, v95
	v_mul_f32_e32 v58, v58, v95
	v_mul_f32_e32 v61, v61, v95
	s_waitcnt vmcnt(15)
	v_mul_f32_e32 v62, v230, v62
	v_mul_f32_e32 v63, v231, v63
	v_mul_f32_e32 v64, v232, v64
	v_mul_f32_e32 v65, v233, v65
	v_lshlrev_b32_e32 v115, 16, v182
	v_and_b32_e32 v116, 0xffff0000, v182
	v_lshlrev_b32_e32 v117, 16, v183
	v_and_b32_e32 v118, 0xffff0000, v183
	v_mul_f32_e32 v130, 0xbfb8aa3b, v115
	v_mul_f32_e32 v131, 0xbfb8aa3b, v116
	v_mul_f32_e32 v132, 0xbfb8aa3b, v117
	v_mul_f32_e32 v133, 0xbfb8aa3b, v118
	v_mul_f32_e32 v62, v62, v115
	v_mul_f32_e32 v63, v63, v116
	v_mul_f32_e32 v64, v64, v117
	v_mul_f32_e32 v65, v65, v118
	v_exp_f32_e32 v130, v130
	v_exp_f32_e32 v131, v131
	v_exp_f32_e32 v132, v132
	v_exp_f32_e32 v133, v133
	v_add_f32_e32 v130, 1.0, v130
	v_add_f32_e32 v131, 1.0, v131
	v_add_f32_e32 v132, 1.0, v132
	v_add_f32_e32 v133, 1.0, v133
	v_rcp_f32_e32 v130, v130
	v_rcp_f32_e32 v131, v131
	v_rcp_f32_e32 v132, v132
	v_rcp_f32_e32 v133, v133
	v_mul_f32_e32 v62, v130, v62
	v_mul_f32_e32 v63, v131, v63
	v_mul_f32_e32 v64, v132, v64
	v_mul_f32_e32 v65, v133, v65
	v_cvt_pk_bf16_f32 v62, v62, v63
	v_cvt_pk_bf16_f32 v63, v64, v65
	global_store_dwordx2 v[134:135], v[62:63], off
	s_waitcnt vmcnt(15)
	v_mul_f32_e32 v58, v234, v58
	v_mul_f32_e32 v59, v235, v59
	v_mul_f32_e32 v60, v236, v60
	v_mul_f32_e32 v61, v237, v61
	v_lshlrev_b32_e32 v115, 16, v184
	v_and_b32_e32 v116, 0xffff0000, v184
	v_lshlrev_b32_e32 v117, 16, v185
	v_and_b32_e32 v118, 0xffff0000, v185
	v_mul_f32_e32 v130, 0xbfb8aa3b, v115
	v_mul_f32_e32 v131, 0xbfb8aa3b, v116
	v_mul_f32_e32 v132, 0xbfb8aa3b, v117
	v_mul_f32_e32 v133, 0xbfb8aa3b, v118
	v_mul_f32_e32 v58, v58, v115
	v_mul_f32_e32 v59, v59, v116
	v_mul_f32_e32 v60, v60, v117
	v_mul_f32_e32 v61, v61, v118
	v_exp_f32_e32 v130, v130
	v_exp_f32_e32 v131, v131
	v_exp_f32_e32 v132, v132
	v_exp_f32_e32 v133, v133
	v_add_f32_e32 v130, 1.0, v130
	v_add_f32_e32 v131, 1.0, v131
	v_add_f32_e32 v132, 1.0, v132
	v_add_f32_e32 v133, 1.0, v133
	v_rcp_f32_e32 v130, v130
	v_rcp_f32_e32 v131, v131
	v_rcp_f32_e32 v132, v132
	v_rcp_f32_e32 v133, v133
	v_mul_f32_e32 v58, v130, v58
	v_mul_f32_e32 v59, v131, v59
	v_mul_f32_e32 v60, v132, v60
	v_mul_f32_e32 v61, v133, v61
	v_cvt_pk_bf16_f32 v58, v58, v59
	v_cvt_pk_bf16_f32 v59, v60, v61
	global_store_dwordx2 v[134:135], v[58:59], off offset:32
	ds_read2st64_b32 v[238:239], v106 offset1:2
	ds_read2st64_b32 v[240:241], v106 offset0:4 offset1:6
	ds_read2st64_b32 v[242:243], v106 offset0:8 offset1:10
	ds_read2st64_b32 v[244:245], v106 offset0:12 offset1:14
	s_waitcnt lgkmcnt(4)
	v_add_f32_e32 v95, 0, v122
	v_add_f32_e32 v95, v95, v123
	v_add_f32_e32 v95, v95, v124
	v_add_f32_e32 v95, v95, v125
	v_add_f32_e32 v95, v95, v126
	v_add_f32_e32 v95, v95, v127
	v_add_f32_e32 v95, v95, v128
	v_add_f32_e32 v95, v95, v129
	v_fmamk_f32 v95, v95, 0x3b800000, v196
	v_mul_f32_e32 v119, 0x4b800000, v95
	v_cmp_gt_f32_e32 vcc, s84, v95
	s_nop 1
	v_cndmask_b32_e32 v95, v95, v119, vcc
	v_rsq_f32_e32 v95, v95
	s_nop 0
	v_mul_f32_e32 v119, 0x45800000, v95
	v_cndmask_b32_e32 v95, v95, v119, vcc
	v_mul_f32_e32 v56, v56, v95
	v_mul_f32_e32 v55, v55, v95
	v_mul_f32_e32 v54, v54, v95
	v_mul_f32_e32 v57, v57, v95
	v_mul_f32_e32 v52, v52, v95
	v_mul_f32_e32 v51, v51, v95
	v_mul_f32_e32 v50, v50, v95
	v_mul_f32_e32 v53, v53, v95
	s_waitcnt vmcnt(15)
	v_mul_f32_e32 v54, v230, v54
	v_mul_f32_e32 v55, v231, v55
	v_mul_f32_e32 v56, v232, v56
	v_mul_f32_e32 v57, v233, v57
	v_lshlrev_b32_e32 v115, 16, v186
	v_and_b32_e32 v116, 0xffff0000, v186
	v_lshlrev_b32_e32 v117, 16, v187
	v_and_b32_e32 v118, 0xffff0000, v187
	v_mul_f32_e32 v130, 0xbfb8aa3b, v115
	v_mul_f32_e32 v131, 0xbfb8aa3b, v116
	v_mul_f32_e32 v132, 0xbfb8aa3b, v117
	v_mul_f32_e32 v133, 0xbfb8aa3b, v118
	v_mul_f32_e32 v54, v54, v115
	v_mul_f32_e32 v55, v55, v116
	v_mul_f32_e32 v56, v56, v117
	v_mul_f32_e32 v57, v57, v118
	v_exp_f32_e32 v130, v130
	v_exp_f32_e32 v131, v131
	v_exp_f32_e32 v132, v132
	v_exp_f32_e32 v133, v133
	v_add_f32_e32 v130, 1.0, v130
	v_add_f32_e32 v131, 1.0, v131
	v_add_f32_e32 v132, 1.0, v132
	v_add_f32_e32 v133, 1.0, v133
	v_rcp_f32_e32 v130, v130
	v_rcp_f32_e32 v131, v131
	v_rcp_f32_e32 v132, v132
	v_rcp_f32_e32 v133, v133
	v_mul_f32_e32 v54, v130, v54
	v_mul_f32_e32 v55, v131, v55
	v_mul_f32_e32 v56, v132, v56
	v_mul_f32_e32 v57, v133, v57
	v_cvt_pk_bf16_f32 v54, v54, v55
	v_cvt_pk_bf16_f32 v55, v56, v57
	global_store_dwordx2 v[136:137], v[54:55], off
	s_waitcnt vmcnt(15)
	v_mul_f32_e32 v50, v234, v50
	v_mul_f32_e32 v51, v235, v51
	v_mul_f32_e32 v52, v236, v52
	v_mul_f32_e32 v53, v237, v53
	v_lshlrev_b32_e32 v115, 16, v188
	v_and_b32_e32 v116, 0xffff0000, v188
	v_lshlrev_b32_e32 v117, 16, v189
	v_and_b32_e32 v118, 0xffff0000, v189
	v_mul_f32_e32 v130, 0xbfb8aa3b, v115
	v_mul_f32_e32 v131, 0xbfb8aa3b, v116
	v_mul_f32_e32 v132, 0xbfb8aa3b, v117
	v_mul_f32_e32 v133, 0xbfb8aa3b, v118
	v_mul_f32_e32 v50, v50, v115
	v_mul_f32_e32 v51, v51, v116
	v_mul_f32_e32 v52, v52, v117
	v_mul_f32_e32 v53, v53, v118
	v_exp_f32_e32 v130, v130
	v_exp_f32_e32 v131, v131
	v_exp_f32_e32 v132, v132
	v_exp_f32_e32 v133, v133
	v_add_f32_e32 v130, 1.0, v130
	v_add_f32_e32 v131, 1.0, v131
	v_add_f32_e32 v132, 1.0, v132
	v_add_f32_e32 v133, 1.0, v133
	v_rcp_f32_e32 v130, v130
	v_rcp_f32_e32 v131, v131
	v_rcp_f32_e32 v132, v132
	v_rcp_f32_e32 v133, v133
	v_mul_f32_e32 v50, v130, v50
	v_mul_f32_e32 v51, v131, v51
	v_mul_f32_e32 v52, v132, v52
	v_mul_f32_e32 v53, v133, v53
	v_cvt_pk_bf16_f32 v50, v50, v51
	v_cvt_pk_bf16_f32 v51, v52, v53
	global_store_dwordx2 v[136:137], v[50:51], off offset:32
	ds_read2st64_b32 v[122:123], v107 offset1:2
	ds_read2st64_b32 v[124:125], v107 offset0:4 offset1:6
	ds_read2st64_b32 v[126:127], v107 offset0:8 offset1:10
	ds_read2st64_b32 v[128:129], v107 offset0:12 offset1:14
	s_waitcnt lgkmcnt(4)
	v_add_f32_e32 v95, 0, v238
	v_add_f32_e32 v95, v95, v239
	v_add_f32_e32 v95, v95, v240
	v_add_f32_e32 v95, v95, v241
	v_add_f32_e32 v95, v95, v242
	v_add_f32_e32 v95, v95, v243
	v_add_f32_e32 v95, v95, v244
	v_add_f32_e32 v95, v95, v245
	v_fmamk_f32 v95, v95, 0x3b800000, v196
	v_mul_f32_e32 v119, 0x4b800000, v95
	v_cmp_gt_f32_e32 vcc, s84, v95
	s_nop 1
	v_cndmask_b32_e32 v95, v95, v119, vcc
	v_rsq_f32_e32 v95, v95
	s_nop 0
	v_mul_f32_e32 v119, 0x45800000, v95
	v_cndmask_b32_e32 v95, v95, v119, vcc
	v_mul_f32_e32 v48, v48, v95
	v_mul_f32_e32 v47, v47, v95
	v_mul_f32_e32 v46, v46, v95
	v_mul_f32_e32 v49, v49, v95
	v_mul_f32_e32 v44, v44, v95
	v_mul_f32_e32 v43, v43, v95
	v_mul_f32_e32 v42, v42, v95
	v_mul_f32_e32 v45, v45, v95
	s_waitcnt vmcnt(15)
	v_mul_f32_e32 v46, v230, v46
	v_mul_f32_e32 v47, v231, v47
	v_mul_f32_e32 v48, v232, v48
	v_mul_f32_e32 v49, v233, v49
	v_lshlrev_b32_e32 v115, 16, v190
	v_and_b32_e32 v116, 0xffff0000, v190
	v_lshlrev_b32_e32 v117, 16, v191
	v_and_b32_e32 v118, 0xffff0000, v191
	v_mul_f32_e32 v130, 0xbfb8aa3b, v115
	v_mul_f32_e32 v131, 0xbfb8aa3b, v116
	v_mul_f32_e32 v132, 0xbfb8aa3b, v117
	v_mul_f32_e32 v133, 0xbfb8aa3b, v118
	v_mul_f32_e32 v46, v46, v115
	v_mul_f32_e32 v47, v47, v116
	v_mul_f32_e32 v48, v48, v117
	v_mul_f32_e32 v49, v49, v118
	v_exp_f32_e32 v130, v130
	v_exp_f32_e32 v131, v131
	v_exp_f32_e32 v132, v132
	v_exp_f32_e32 v133, v133
	v_add_f32_e32 v130, 1.0, v130
	v_add_f32_e32 v131, 1.0, v131
	v_add_f32_e32 v132, 1.0, v132
	v_add_f32_e32 v133, 1.0, v133
	v_rcp_f32_e32 v130, v130
	v_rcp_f32_e32 v131, v131
	v_rcp_f32_e32 v132, v132
	v_rcp_f32_e32 v133, v133
	v_mul_f32_e32 v46, v130, v46
	v_mul_f32_e32 v47, v131, v47
	v_mul_f32_e32 v48, v132, v48
	v_mul_f32_e32 v49, v133, v49
	v_cvt_pk_bf16_f32 v46, v46, v47
	v_cvt_pk_bf16_f32 v47, v48, v49
	global_store_dwordx2 v[138:139], v[46:47], off
	s_waitcnt vmcnt(15)
	v_mul_f32_e32 v42, v234, v42
	v_mul_f32_e32 v43, v235, v43
	v_mul_f32_e32 v44, v236, v44
	v_mul_f32_e32 v45, v237, v45
	v_lshlrev_b32_e32 v115, 16, v192
	v_and_b32_e32 v116, 0xffff0000, v192
	v_lshlrev_b32_e32 v117, 16, v193
	v_and_b32_e32 v118, 0xffff0000, v193
	v_mul_f32_e32 v130, 0xbfb8aa3b, v115
	v_mul_f32_e32 v131, 0xbfb8aa3b, v116
	v_mul_f32_e32 v132, 0xbfb8aa3b, v117
	v_mul_f32_e32 v133, 0xbfb8aa3b, v118
	v_mul_f32_e32 v42, v42, v115
	v_mul_f32_e32 v43, v43, v116
	v_mul_f32_e32 v44, v44, v117
	v_mul_f32_e32 v45, v45, v118
	v_exp_f32_e32 v130, v130
	v_exp_f32_e32 v131, v131
	v_exp_f32_e32 v132, v132
	v_exp_f32_e32 v133, v133
	v_add_f32_e32 v130, 1.0, v130
	v_add_f32_e32 v131, 1.0, v131
	v_add_f32_e32 v132, 1.0, v132
	v_add_f32_e32 v133, 1.0, v133
	v_rcp_f32_e32 v130, v130
	v_rcp_f32_e32 v131, v131
	v_rcp_f32_e32 v132, v132
	v_rcp_f32_e32 v133, v133
	v_mul_f32_e32 v42, v130, v42
	v_mul_f32_e32 v43, v131, v43
	v_mul_f32_e32 v44, v132, v44
	v_mul_f32_e32 v45, v133, v45
	v_cvt_pk_bf16_f32 v42, v42, v43
	v_cvt_pk_bf16_f32 v43, v44, v45
	global_store_dwordx2 v[138:139], v[42:43], off offset:32
	ds_read2st64_b32 v[238:239], v108 offset1:2
	ds_read2st64_b32 v[240:241], v108 offset0:4 offset1:6
	ds_read2st64_b32 v[242:243], v108 offset0:8 offset1:10
	ds_read2st64_b32 v[244:245], v108 offset0:12 offset1:14
	s_waitcnt lgkmcnt(4)
	v_add_f32_e32 v95, 0, v122
	v_add_f32_e32 v95, v95, v123
	v_add_f32_e32 v95, v95, v124
	v_add_f32_e32 v95, v95, v125
	v_add_f32_e32 v95, v95, v126
	v_add_f32_e32 v95, v95, v127
	v_add_f32_e32 v95, v95, v128
	v_add_f32_e32 v95, v95, v129
	v_fmamk_f32 v95, v95, 0x3b800000, v196
	v_mul_f32_e32 v119, 0x4b800000, v95
	v_cmp_gt_f32_e32 vcc, s84, v95
	s_nop 1
	v_cndmask_b32_e32 v95, v95, v119, vcc
	v_rsq_f32_e32 v95, v95
	s_nop 0
	v_mul_f32_e32 v119, 0x45800000, v95
	v_cndmask_b32_e32 v95, v95, v119, vcc
	v_mul_f32_e32 v40, v40, v95
	v_mul_f32_e32 v39, v39, v95
	v_mul_f32_e32 v38, v38, v95
	v_mul_f32_e32 v41, v41, v95
	v_mul_f32_e32 v36, v36, v95
	v_mul_f32_e32 v35, v35, v95
	v_mul_f32_e32 v34, v34, v95
	v_mul_f32_e32 v37, v37, v95
	s_waitcnt vmcnt(15)
	v_mul_f32_e32 v38, v230, v38
	v_mul_f32_e32 v39, v231, v39
	v_mul_f32_e32 v40, v232, v40
	v_mul_f32_e32 v41, v233, v41
	v_lshlrev_b32_e32 v115, 16, v210
	v_and_b32_e32 v116, 0xffff0000, v210
	v_lshlrev_b32_e32 v117, 16, v211
	v_and_b32_e32 v118, 0xffff0000, v211
	v_mul_f32_e32 v130, 0xbfb8aa3b, v115
	v_mul_f32_e32 v131, 0xbfb8aa3b, v116
	v_mul_f32_e32 v132, 0xbfb8aa3b, v117
	v_mul_f32_e32 v133, 0xbfb8aa3b, v118
	v_mul_f32_e32 v38, v38, v115
	v_mul_f32_e32 v39, v39, v116
	v_mul_f32_e32 v40, v40, v117
	v_mul_f32_e32 v41, v41, v118
	v_exp_f32_e32 v130, v130
	v_exp_f32_e32 v131, v131
	v_exp_f32_e32 v132, v132
	v_exp_f32_e32 v133, v133
	v_add_f32_e32 v130, 1.0, v130
	v_add_f32_e32 v131, 1.0, v131
	v_add_f32_e32 v132, 1.0, v132
	v_add_f32_e32 v133, 1.0, v133
	v_rcp_f32_e32 v130, v130
	v_rcp_f32_e32 v131, v131
	v_rcp_f32_e32 v132, v132
	v_rcp_f32_e32 v133, v133
	v_mul_f32_e32 v38, v130, v38
	v_mul_f32_e32 v39, v131, v39
	v_mul_f32_e32 v40, v132, v40
	v_mul_f32_e32 v41, v133, v41
	v_cvt_pk_bf16_f32 v38, v38, v39
	v_cvt_pk_bf16_f32 v39, v40, v41
	global_store_dwordx2 v[140:141], v[38:39], off
	s_waitcnt vmcnt(15)
	v_mul_f32_e32 v34, v234, v34
	v_mul_f32_e32 v35, v235, v35
	v_mul_f32_e32 v36, v236, v36
	v_mul_f32_e32 v37, v237, v37
	v_lshlrev_b32_e32 v115, 16, v212
	v_and_b32_e32 v116, 0xffff0000, v212
	v_lshlrev_b32_e32 v117, 16, v213
	v_and_b32_e32 v118, 0xffff0000, v213
	v_mul_f32_e32 v130, 0xbfb8aa3b, v115
	v_mul_f32_e32 v131, 0xbfb8aa3b, v116
	v_mul_f32_e32 v132, 0xbfb8aa3b, v117
	v_mul_f32_e32 v133, 0xbfb8aa3b, v118
	v_mul_f32_e32 v34, v34, v115
	v_mul_f32_e32 v35, v35, v116
	v_mul_f32_e32 v36, v36, v117
	v_mul_f32_e32 v37, v37, v118
	v_exp_f32_e32 v130, v130
	v_exp_f32_e32 v131, v131
	v_exp_f32_e32 v132, v132
	v_exp_f32_e32 v133, v133
	v_add_f32_e32 v130, 1.0, v130
	v_add_f32_e32 v131, 1.0, v131
	v_add_f32_e32 v132, 1.0, v132
	v_add_f32_e32 v133, 1.0, v133
	v_rcp_f32_e32 v130, v130
	v_rcp_f32_e32 v131, v131
	v_rcp_f32_e32 v132, v132
	v_rcp_f32_e32 v133, v133
	v_mul_f32_e32 v34, v130, v34
	v_mul_f32_e32 v35, v131, v35
	v_mul_f32_e32 v36, v132, v36
	v_mul_f32_e32 v37, v133, v37
	v_cvt_pk_bf16_f32 v34, v34, v35
	v_cvt_pk_bf16_f32 v35, v36, v37
	global_store_dwordx2 v[140:141], v[34:35], off offset:32
	ds_read2st64_b32 v[122:123], v109 offset1:2
	ds_read2st64_b32 v[124:125], v109 offset0:4 offset1:6
	ds_read2st64_b32 v[126:127], v109 offset0:8 offset1:10
	ds_read2st64_b32 v[128:129], v109 offset0:12 offset1:14
	s_waitcnt lgkmcnt(4)
	v_add_f32_e32 v95, 0, v238
	v_add_f32_e32 v95, v95, v239
	v_add_f32_e32 v95, v95, v240
	v_add_f32_e32 v95, v95, v241
	v_add_f32_e32 v95, v95, v242
	v_add_f32_e32 v95, v95, v243
	v_add_f32_e32 v95, v95, v244
	v_add_f32_e32 v95, v95, v245
	v_fmamk_f32 v95, v95, 0x3b800000, v196
	v_mul_f32_e32 v119, 0x4b800000, v95
	v_cmp_gt_f32_e32 vcc, s84, v95
	s_nop 1
	v_cndmask_b32_e32 v95, v95, v119, vcc
	v_rsq_f32_e32 v95, v95
	s_nop 0
	v_mul_f32_e32 v119, 0x45800000, v95
	v_cndmask_b32_e32 v95, v95, v119, vcc
	v_mul_f32_e32 v32, v32, v95
	v_mul_f32_e32 v31, v31, v95
	v_mul_f32_e32 v30, v30, v95
	v_mul_f32_e32 v33, v33, v95
	v_mul_f32_e32 v28, v28, v95
	v_mul_f32_e32 v27, v27, v95
	v_mul_f32_e32 v26, v26, v95
	v_mul_f32_e32 v29, v29, v95
	s_waitcnt vmcnt(15)
	v_mul_f32_e32 v30, v230, v30
	v_mul_f32_e32 v31, v231, v31
	v_mul_f32_e32 v32, v232, v32
	v_mul_f32_e32 v33, v233, v33
	v_lshlrev_b32_e32 v115, 16, v214
	v_and_b32_e32 v116, 0xffff0000, v214
	v_lshlrev_b32_e32 v117, 16, v215
	v_and_b32_e32 v118, 0xffff0000, v215
	v_mul_f32_e32 v130, 0xbfb8aa3b, v115
	v_mul_f32_e32 v131, 0xbfb8aa3b, v116
	v_mul_f32_e32 v132, 0xbfb8aa3b, v117
	v_mul_f32_e32 v133, 0xbfb8aa3b, v118
	v_mul_f32_e32 v30, v30, v115
	v_mul_f32_e32 v31, v31, v116
	v_mul_f32_e32 v32, v32, v117
	v_mul_f32_e32 v33, v33, v118
	v_exp_f32_e32 v130, v130
	v_exp_f32_e32 v131, v131
	v_exp_f32_e32 v132, v132
	v_exp_f32_e32 v133, v133
	v_add_f32_e32 v130, 1.0, v130
	v_add_f32_e32 v131, 1.0, v131
	v_add_f32_e32 v132, 1.0, v132
	v_add_f32_e32 v133, 1.0, v133
	v_rcp_f32_e32 v130, v130
	v_rcp_f32_e32 v131, v131
	v_rcp_f32_e32 v132, v132
	v_rcp_f32_e32 v133, v133
	v_mul_f32_e32 v30, v130, v30
	v_mul_f32_e32 v31, v131, v31
	v_mul_f32_e32 v32, v132, v32
	v_mul_f32_e32 v33, v133, v33
	v_cvt_pk_bf16_f32 v30, v30, v31
	v_cvt_pk_bf16_f32 v31, v32, v33
	global_store_dwordx2 v[142:143], v[30:31], off
	s_waitcnt vmcnt(15)
	v_mul_f32_e32 v26, v234, v26
	v_mul_f32_e32 v27, v235, v27
	v_mul_f32_e32 v28, v236, v28
	v_mul_f32_e32 v29, v237, v29
	v_lshlrev_b32_e32 v115, 16, v216
	v_and_b32_e32 v116, 0xffff0000, v216
	v_lshlrev_b32_e32 v117, 16, v217
	v_and_b32_e32 v118, 0xffff0000, v217
	v_mul_f32_e32 v130, 0xbfb8aa3b, v115
	v_mul_f32_e32 v131, 0xbfb8aa3b, v116
	v_mul_f32_e32 v132, 0xbfb8aa3b, v117
	v_mul_f32_e32 v133, 0xbfb8aa3b, v118
	v_mul_f32_e32 v26, v26, v115
	v_mul_f32_e32 v27, v27, v116
	v_mul_f32_e32 v28, v28, v117
	v_mul_f32_e32 v29, v29, v118
	v_exp_f32_e32 v130, v130
	v_exp_f32_e32 v131, v131
	v_exp_f32_e32 v132, v132
	v_exp_f32_e32 v133, v133
	v_add_f32_e32 v130, 1.0, v130
	v_add_f32_e32 v131, 1.0, v131
	v_add_f32_e32 v132, 1.0, v132
	v_add_f32_e32 v133, 1.0, v133
	v_rcp_f32_e32 v130, v130
	v_rcp_f32_e32 v131, v131
	v_rcp_f32_e32 v132, v132
	v_rcp_f32_e32 v133, v133
	v_mul_f32_e32 v26, v130, v26
	v_mul_f32_e32 v27, v131, v27
	v_mul_f32_e32 v28, v132, v28
	v_mul_f32_e32 v29, v133, v29
	v_cvt_pk_bf16_f32 v26, v26, v27
	v_cvt_pk_bf16_f32 v27, v28, v29
	global_store_dwordx2 v[142:143], v[26:27], off offset:32
	ds_read2st64_b32 v[238:239], v110 offset1:2
	ds_read2st64_b32 v[240:241], v110 offset0:4 offset1:6
	ds_read2st64_b32 v[242:243], v110 offset0:8 offset1:10
	ds_read2st64_b32 v[244:245], v110 offset0:12 offset1:14
	s_waitcnt lgkmcnt(4)
	v_add_f32_e32 v95, 0, v122
	v_add_f32_e32 v95, v95, v123
	v_add_f32_e32 v95, v95, v124
	v_add_f32_e32 v95, v95, v125
	v_add_f32_e32 v95, v95, v126
	v_add_f32_e32 v95, v95, v127
	v_add_f32_e32 v95, v95, v128
	v_add_f32_e32 v95, v95, v129
	v_fmamk_f32 v95, v95, 0x3b800000, v196
	v_mul_f32_e32 v119, 0x4b800000, v95
	v_cmp_gt_f32_e32 vcc, s84, v95
	s_nop 1
	v_cndmask_b32_e32 v95, v95, v119, vcc
	v_rsq_f32_e32 v95, v95
	s_nop 0
	v_mul_f32_e32 v119, 0x45800000, v95
	v_cndmask_b32_e32 v95, v95, v119, vcc
	v_mul_f32_e32 v24, v24, v95
	v_mul_f32_e32 v23, v23, v95
	v_mul_f32_e32 v22, v22, v95
	v_mul_f32_e32 v25, v25, v95
	v_mul_f32_e32 v20, v20, v95
	v_mul_f32_e32 v19, v19, v95
	v_mul_f32_e32 v18, v18, v95
	v_mul_f32_e32 v21, v21, v95
	s_waitcnt vmcnt(15)
	v_mul_f32_e32 v22, v230, v22
	v_mul_f32_e32 v23, v231, v23
	v_mul_f32_e32 v24, v232, v24
	v_mul_f32_e32 v25, v233, v25
	v_lshlrev_b32_e32 v115, 16, v218
	v_and_b32_e32 v116, 0xffff0000, v218
	v_lshlrev_b32_e32 v117, 16, v219
	v_and_b32_e32 v118, 0xffff0000, v219
	v_mul_f32_e32 v130, 0xbfb8aa3b, v115
	v_mul_f32_e32 v131, 0xbfb8aa3b, v116
	v_mul_f32_e32 v132, 0xbfb8aa3b, v117
	v_mul_f32_e32 v133, 0xbfb8aa3b, v118
	v_mul_f32_e32 v22, v22, v115
	v_mul_f32_e32 v23, v23, v116
	v_mul_f32_e32 v24, v24, v117
	v_mul_f32_e32 v25, v25, v118
	v_exp_f32_e32 v130, v130
	v_exp_f32_e32 v131, v131
	v_exp_f32_e32 v132, v132
	v_exp_f32_e32 v133, v133
	v_add_f32_e32 v130, 1.0, v130
	v_add_f32_e32 v131, 1.0, v131
	v_add_f32_e32 v132, 1.0, v132
	v_add_f32_e32 v133, 1.0, v133
	v_rcp_f32_e32 v130, v130
	v_rcp_f32_e32 v131, v131
	v_rcp_f32_e32 v132, v132
	v_rcp_f32_e32 v133, v133
	v_mul_f32_e32 v22, v130, v22
	v_mul_f32_e32 v23, v131, v23
	v_mul_f32_e32 v24, v132, v24
	v_mul_f32_e32 v25, v133, v25
	v_cvt_pk_bf16_f32 v22, v22, v23
	v_cvt_pk_bf16_f32 v23, v24, v25
	global_store_dwordx2 v[144:145], v[22:23], off
	s_waitcnt vmcnt(15)
	v_mul_f32_e32 v18, v234, v18
	v_mul_f32_e32 v19, v235, v19
	v_mul_f32_e32 v20, v236, v20
	v_mul_f32_e32 v21, v237, v21
	v_lshlrev_b32_e32 v115, 16, v220
	v_and_b32_e32 v116, 0xffff0000, v220
	v_lshlrev_b32_e32 v117, 16, v221
	v_and_b32_e32 v118, 0xffff0000, v221
	v_mul_f32_e32 v130, 0xbfb8aa3b, v115
	v_mul_f32_e32 v131, 0xbfb8aa3b, v116
	v_mul_f32_e32 v132, 0xbfb8aa3b, v117
	v_mul_f32_e32 v133, 0xbfb8aa3b, v118
	v_mul_f32_e32 v18, v18, v115
	v_mul_f32_e32 v19, v19, v116
	v_mul_f32_e32 v20, v20, v117
	v_mul_f32_e32 v21, v21, v118
	v_exp_f32_e32 v130, v130
	v_exp_f32_e32 v131, v131
	v_exp_f32_e32 v132, v132
	v_exp_f32_e32 v133, v133
	v_add_f32_e32 v130, 1.0, v130
	v_add_f32_e32 v131, 1.0, v131
	v_add_f32_e32 v132, 1.0, v132
	v_add_f32_e32 v133, 1.0, v133
	v_rcp_f32_e32 v130, v130
	v_rcp_f32_e32 v131, v131
	v_rcp_f32_e32 v132, v132
	v_rcp_f32_e32 v133, v133
	v_mul_f32_e32 v18, v130, v18
	v_mul_f32_e32 v19, v131, v19
	v_mul_f32_e32 v20, v132, v20
	v_mul_f32_e32 v21, v133, v21
	v_cvt_pk_bf16_f32 v18, v18, v19
	v_cvt_pk_bf16_f32 v19, v20, v21
	global_store_dwordx2 v[144:145], v[18:19], off offset:32
	ds_read2st64_b32 v[122:123], v111 offset1:2
	ds_read2st64_b32 v[124:125], v111 offset0:4 offset1:6
	ds_read2st64_b32 v[126:127], v111 offset0:8 offset1:10
	ds_read2st64_b32 v[128:129], v111 offset0:12 offset1:14
	s_waitcnt lgkmcnt(4)
	v_add_f32_e32 v95, 0, v238
	v_add_f32_e32 v95, v95, v239
	v_add_f32_e32 v95, v95, v240
	v_add_f32_e32 v95, v95, v241
	v_add_f32_e32 v95, v95, v242
	v_add_f32_e32 v95, v95, v243
	v_add_f32_e32 v95, v95, v244
	v_add_f32_e32 v95, v95, v245
	v_fmamk_f32 v95, v95, 0x3b800000, v196
	v_mul_f32_e32 v119, 0x4b800000, v95
	v_cmp_gt_f32_e32 vcc, s84, v95
	s_nop 1
	v_cndmask_b32_e32 v95, v95, v119, vcc
	v_rsq_f32_e32 v95, v95
	s_nop 0
	v_mul_f32_e32 v119, 0x45800000, v95
	v_cndmask_b32_e32 v95, v95, v119, vcc
	v_mul_f32_e32 v16, v16, v95
	v_mul_f32_e32 v15, v15, v95
	v_mul_f32_e32 v14, v14, v95
	v_mul_f32_e32 v17, v17, v95
	v_mul_f32_e32 v12, v12, v95
	v_mul_f32_e32 v11, v11, v95
	v_mul_f32_e32 v10, v10, v95
	v_mul_f32_e32 v13, v13, v95
	s_waitcnt vmcnt(15)
	v_mul_f32_e32 v14, v230, v14
	v_mul_f32_e32 v15, v231, v15
	v_mul_f32_e32 v16, v232, v16
	v_mul_f32_e32 v17, v233, v17
	v_lshlrev_b32_e32 v115, 16, v222
	v_and_b32_e32 v116, 0xffff0000, v222
	v_lshlrev_b32_e32 v117, 16, v223
	v_and_b32_e32 v118, 0xffff0000, v223
	v_mul_f32_e32 v130, 0xbfb8aa3b, v115
	v_mul_f32_e32 v131, 0xbfb8aa3b, v116
	v_mul_f32_e32 v132, 0xbfb8aa3b, v117
	v_mul_f32_e32 v133, 0xbfb8aa3b, v118
	v_mul_f32_e32 v14, v14, v115
	v_mul_f32_e32 v15, v15, v116
	v_mul_f32_e32 v16, v16, v117
	v_mul_f32_e32 v17, v17, v118
	v_exp_f32_e32 v130, v130
	v_exp_f32_e32 v131, v131
	v_exp_f32_e32 v132, v132
	v_exp_f32_e32 v133, v133
	v_add_f32_e32 v130, 1.0, v130
	v_add_f32_e32 v131, 1.0, v131
	v_add_f32_e32 v132, 1.0, v132
	v_add_f32_e32 v133, 1.0, v133
	v_rcp_f32_e32 v130, v130
	v_rcp_f32_e32 v131, v131
	v_rcp_f32_e32 v132, v132
	v_rcp_f32_e32 v133, v133
	v_mul_f32_e32 v14, v130, v14
	v_mul_f32_e32 v15, v131, v15
	v_mul_f32_e32 v16, v132, v16
	v_mul_f32_e32 v17, v133, v17
	v_cvt_pk_bf16_f32 v14, v14, v15
	v_cvt_pk_bf16_f32 v15, v16, v17
	global_store_dwordx2 v[148:149], v[14:15], off
	s_waitcnt vmcnt(15)
	v_mul_f32_e32 v10, v234, v10
	v_mul_f32_e32 v11, v235, v11
	v_mul_f32_e32 v12, v236, v12
	v_mul_f32_e32 v13, v237, v13
	v_lshlrev_b32_e32 v115, 16, v224
	v_and_b32_e32 v116, 0xffff0000, v224
	v_lshlrev_b32_e32 v117, 16, v225
	v_and_b32_e32 v118, 0xffff0000, v225
	v_mul_f32_e32 v130, 0xbfb8aa3b, v115
	v_mul_f32_e32 v131, 0xbfb8aa3b, v116
	v_mul_f32_e32 v132, 0xbfb8aa3b, v117
	v_mul_f32_e32 v133, 0xbfb8aa3b, v118
	v_mul_f32_e32 v10, v10, v115
	v_mul_f32_e32 v11, v11, v116
	v_mul_f32_e32 v12, v12, v117
	v_mul_f32_e32 v13, v13, v118
	v_exp_f32_e32 v130, v130
	v_exp_f32_e32 v131, v131
	v_exp_f32_e32 v132, v132
	v_exp_f32_e32 v133, v133
	v_add_f32_e32 v130, 1.0, v130
	v_add_f32_e32 v131, 1.0, v131
	v_add_f32_e32 v132, 1.0, v132
	v_add_f32_e32 v133, 1.0, v133
	v_rcp_f32_e32 v130, v130
	v_rcp_f32_e32 v131, v131
	v_rcp_f32_e32 v132, v132
	v_rcp_f32_e32 v133, v133
	v_mul_f32_e32 v10, v130, v10
	v_mul_f32_e32 v11, v131, v11
	v_mul_f32_e32 v12, v132, v12
	v_mul_f32_e32 v13, v133, v13
	v_cvt_pk_bf16_f32 v10, v10, v11
	v_cvt_pk_bf16_f32 v11, v12, v13
	global_store_dwordx2 v[148:149], v[10:11], off offset:32
	s_waitcnt lgkmcnt(0)
	v_add_f32_e32 v95, 0, v122
	v_add_f32_e32 v95, v95, v123
	v_add_f32_e32 v95, v95, v124
	v_add_f32_e32 v95, v95, v125
	v_add_f32_e32 v95, v95, v126
	v_add_f32_e32 v95, v95, v127
	v_add_f32_e32 v95, v95, v128
	v_add_f32_e32 v95, v95, v129
	v_fmamk_f32 v95, v95, 0x3b800000, v196
	v_mul_f32_e32 v119, 0x4b800000, v95
	v_cmp_gt_f32_e32 vcc, s84, v95
	s_nop 1
	v_cndmask_b32_e32 v95, v95, v119, vcc
	v_rsq_f32_e32 v95, v95
	s_nop 0
	v_mul_f32_e32 v119, 0x45800000, v95
	v_cndmask_b32_e32 v95, v95, v119, vcc
	v_mul_f32_e32 v8, v8, v95
	v_mul_f32_e32 v7, v7, v95
	v_mul_f32_e32 v6, v6, v95
	v_mul_f32_e32 v9, v9, v95
	v_mul_f32_e32 v4, v4, v95
	v_mul_f32_e32 v3, v3, v95
	v_mul_f32_e32 v2, v2, v95
	v_mul_f32_e32 v5, v5, v95
	s_waitcnt vmcnt(15)
	v_mul_f32_e32 v6, v230, v6
	v_mul_f32_e32 v7, v231, v7
	v_mul_f32_e32 v8, v232, v8
	v_mul_f32_e32 v9, v233, v9
	v_lshlrev_b32_e32 v115, 16, v226
	v_and_b32_e32 v116, 0xffff0000, v226
	v_lshlrev_b32_e32 v117, 16, v227
	v_and_b32_e32 v118, 0xffff0000, v227
	v_mul_f32_e32 v130, 0xbfb8aa3b, v115
	v_mul_f32_e32 v131, 0xbfb8aa3b, v116
	v_mul_f32_e32 v132, 0xbfb8aa3b, v117
	v_mul_f32_e32 v133, 0xbfb8aa3b, v118
	v_mul_f32_e32 v6, v6, v115
	v_mul_f32_e32 v7, v7, v116
	v_mul_f32_e32 v8, v8, v117
	v_mul_f32_e32 v9, v9, v118
	v_exp_f32_e32 v130, v130
	v_exp_f32_e32 v131, v131
	v_exp_f32_e32 v132, v132
	v_exp_f32_e32 v133, v133
	v_add_f32_e32 v130, 1.0, v130
	v_add_f32_e32 v131, 1.0, v131
	v_add_f32_e32 v132, 1.0, v132
	v_add_f32_e32 v133, 1.0, v133
	v_rcp_f32_e32 v130, v130
	v_rcp_f32_e32 v131, v131
	v_rcp_f32_e32 v132, v132
	v_rcp_f32_e32 v133, v133
	v_mul_f32_e32 v6, v130, v6
	v_mul_f32_e32 v7, v131, v7
	v_mul_f32_e32 v8, v132, v8
	v_mul_f32_e32 v9, v133, v9
	v_cvt_pk_bf16_f32 v6, v6, v7
	v_cvt_pk_bf16_f32 v7, v8, v9
	global_store_dwordx2 v[150:151], v[6:7], off
	s_waitcnt vmcnt(15)
	v_mul_f32_e32 v2, v234, v2
	v_mul_f32_e32 v3, v235, v3
	v_mul_f32_e32 v4, v236, v4
	v_mul_f32_e32 v5, v237, v5
	v_lshlrev_b32_e32 v115, 16, v228
	v_and_b32_e32 v116, 0xffff0000, v228
	v_lshlrev_b32_e32 v117, 16, v229
	v_and_b32_e32 v118, 0xffff0000, v229
	v_mul_f32_e32 v130, 0xbfb8aa3b, v115
	v_mul_f32_e32 v131, 0xbfb8aa3b, v116
	v_mul_f32_e32 v132, 0xbfb8aa3b, v117
	v_mul_f32_e32 v133, 0xbfb8aa3b, v118
	v_mul_f32_e32 v2, v2, v115
	v_mul_f32_e32 v3, v3, v116
	v_mul_f32_e32 v4, v4, v117
	v_mul_f32_e32 v5, v5, v118
	v_exp_f32_e32 v130, v130
	v_exp_f32_e32 v131, v131
	v_exp_f32_e32 v132, v132
	v_exp_f32_e32 v133, v133
	v_add_f32_e32 v130, 1.0, v130
	v_add_f32_e32 v131, 1.0, v131
	v_add_f32_e32 v132, 1.0, v132
	v_add_f32_e32 v133, 1.0, v133
	v_rcp_f32_e32 v130, v130
	v_rcp_f32_e32 v131, v131
	v_rcp_f32_e32 v132, v132
	v_rcp_f32_e32 v133, v133
	v_mul_f32_e32 v2, v130, v2
	v_mul_f32_e32 v3, v131, v3
	v_mul_f32_e32 v4, v132, v4
	v_mul_f32_e32 v5, v133, v5
	v_cvt_pk_bf16_f32 v2, v2, v3
	v_cvt_pk_bf16_f32 v3, v4, v5
	global_store_dwordx2 v[150:151], v[2:3], off offset:32
	s_mov_b64 s[18:19], s[72:73]
	s_mov_b64 s[72:73], s[60:61]
	s_mov_b64 s[60:61], s[62:63]
	s_mov_b64 s[62:63], s[64:65]
	s_mov_b64 s[64:65], s[66:67]
	s_mov_b64 s[66:67], s[68:69]
	s_mov_b64 s[68:69], s[70:71]
	s_mov_b64 s[70:71], s[44:45]
	s_mov_b64 s[44:45], s[74:75]
	s_mov_b64 s[74:75], s[76:77]
	s_mov_b64 s[76:77], s[78:79]
	s_mov_b64 s[78:79], s[46:47]
	s_mov_b64 s[46:47], s[48:49]
	s_mov_b64 s[48:49], s[50:51]
	s_mov_b64 s[50:51], s[52:53]
	s_mov_b64 s[52:53], s[54:55]
	s_mov_b64 s[54:55], s[56:57]
	s_mov_b64 s[56:57], s[92:93]
	s_mov_b64 s[92:93], s[94:95]
	s_mov_b64 s[94:95], s[38:39]
	s_mov_b64 s[38:39], s[96:97]
	s_mov_b64 s[96:97], s[0:1]
	s_mov_b64 s[0:1], s[4:5]
	v_readlane_b32 s22, v250, 51
	v_readlane_b32 s23, v250, 52
	s_branch .LBB0_72

.LBB0_160:
	v_cndmask_b32_e64 v2, 0, 1, s[6:7]
	v_cmp_ne_u32_e32 vcc, 1, v2
	v_add_u32_e32 v2, s5, v208
	v_ashrrev_i32_e32 v20, 5, v2
	v_add_u32_e32 v6, s5, v127
	v_ashrrev_i32_e32 v21, 31, v20
	v_ashrrev_i32_e32 v22, 5, v6
	v_add_u32_e32 v10, s5, v136
	v_lshlrev_b64 v[2:3], 11, v[20:21]
	v_ashrrev_i32_e32 v23, 31, v22
	v_ashrrev_i32_e32 v24, 5, v10
	v_add_u32_e32 v14, s5, v137
	v_lshl_add_u64 v[2:3], v[18:19], 0, v[2:3]
	v_lshlrev_b64 v[6:7], 11, v[22:23]
	v_ashrrev_i32_e32 v25, 31, v24
	v_ashrrev_i32_e32 v26, 5, v14
	v_add_u32_e32 v21, s5, v141
	flat_load_dwordx4 v[2:5], v[2:3]
	v_lshl_add_u64 v[6:7], v[18:19], 0, v[6:7]
	v_lshlrev_b64 v[10:11], 11, v[24:25]
	v_ashrrev_i32_e32 v27, 31, v26
	v_ashrrev_i32_e32 v44, 5, v21
	v_add_u32_e32 v21, s5, v142
	flat_load_dwordx4 v[6:9], v[6:7]
	v_lshl_add_u64 v[10:11], v[18:19], 0, v[10:11]
	v_lshlrev_b64 v[14:15], 11, v[26:27]
	v_ashrrev_i32_e32 v45, 31, v44
	v_ashrrev_i32_e32 v46, 5, v21
	v_add_u32_e32 v21, s5, v143
	flat_load_dwordx4 v[10:13], v[10:11]
	v_lshl_add_u64 v[14:15], v[18:19], 0, v[14:15]
	v_lshlrev_b64 v[28:29], 11, v[44:45]
	v_ashrrev_i32_e32 v47, 31, v46
	v_ashrrev_i32_e32 v48, 5, v21
	flat_load_dwordx4 v[14:17], v[14:15]
	v_lshl_add_u64 v[28:29], v[18:19], 0, v[28:29]
	v_lshlrev_b64 v[32:33], 11, v[46:47]
	v_ashrrev_i32_e32 v49, 31, v48
	v_add_u32_e32 v21, s5, v144
	flat_load_dwordx4 v[28:31], v[28:29]
	v_lshl_add_u64 v[32:33], v[18:19], 0, v[32:33]
	v_lshlrev_b64 v[36:37], 11, v[48:49]
	v_ashrrev_i32_e32 v50, 5, v21
	flat_load_dwordx4 v[32:35], v[32:33]
	v_lshl_add_u64 v[36:37], v[18:19], 0, v[36:37]
	v_ashrrev_i32_e32 v51, 31, v50
	flat_load_dwordx4 v[36:39], v[36:37]
	v_lshlrev_b64 v[40:41], 11, v[50:51]
	v_lshl_add_u64 v[40:41], v[18:19], 0, v[40:41]
	flat_load_dwordx4 v[40:43], v[40:41]
	v_mad_u64_u32 v[20:21], s[6:7], v20, s85, v[126:127]
	s_movk_i32 s5, 0x1000
	s_and_b64 vcc, exec, vcc
	s_waitcnt vmcnt(0) lgkmcnt(0)
	ds_write_b128 v20, v[2:5]
	v_mad_u64_u32 v[2:3], s[6:7], v22, s85, v[126:127]
	ds_write_b128 v2, v[6:9]
	v_mad_u64_u32 v[2:3], s[6:7], v24, s85, v[126:127]
	ds_write_b128 v2, v[10:13]
	v_mad_u64_u32 v[2:3], s[6:7], v26, s85, v[126:127]
	ds_write_b128 v2, v[14:17]
	v_mad_u64_u32 v[2:3], s[6:7], v44, s85, v[126:127]
	ds_write_b128 v2, v[28:31]
	v_mad_u64_u32 v[2:3], s[6:7], v46, s85, v[126:127]
	ds_write_b128 v2, v[32:35]
	v_mad_u64_u32 v[2:3], s[6:7], v48, s85, v[126:127]
	ds_write_b128 v2, v[36:39]
	v_mad_u64_u32 v[2:3], s[6:7], v50, s85, v[126:127]
	s_mov_b64 s[6:7], 0
	ds_write_b128 v2, v[40:43]
	s_cbranch_vccz .LBB0_160
	s_lshl_b32 s5, s25, 8
	s_and_b32 s6, s5, 0xf00
	s_ashr_i32 s5, s4, 31
	s_lshl_b64 s[4:5], s[4:5], 12
	s_or_b32 s4, s4, s6
	v_lshl_add_u64 v[2:3], s[4:5], 0, v[128:129]
	v_mov_b64_e32 v[4:5], s[26:27]
	v_mad_u64_u32 v[4:5], s[4:5], v2, s83, v[4:5]
	v_mad_i32_i24 v5, v3, s83, v5
	s_lshl_b32 s36, s28, 1
	v_lshl_add_u64 v[2:3], v[4:5], 0, s[36:37]
	s_mov_b64 s[4:5], 0x2200
	v_lshl_add_u64 v[134:135], v[2:3], 0, s[4:5]
	v_lshl_add_u64 v[132:133], v[134:135], 0, v[0:1]
	s_waitcnt lgkmcnt(0)
	s_barrier
	s_mov_b32 s5, 0x210000
	s_lshl_b32 s4, s28, 9
	s_add_u32 s0, s21, s0
	s_addc_u32 s1, s24, s1
	s_add_u32 s0, s0, s4
	s_addc_u32 s1, s1, 0
	global_load_dwordx4 v[98:101], v[132:133], off
	global_load_dwordx4 v[102:105], v[132:133], off offset:64
	global_load_dwordx4 v[106:109], v[132:133], off offset:128
	global_load_dwordx4 v[110:113], v[132:133], off offset:192
	global_load_dwordx4 v[114:117], v[132:133], off offset:256
	global_load_dwordx4 v[118:121], v[132:133], off offset:320
	global_load_dwordx4 v[122:125], v[132:133], off offset:384
	global_load_dwordx4 v[224:227], v[132:133], off offset:448
	v_and_b32_e32 v244, 15, v195
	v_lshrrev_b32_e32 v245, 4, v195
	v_and_b32_e32 v245, 3, v245
	v_mul_u32_u24_e32 v244, 0x210, v244
	v_lshl_add_u32 v244, v245, 4, v244
	v_add_u32_e32 v245, 0x10800, v244
	v_add_co_u32_e32 v246, vcc, s5, v132
	s_nop 1
	v_addc_co_u32_e32 v247, vcc, 0, v133, vcc
	s_waitcnt vmcnt(0)
	ds_read_b128 v[2:5], v244
	ds_read_b128 v[6:9], v244 offset:64
	ds_read_b128 v[10:13], v244 offset:128
	ds_read_b128 v[14:17], v244 offset:192
	ds_read_b128 v[18:21], v244 offset:256
	ds_read_b128 v[22:25], v244 offset:320
	ds_read_b128 v[26:29], v244 offset:384
	ds_read_b128 v[30:33], v244 offset:448
	s_waitcnt lgkmcnt(7)
	v_mfma_f32_16x16x32_bf16 v[34:37], v[2:5], v[98:101], 0
	ds_read_b128 v[2:5], v244 offset:8448
	s_waitcnt lgkmcnt(7)
	v_mfma_f32_16x16x32_bf16 v[34:37], v[6:9], v[102:105], v[34:37]
	ds_read_b128 v[6:9], v244 offset:8512
	s_waitcnt lgkmcnt(7)
	v_mfma_f32_16x16x32_bf16 v[34:37], v[10:13], v[106:109], v[34:37]
	ds_read_b128 v[10:13], v244 offset:8576
	s_waitcnt lgkmcnt(7)
	v_mfma_f32_16x16x32_bf16 v[34:37], v[14:17], v[110:113], v[34:37]
	ds_read_b128 v[14:17], v244 offset:8640
	s_waitcnt lgkmcnt(7)
	v_mfma_f32_16x16x32_bf16 v[34:37], v[18:21], v[114:117], v[34:37]
	ds_read_b128 v[18:21], v244 offset:8704
	s_waitcnt lgkmcnt(7)
	v_mfma_f32_16x16x32_bf16 v[34:37], v[22:25], v[118:121], v[34:37]
	ds_read_b128 v[22:25], v244 offset:8768
	s_waitcnt lgkmcnt(7)
	v_mfma_f32_16x16x32_bf16 v[34:37], v[26:29], v[122:125], v[34:37]
	ds_read_b128 v[26:29], v244 offset:8832
	s_waitcnt lgkmcnt(7)
	v_mfma_f32_16x16x32_bf16 v[34:37], v[30:33], v[224:227], v[34:37]
	ds_read_b128 v[30:33], v244 offset:8896
	s_waitcnt lgkmcnt(7)
	v_mfma_f32_16x16x32_bf16 v[38:41], v[2:5], v[98:101], 0
	ds_read_b128 v[2:5], v244 offset:16896
	s_waitcnt lgkmcnt(7)
	v_mfma_f32_16x16x32_bf16 v[38:41], v[6:9], v[102:105], v[38:41]
	ds_read_b128 v[6:9], v244 offset:16960
	s_waitcnt lgkmcnt(7)
	v_mfma_f32_16x16x32_bf16 v[38:41], v[10:13], v[106:109], v[38:41]
	ds_read_b128 v[10:13], v244 offset:17024
	s_waitcnt lgkmcnt(7)
	v_mfma_f32_16x16x32_bf16 v[38:41], v[14:17], v[110:113], v[38:41]
	ds_read_b128 v[14:17], v244 offset:17088
	s_waitcnt lgkmcnt(7)
	v_mfma_f32_16x16x32_bf16 v[38:41], v[18:21], v[114:117], v[38:41]
	ds_read_b128 v[18:21], v244 offset:17152
	s_waitcnt lgkmcnt(7)
	v_mfma_f32_16x16x32_bf16 v[38:41], v[22:25], v[118:121], v[38:41]
	ds_read_b128 v[22:25], v244 offset:17216
	s_waitcnt lgkmcnt(7)
	v_mfma_f32_16x16x32_bf16 v[38:41], v[26:29], v[122:125], v[38:41]
	ds_read_b128 v[26:29], v244 offset:17280
	s_waitcnt lgkmcnt(7)
	v_mfma_f32_16x16x32_bf16 v[38:41], v[30:33], v[224:227], v[38:41]
	ds_read_b128 v[30:33], v244 offset:17344
	s_waitcnt lgkmcnt(7)
	v_mfma_f32_16x16x32_bf16 v[42:45], v[2:5], v[98:101], 0
	ds_read_b128 v[2:5], v244 offset:25344
	s_waitcnt lgkmcnt(7)
	v_mfma_f32_16x16x32_bf16 v[42:45], v[6:9], v[102:105], v[42:45]
	ds_read_b128 v[6:9], v244 offset:25408
	s_waitcnt lgkmcnt(7)
	v_mfma_f32_16x16x32_bf16 v[42:45], v[10:13], v[106:109], v[42:45]
	ds_read_b128 v[10:13], v244 offset:25472
	s_waitcnt lgkmcnt(7)
	v_mfma_f32_16x16x32_bf16 v[42:45], v[14:17], v[110:113], v[42:45]
	ds_read_b128 v[14:17], v244 offset:25536
	s_waitcnt lgkmcnt(7)
	v_mfma_f32_16x16x32_bf16 v[42:45], v[18:21], v[114:117], v[42:45]
	ds_read_b128 v[18:21], v244 offset:25600
	s_waitcnt lgkmcnt(7)
	v_mfma_f32_16x16x32_bf16 v[42:45], v[22:25], v[118:121], v[42:45]
	ds_read_b128 v[22:25], v244 offset:25664
	s_waitcnt lgkmcnt(7)
	v_mfma_f32_16x16x32_bf16 v[42:45], v[26:29], v[122:125], v[42:45]
	ds_read_b128 v[26:29], v244 offset:25728
	s_waitcnt lgkmcnt(7)
	v_mfma_f32_16x16x32_bf16 v[42:45], v[30:33], v[224:227], v[42:45]
	ds_read_b128 v[30:33], v244 offset:25792
	s_waitcnt lgkmcnt(7)
	v_mfma_f32_16x16x32_bf16 v[46:49], v[2:5], v[98:101], 0
	ds_read_b128 v[2:5], v244 offset:33792
	s_waitcnt lgkmcnt(7)
	v_mfma_f32_16x16x32_bf16 v[46:49], v[6:9], v[102:105], v[46:49]
	ds_read_b128 v[6:9], v244 offset:33856
	s_waitcnt lgkmcnt(7)
	v_mfma_f32_16x16x32_bf16 v[46:49], v[10:13], v[106:109], v[46:49]
	ds_read_b128 v[10:13], v244 offset:33920
	s_waitcnt lgkmcnt(7)
	v_mfma_f32_16x16x32_bf16 v[46:49], v[14:17], v[110:113], v[46:49]
	ds_read_b128 v[14:17], v244 offset:33984
	s_waitcnt lgkmcnt(7)
	v_mfma_f32_16x16x32_bf16 v[46:49], v[18:21], v[114:117], v[46:49]
	ds_read_b128 v[18:21], v244 offset:34048
	s_waitcnt lgkmcnt(7)
	v_mfma_f32_16x16x32_bf16 v[46:49], v[22:25], v[118:121], v[46:49]
	ds_read_b128 v[22:25], v244 offset:34112
	s_waitcnt lgkmcnt(7)
	v_mfma_f32_16x16x32_bf16 v[46:49], v[26:29], v[122:125], v[46:49]
	ds_read_b128 v[26:29], v244 offset:34176
	s_waitcnt lgkmcnt(7)
	v_mfma_f32_16x16x32_bf16 v[46:49], v[30:33], v[224:227], v[46:49]
	ds_read_b128 v[30:33], v244 offset:34240
	s_waitcnt lgkmcnt(7)
	v_mfma_f32_16x16x32_bf16 v[50:53], v[2:5], v[98:101], 0
	ds_read_b128 v[2:5], v244 offset:42240
	s_waitcnt lgkmcnt(7)
	v_mfma_f32_16x16x32_bf16 v[50:53], v[6:9], v[102:105], v[50:53]
	ds_read_b128 v[6:9], v244 offset:42304
	s_waitcnt lgkmcnt(7)
	v_mfma_f32_16x16x32_bf16 v[50:53], v[10:13], v[106:109], v[50:53]
	ds_read_b128 v[10:13], v244 offset:42368
	s_waitcnt lgkmcnt(7)
	v_mfma_f32_16x16x32_bf16 v[50:53], v[14:17], v[110:113], v[50:53]
	ds_read_b128 v[14:17], v244 offset:42432
	s_waitcnt lgkmcnt(7)
	v_mfma_f32_16x16x32_bf16 v[50:53], v[18:21], v[114:117], v[50:53]
	ds_read_b128 v[18:21], v244 offset:42496
	s_waitcnt lgkmcnt(7)
	v_mfma_f32_16x16x32_bf16 v[50:53], v[22:25], v[118:121], v[50:53]
	ds_read_b128 v[22:25], v244 offset:42560
	s_waitcnt lgkmcnt(7)
	v_mfma_f32_16x16x32_bf16 v[50:53], v[26:29], v[122:125], v[50:53]
	ds_read_b128 v[26:29], v244 offset:42624
	s_waitcnt lgkmcnt(7)
	v_mfma_f32_16x16x32_bf16 v[50:53], v[30:33], v[224:227], v[50:53]
	ds_read_b128 v[30:33], v244 offset:42688
	s_waitcnt lgkmcnt(7)
	v_mfma_f32_16x16x32_bf16 v[54:57], v[2:5], v[98:101], 0
	ds_read_b128 v[2:5], v244 offset:50688
	s_waitcnt lgkmcnt(7)
	v_mfma_f32_16x16x32_bf16 v[54:57], v[6:9], v[102:105], v[54:57]
	ds_read_b128 v[6:9], v244 offset:50752
	s_waitcnt lgkmcnt(7)
	v_mfma_f32_16x16x32_bf16 v[54:57], v[10:13], v[106:109], v[54:57]
	ds_read_b128 v[10:13], v244 offset:50816
	s_waitcnt lgkmcnt(7)
	v_mfma_f32_16x16x32_bf16 v[54:57], v[14:17], v[110:113], v[54:57]
	ds_read_b128 v[14:17], v244 offset:50880
	s_waitcnt lgkmcnt(7)
	v_mfma_f32_16x16x32_bf16 v[54:57], v[18:21], v[114:117], v[54:57]
	ds_read_b128 v[18:21], v244 offset:50944
	s_waitcnt lgkmcnt(7)
	v_mfma_f32_16x16x32_bf16 v[54:57], v[22:25], v[118:121], v[54:57]
	ds_read_b128 v[22:25], v244 offset:51008
	s_waitcnt lgkmcnt(7)
	v_mfma_f32_16x16x32_bf16 v[54:57], v[26:29], v[122:125], v[54:57]
	ds_read_b128 v[26:29], v244 offset:51072
	s_waitcnt lgkmcnt(7)
	v_mfma_f32_16x16x32_bf16 v[54:57], v[30:33], v[224:227], v[54:57]
	ds_read_b128 v[30:33], v244 offset:51136
	s_waitcnt lgkmcnt(7)
	v_mfma_f32_16x16x32_bf16 v[58:61], v[2:5], v[98:101], 0
	ds_read_b128 v[2:5], v244 offset:59136
	s_waitcnt lgkmcnt(7)
	v_mfma_f32_16x16x32_bf16 v[58:61], v[6:9], v[102:105], v[58:61]
	ds_read_b128 v[6:9], v244 offset:59200
	s_waitcnt lgkmcnt(7)
	v_mfma_f32_16x16x32_bf16 v[58:61], v[10:13], v[106:109], v[58:61]
	ds_read_b128 v[10:13], v244 offset:59264
	s_waitcnt lgkmcnt(7)
	v_mfma_f32_16x16x32_bf16 v[58:61], v[14:17], v[110:113], v[58:61]
	ds_read_b128 v[14:17], v244 offset:59328
	s_waitcnt lgkmcnt(7)
	v_mfma_f32_16x16x32_bf16 v[58:61], v[18:21], v[114:117], v[58:61]
	ds_read_b128 v[18:21], v244 offset:59392
	s_waitcnt lgkmcnt(7)
	v_mfma_f32_16x16x32_bf16 v[58:61], v[22:25], v[118:121], v[58:61]
	ds_read_b128 v[22:25], v244 offset:59456
	s_waitcnt lgkmcnt(7)
	v_mfma_f32_16x16x32_bf16 v[58:61], v[26:29], v[122:125], v[58:61]
	ds_read_b128 v[26:29], v244 offset:59520
	s_waitcnt lgkmcnt(7)
	v_mfma_f32_16x16x32_bf16 v[58:61], v[30:33], v[224:227], v[58:61]
	ds_read_b128 v[30:33], v244 offset:59584
	s_waitcnt lgkmcnt(7)
	v_mfma_f32_16x16x32_bf16 v[62:65], v[2:5], v[98:101], 0
	ds_read_b128 v[2:5], v245
	s_waitcnt lgkmcnt(7)
	v_mfma_f32_16x16x32_bf16 v[62:65], v[6:9], v[102:105], v[62:65]
	ds_read_b128 v[6:9], v245 offset:64
	s_waitcnt lgkmcnt(7)
	v_mfma_f32_16x16x32_bf16 v[62:65], v[10:13], v[106:109], v[62:65]
	ds_read_b128 v[10:13], v245 offset:128
	s_waitcnt lgkmcnt(7)
	v_mfma_f32_16x16x32_bf16 v[62:65], v[14:17], v[110:113], v[62:65]
	ds_read_b128 v[14:17], v245 offset:192
	s_waitcnt lgkmcnt(7)
	v_mfma_f32_16x16x32_bf16 v[62:65], v[18:21], v[114:117], v[62:65]
	ds_read_b128 v[18:21], v245 offset:256
	s_waitcnt lgkmcnt(7)
	v_mfma_f32_16x16x32_bf16 v[62:65], v[22:25], v[118:121], v[62:65]
	ds_read_b128 v[22:25], v245 offset:320
	s_waitcnt lgkmcnt(7)
	v_mfma_f32_16x16x32_bf16 v[62:65], v[26:29], v[122:125], v[62:65]
	ds_read_b128 v[26:29], v245 offset:384
	s_waitcnt lgkmcnt(7)
	v_mfma_f32_16x16x32_bf16 v[62:65], v[30:33], v[224:227], v[62:65]
	ds_read_b128 v[30:33], v245 offset:448
	s_waitcnt lgkmcnt(7)
	v_mfma_f32_16x16x32_bf16 v[66:69], v[2:5], v[98:101], 0
	ds_read_b128 v[2:5], v245 offset:8448
	s_waitcnt lgkmcnt(7)
	v_mfma_f32_16x16x32_bf16 v[66:69], v[6:9], v[102:105], v[66:69]
	ds_read_b128 v[6:9], v245 offset:8512
	s_waitcnt lgkmcnt(7)
	v_mfma_f32_16x16x32_bf16 v[66:69], v[10:13], v[106:109], v[66:69]
	ds_read_b128 v[10:13], v245 offset:8576
	s_waitcnt lgkmcnt(7)
	v_mfma_f32_16x16x32_bf16 v[66:69], v[14:17], v[110:113], v[66:69]
	ds_read_b128 v[14:17], v245 offset:8640
	s_waitcnt lgkmcnt(7)
	v_mfma_f32_16x16x32_bf16 v[66:69], v[18:21], v[114:117], v[66:69]
	ds_read_b128 v[18:21], v245 offset:8704
	s_waitcnt lgkmcnt(7)
	v_mfma_f32_16x16x32_bf16 v[66:69], v[22:25], v[118:121], v[66:69]
	ds_read_b128 v[22:25], v245 offset:8768
	s_waitcnt lgkmcnt(7)
	v_mfma_f32_16x16x32_bf16 v[66:69], v[26:29], v[122:125], v[66:69]
	ds_read_b128 v[26:29], v245 offset:8832
	s_waitcnt lgkmcnt(7)
	v_mfma_f32_16x16x32_bf16 v[66:69], v[30:33], v[224:227], v[66:69]
	ds_read_b128 v[30:33], v245 offset:8896
	s_waitcnt lgkmcnt(7)
	v_mfma_f32_16x16x32_bf16 v[70:73], v[2:5], v[98:101], 0
	ds_read_b128 v[2:5], v245 offset:16896
	s_waitcnt lgkmcnt(7)
	v_mfma_f32_16x16x32_bf16 v[70:73], v[6:9], v[102:105], v[70:73]
	ds_read_b128 v[6:9], v245 offset:16960
	s_waitcnt lgkmcnt(7)
	v_mfma_f32_16x16x32_bf16 v[70:73], v[10:13], v[106:109], v[70:73]
	ds_read_b128 v[10:13], v245 offset:17024
	s_waitcnt lgkmcnt(7)
	v_mfma_f32_16x16x32_bf16 v[70:73], v[14:17], v[110:113], v[70:73]
	ds_read_b128 v[14:17], v245 offset:17088
	s_waitcnt lgkmcnt(7)
	v_mfma_f32_16x16x32_bf16 v[70:73], v[18:21], v[114:117], v[70:73]
	ds_read_b128 v[18:21], v245 offset:17152
	s_waitcnt lgkmcnt(7)
	v_mfma_f32_16x16x32_bf16 v[70:73], v[22:25], v[118:121], v[70:73]
	ds_read_b128 v[22:25], v245 offset:17216
	s_waitcnt lgkmcnt(7)
	v_mfma_f32_16x16x32_bf16 v[70:73], v[26:29], v[122:125], v[70:73]
	ds_read_b128 v[26:29], v245 offset:17280
	s_waitcnt lgkmcnt(7)
	v_mfma_f32_16x16x32_bf16 v[70:73], v[30:33], v[224:227], v[70:73]
	ds_read_b128 v[30:33], v245 offset:17344
	s_waitcnt lgkmcnt(7)
	v_mfma_f32_16x16x32_bf16 v[74:77], v[2:5], v[98:101], 0
	ds_read_b128 v[2:5], v245 offset:25344
	s_waitcnt lgkmcnt(7)
	v_mfma_f32_16x16x32_bf16 v[74:77], v[6:9], v[102:105], v[74:77]
	ds_read_b128 v[6:9], v245 offset:25408
	s_waitcnt lgkmcnt(7)
	v_mfma_f32_16x16x32_bf16 v[74:77], v[10:13], v[106:109], v[74:77]
	ds_read_b128 v[10:13], v245 offset:25472
	s_waitcnt lgkmcnt(7)
	v_mfma_f32_16x16x32_bf16 v[74:77], v[14:17], v[110:113], v[74:77]
	ds_read_b128 v[14:17], v245 offset:25536
	s_waitcnt lgkmcnt(7)
	v_mfma_f32_16x16x32_bf16 v[74:77], v[18:21], v[114:117], v[74:77]
	ds_read_b128 v[18:21], v245 offset:25600
	s_waitcnt lgkmcnt(7)
	v_mfma_f32_16x16x32_bf16 v[74:77], v[22:25], v[118:121], v[74:77]
	ds_read_b128 v[22:25], v245 offset:25664
	s_waitcnt lgkmcnt(7)
	v_mfma_f32_16x16x32_bf16 v[74:77], v[26:29], v[122:125], v[74:77]
	ds_read_b128 v[26:29], v245 offset:25728
	s_waitcnt lgkmcnt(7)
	v_mfma_f32_16x16x32_bf16 v[74:77], v[30:33], v[224:227], v[74:77]
	ds_read_b128 v[30:33], v245 offset:25792
	s_waitcnt lgkmcnt(7)
	v_mfma_f32_16x16x32_bf16 v[78:81], v[2:5], v[98:101], 0
	ds_read_b128 v[2:5], v245 offset:33792
	s_waitcnt lgkmcnt(7)
	v_mfma_f32_16x16x32_bf16 v[78:81], v[6:9], v[102:105], v[78:81]
	ds_read_b128 v[6:9], v245 offset:33856
	s_waitcnt lgkmcnt(7)
	v_mfma_f32_16x16x32_bf16 v[78:81], v[10:13], v[106:109], v[78:81]
	ds_read_b128 v[10:13], v245 offset:33920
	s_waitcnt lgkmcnt(7)
	v_mfma_f32_16x16x32_bf16 v[78:81], v[14:17], v[110:113], v[78:81]
	ds_read_b128 v[14:17], v245 offset:33984
	s_waitcnt lgkmcnt(7)
	v_mfma_f32_16x16x32_bf16 v[78:81], v[18:21], v[114:117], v[78:81]
	ds_read_b128 v[18:21], v245 offset:34048
	s_waitcnt lgkmcnt(7)
	v_mfma_f32_16x16x32_bf16 v[78:81], v[22:25], v[118:121], v[78:81]
	ds_read_b128 v[22:25], v245 offset:34112
	s_waitcnt lgkmcnt(7)
	v_mfma_f32_16x16x32_bf16 v[78:81], v[26:29], v[122:125], v[78:81]
	ds_read_b128 v[26:29], v245 offset:34176
	s_waitcnt lgkmcnt(7)
	v_mfma_f32_16x16x32_bf16 v[78:81], v[30:33], v[224:227], v[78:81]
	ds_read_b128 v[30:33], v245 offset:34240
	s_waitcnt lgkmcnt(7)
	v_mfma_f32_16x16x32_bf16 v[82:85], v[2:5], v[98:101], 0
	ds_read_b128 v[2:5], v245 offset:42240
	s_waitcnt lgkmcnt(7)
	v_mfma_f32_16x16x32_bf16 v[82:85], v[6:9], v[102:105], v[82:85]
	ds_read_b128 v[6:9], v245 offset:42304
	s_waitcnt lgkmcnt(7)
	v_mfma_f32_16x16x32_bf16 v[82:85], v[10:13], v[106:109], v[82:85]
	ds_read_b128 v[10:13], v245 offset:42368
	s_waitcnt lgkmcnt(7)
	v_mfma_f32_16x16x32_bf16 v[82:85], v[14:17], v[110:113], v[82:85]
	ds_read_b128 v[14:17], v245 offset:42432
	s_waitcnt lgkmcnt(7)
	v_mfma_f32_16x16x32_bf16 v[82:85], v[18:21], v[114:117], v[82:85]
	ds_read_b128 v[18:21], v245 offset:42496
	s_waitcnt lgkmcnt(7)
	v_mfma_f32_16x16x32_bf16 v[82:85], v[22:25], v[118:121], v[82:85]
	ds_read_b128 v[22:25], v245 offset:42560
	s_waitcnt lgkmcnt(7)
	v_mfma_f32_16x16x32_bf16 v[82:85], v[26:29], v[122:125], v[82:85]
	ds_read_b128 v[26:29], v245 offset:42624
	s_waitcnt lgkmcnt(7)
	v_mfma_f32_16x16x32_bf16 v[82:85], v[30:33], v[224:227], v[82:85]
	ds_read_b128 v[30:33], v245 offset:42688
	s_waitcnt lgkmcnt(7)
	v_mfma_f32_16x16x32_bf16 v[86:89], v[2:5], v[98:101], 0
	ds_read_b128 v[2:5], v245 offset:50688
	s_waitcnt lgkmcnt(7)
	v_mfma_f32_16x16x32_bf16 v[86:89], v[6:9], v[102:105], v[86:89]
	ds_read_b128 v[6:9], v245 offset:50752
	s_waitcnt lgkmcnt(7)
	v_mfma_f32_16x16x32_bf16 v[86:89], v[10:13], v[106:109], v[86:89]
	ds_read_b128 v[10:13], v245 offset:50816
	s_waitcnt lgkmcnt(7)
	v_mfma_f32_16x16x32_bf16 v[86:89], v[14:17], v[110:113], v[86:89]
	ds_read_b128 v[14:17], v245 offset:50880
	s_waitcnt lgkmcnt(7)
	v_mfma_f32_16x16x32_bf16 v[86:89], v[18:21], v[114:117], v[86:89]
	ds_read_b128 v[18:21], v245 offset:50944
	s_waitcnt lgkmcnt(7)
	v_mfma_f32_16x16x32_bf16 v[86:89], v[22:25], v[118:121], v[86:89]
	ds_read_b128 v[22:25], v245 offset:51008
	s_waitcnt lgkmcnt(7)
	v_mfma_f32_16x16x32_bf16 v[86:89], v[26:29], v[122:125], v[86:89]
	ds_read_b128 v[26:29], v245 offset:51072
	s_waitcnt lgkmcnt(7)
	v_mfma_f32_16x16x32_bf16 v[86:89], v[30:33], v[224:227], v[86:89]
	ds_read_b128 v[30:33], v245 offset:51136
	s_waitcnt lgkmcnt(7)
	v_mfma_f32_16x16x32_bf16 v[90:93], v[2:5], v[98:101], 0
	ds_read_b128 v[2:5], v245 offset:59136
	s_waitcnt lgkmcnt(7)
	v_mfma_f32_16x16x32_bf16 v[90:93], v[6:9], v[102:105], v[90:93]
	ds_read_b128 v[6:9], v245 offset:59200
	s_waitcnt lgkmcnt(7)
	v_mfma_f32_16x16x32_bf16 v[90:93], v[10:13], v[106:109], v[90:93]
	ds_read_b128 v[10:13], v245 offset:59264
	s_waitcnt lgkmcnt(7)
	v_mfma_f32_16x16x32_bf16 v[90:93], v[14:17], v[110:113], v[90:93]
	ds_read_b128 v[14:17], v245 offset:59328
	s_waitcnt lgkmcnt(7)
	v_mfma_f32_16x16x32_bf16 v[90:93], v[18:21], v[114:117], v[90:93]
	ds_read_b128 v[18:21], v245 offset:59392
	s_waitcnt lgkmcnt(7)
	v_mfma_f32_16x16x32_bf16 v[90:93], v[22:25], v[118:121], v[90:93]
	ds_read_b128 v[22:25], v245 offset:59456
	s_waitcnt lgkmcnt(7)
	v_mfma_f32_16x16x32_bf16 v[90:93], v[26:29], v[122:125], v[90:93]
	ds_read_b128 v[26:29], v245 offset:59520
	s_waitcnt lgkmcnt(7)
	v_mfma_f32_16x16x32_bf16 v[90:93], v[30:33], v[224:227], v[90:93]
	ds_read_b128 v[30:33], v245 offset:59584
	s_waitcnt lgkmcnt(7)
	v_mfma_f32_16x16x32_bf16 v[94:97], v[2:5], v[98:101], 0
	s_waitcnt lgkmcnt(6)
	v_mfma_f32_16x16x32_bf16 v[94:97], v[6:9], v[102:105], v[94:97]
	s_waitcnt lgkmcnt(5)
	v_mfma_f32_16x16x32_bf16 v[94:97], v[10:13], v[106:109], v[94:97]
	s_waitcnt lgkmcnt(4)
	v_mfma_f32_16x16x32_bf16 v[94:97], v[14:17], v[110:113], v[94:97]
	s_waitcnt lgkmcnt(3)
	v_mfma_f32_16x16x32_bf16 v[94:97], v[18:21], v[114:117], v[94:97]
	s_waitcnt lgkmcnt(2)
	v_mfma_f32_16x16x32_bf16 v[94:97], v[22:25], v[118:121], v[94:97]
	s_waitcnt lgkmcnt(1)
	v_mfma_f32_16x16x32_bf16 v[94:97], v[26:29], v[122:125], v[94:97]
	s_waitcnt lgkmcnt(0)
	v_mfma_f32_16x16x32_bf16 v[94:97], v[30:33], v[224:227], v[94:97]
	global_load_dwordx4 v[98:101], v[246:247], off
	global_load_dwordx4 v[102:105], v[246:247], off offset:64
	global_load_dwordx4 v[106:109], v[246:247], off offset:128
	global_load_dwordx4 v[110:113], v[246:247], off offset:192
	global_load_dwordx4 v[114:117], v[246:247], off offset:256
	global_load_dwordx4 v[118:121], v[246:247], off offset:320
	global_load_dwordx4 v[122:125], v[246:247], off offset:384
	global_load_dwordx4 v[224:227], v[246:247], off offset:448
	v_max3_f32 v248, v34, v35, v205
	v_max3_f32 v248, v248, v36, v37
	v_max3_f32 v248, v248, v38, v39
	v_max3_f32 v248, v248, v40, v41
	v_max3_f32 v248, v248, v42, v43
	v_max3_f32 v248, v248, v44, v45
	v_max3_f32 v248, v248, v46, v47
	v_max3_f32 v248, v248, v48, v49
	v_max3_f32 v248, v248, v50, v51
	v_max3_f32 v248, v248, v52, v53
	v_max3_f32 v248, v248, v54, v55
	v_max3_f32 v248, v248, v56, v57
	v_max3_f32 v248, v248, v58, v59
	v_max3_f32 v248, v248, v60, v61
	v_max3_f32 v248, v248, v62, v63
	v_max3_f32 v248, v248, v64, v65
	v_max3_f32 v248, v248, v66, v67
	v_max3_f32 v248, v248, v68, v69
	v_max3_f32 v248, v248, v70, v71
	v_max3_f32 v248, v248, v72, v73
	v_max3_f32 v248, v248, v74, v75
	v_max3_f32 v248, v248, v76, v77
	v_max3_f32 v248, v248, v78, v79
	v_max3_f32 v248, v248, v80, v81
	v_max3_f32 v248, v248, v82, v83
	v_max3_f32 v248, v248, v84, v85
	v_max3_f32 v248, v248, v86, v87
	v_max3_f32 v248, v248, v88, v89
	v_max3_f32 v248, v248, v90, v91
	v_max3_f32 v248, v248, v92, v93
	v_max3_f32 v248, v248, v94, v95
	v_max3_f32 v248, v248, v96, v97
	v_xor_b32_e32 v228, 16, v195
	v_lshlrev_b32_e32 v228, 2, v228
	ds_bpermute_b32 v228, v228, v248
	s_waitcnt lgkmcnt(0)
	v_max_f32_e32 v248, v248, v228
	v_xor_b32_e32 v228, 32, v195
	v_lshlrev_b32_e32 v228, 2, v228
	ds_bpermute_b32 v228, v228, v248
	s_waitcnt lgkmcnt(0)
	v_max_f32_e32 v248, v248, v228
	v_mul_f32_e32 v248, 0xbdb8aa3b, v248
	v_fmamk_f32 v34, v34, 0x3db8aa3b, v248
	v_fmamk_f32 v35, v35, 0x3db8aa3b, v248
	v_fmamk_f32 v36, v36, 0x3db8aa3b, v248
	v_fmamk_f32 v37, v37, 0x3db8aa3b, v248
	v_exp_f32_e32 v34, v34
	v_exp_f32_e32 v35, v35
	v_exp_f32_e32 v36, v36
	v_exp_f32_e32 v37, v37
	v_fmamk_f32 v38, v38, 0x3db8aa3b, v248
	v_fmamk_f32 v39, v39, 0x3db8aa3b, v248
	v_fmamk_f32 v40, v40, 0x3db8aa3b, v248
	v_fmamk_f32 v41, v41, 0x3db8aa3b, v248
	v_exp_f32_e32 v38, v38
	v_exp_f32_e32 v39, v39
	v_exp_f32_e32 v40, v40
	v_exp_f32_e32 v41, v41
	v_add_f32_e32 v249, 0, v34
	v_add_f32_e32 v249, v249, v35
	v_add_f32_e32 v249, v249, v36
	v_add_f32_e32 v249, v249, v37
	v_fmamk_f32 v42, v42, 0x3db8aa3b, v248
	v_fmamk_f32 v43, v43, 0x3db8aa3b, v248
	v_fmamk_f32 v44, v44, 0x3db8aa3b, v248
	v_fmamk_f32 v45, v45, 0x3db8aa3b, v248
	v_exp_f32_e32 v42, v42
	v_exp_f32_e32 v43, v43
	v_exp_f32_e32 v44, v44
	v_exp_f32_e32 v45, v45
	v_add_f32_e32 v249, v249, v38
	v_add_f32_e32 v249, v249, v39
	v_add_f32_e32 v249, v249, v40
	v_add_f32_e32 v249, v249, v41
	v_fmamk_f32 v46, v46, 0x3db8aa3b, v248
	v_fmamk_f32 v47, v47, 0x3db8aa3b, v248
	v_fmamk_f32 v48, v48, 0x3db8aa3b, v248
	v_fmamk_f32 v49, v49, 0x3db8aa3b, v248
	v_exp_f32_e32 v46, v46
	v_exp_f32_e32 v47, v47
	v_exp_f32_e32 v48, v48
	v_exp_f32_e32 v49, v49
	v_add_f32_e32 v249, v249, v42
	v_add_f32_e32 v249, v249, v43
	v_add_f32_e32 v249, v249, v44
	v_add_f32_e32 v249, v249, v45
	v_fmamk_f32 v50, v50, 0x3db8aa3b, v248
	v_fmamk_f32 v51, v51, 0x3db8aa3b, v248
	v_fmamk_f32 v52, v52, 0x3db8aa3b, v248
	v_fmamk_f32 v53, v53, 0x3db8aa3b, v248
	v_exp_f32_e32 v50, v50
	v_exp_f32_e32 v51, v51
	v_exp_f32_e32 v52, v52
	v_exp_f32_e32 v53, v53
	v_add_f32_e32 v249, v249, v46
	v_add_f32_e32 v249, v249, v47
	v_add_f32_e32 v249, v249, v48
	v_add_f32_e32 v249, v249, v49
	v_fmamk_f32 v54, v54, 0x3db8aa3b, v248
	v_fmamk_f32 v55, v55, 0x3db8aa3b, v248
	v_fmamk_f32 v56, v56, 0x3db8aa3b, v248
	v_fmamk_f32 v57, v57, 0x3db8aa3b, v248
	v_exp_f32_e32 v54, v54
	v_exp_f32_e32 v55, v55
	v_exp_f32_e32 v56, v56
	v_exp_f32_e32 v57, v57
	v_add_f32_e32 v249, v249, v50
	v_add_f32_e32 v249, v249, v51
	v_add_f32_e32 v249, v249, v52
	v_add_f32_e32 v249, v249, v53
	v_fmamk_f32 v58, v58, 0x3db8aa3b, v248
	v_fmamk_f32 v59, v59, 0x3db8aa3b, v248
	v_fmamk_f32 v60, v60, 0x3db8aa3b, v248
	v_fmamk_f32 v61, v61, 0x3db8aa3b, v248
	v_exp_f32_e32 v58, v58
	v_exp_f32_e32 v59, v59
	v_exp_f32_e32 v60, v60
	v_exp_f32_e32 v61, v61
	v_add_f32_e32 v249, v249, v54
	v_add_f32_e32 v249, v249, v55
	v_add_f32_e32 v249, v249, v56
	v_add_f32_e32 v249, v249, v57
	v_fmamk_f32 v62, v62, 0x3db8aa3b, v248
	v_fmamk_f32 v63, v63, 0x3db8aa3b, v248
	v_fmamk_f32 v64, v64, 0x3db8aa3b, v248
	v_fmamk_f32 v65, v65, 0x3db8aa3b, v248
	v_exp_f32_e32 v62, v62
	v_exp_f32_e32 v63, v63
	v_exp_f32_e32 v64, v64
	v_exp_f32_e32 v65, v65
	v_add_f32_e32 v249, v249, v58
	v_add_f32_e32 v249, v249, v59
	v_add_f32_e32 v249, v249, v60
	v_add_f32_e32 v249, v249, v61
	v_fmamk_f32 v66, v66, 0x3db8aa3b, v248
	v_fmamk_f32 v67, v67, 0x3db8aa3b, v248
	v_fmamk_f32 v68, v68, 0x3db8aa3b, v248
	v_fmamk_f32 v69, v69, 0x3db8aa3b, v248
	v_exp_f32_e32 v66, v66
	v_exp_f32_e32 v67, v67
	v_exp_f32_e32 v68, v68
	v_exp_f32_e32 v69, v69
	v_add_f32_e32 v249, v249, v62
	v_add_f32_e32 v249, v249, v63
	v_add_f32_e32 v249, v249, v64
	v_add_f32_e32 v249, v249, v65
	v_fmamk_f32 v70, v70, 0x3db8aa3b, v248
	v_fmamk_f32 v71, v71, 0x3db8aa3b, v248
	v_fmamk_f32 v72, v72, 0x3db8aa3b, v248
	v_fmamk_f32 v73, v73, 0x3db8aa3b, v248
	v_exp_f32_e32 v70, v70
	v_exp_f32_e32 v71, v71
	v_exp_f32_e32 v72, v72
	v_exp_f32_e32 v73, v73
	v_add_f32_e32 v249, v249, v66
	v_add_f32_e32 v249, v249, v67
	v_add_f32_e32 v249, v249, v68
	v_add_f32_e32 v249, v249, v69
	v_fmamk_f32 v74, v74, 0x3db8aa3b, v248
	v_fmamk_f32 v75, v75, 0x3db8aa3b, v248
	v_fmamk_f32 v76, v76, 0x3db8aa3b, v248
	v_fmamk_f32 v77, v77, 0x3db8aa3b, v248
	v_exp_f32_e32 v74, v74
	v_exp_f32_e32 v75, v75
	v_exp_f32_e32 v76, v76
	v_exp_f32_e32 v77, v77
	v_add_f32_e32 v249, v249, v70
	v_add_f32_e32 v249, v249, v71
	v_add_f32_e32 v249, v249, v72
	v_add_f32_e32 v249, v249, v73
	v_fmamk_f32 v78, v78, 0x3db8aa3b, v248
	v_fmamk_f32 v79, v79, 0x3db8aa3b, v248
	v_fmamk_f32 v80, v80, 0x3db8aa3b, v248
	v_fmamk_f32 v81, v81, 0x3db8aa3b, v248
	v_exp_f32_e32 v78, v78
	v_exp_f32_e32 v79, v79
	v_exp_f32_e32 v80, v80
	v_exp_f32_e32 v81, v81
	v_add_f32_e32 v249, v249, v74
	v_add_f32_e32 v249, v249, v75
	v_add_f32_e32 v249, v249, v76
	v_add_f32_e32 v249, v249, v77
	v_fmamk_f32 v82, v82, 0x3db8aa3b, v248
	v_fmamk_f32 v83, v83, 0x3db8aa3b, v248
	v_fmamk_f32 v84, v84, 0x3db8aa3b, v248
	v_fmamk_f32 v85, v85, 0x3db8aa3b, v248
	v_exp_f32_e32 v82, v82
	v_exp_f32_e32 v83, v83
	v_exp_f32_e32 v84, v84
	v_exp_f32_e32 v85, v85
	v_add_f32_e32 v249, v249, v78
	v_add_f32_e32 v249, v249, v79
	v_add_f32_e32 v249, v249, v80
	v_add_f32_e32 v249, v249, v81
	v_fmamk_f32 v86, v86, 0x3db8aa3b, v248
	v_fmamk_f32 v87, v87, 0x3db8aa3b, v248
	v_fmamk_f32 v88, v88, 0x3db8aa3b, v248
	v_fmamk_f32 v89, v89, 0x3db8aa3b, v248
	v_exp_f32_e32 v86, v86
	v_exp_f32_e32 v87, v87
	v_exp_f32_e32 v88, v88
	v_exp_f32_e32 v89, v89
	v_add_f32_e32 v249, v249, v82
	v_add_f32_e32 v249, v249, v83
	v_add_f32_e32 v249, v249, v84
	v_add_f32_e32 v249, v249, v85
	v_fmamk_f32 v90, v90, 0x3db8aa3b, v248
	v_fmamk_f32 v91, v91, 0x3db8aa3b, v248
	v_fmamk_f32 v92, v92, 0x3db8aa3b, v248
	v_fmamk_f32 v93, v93, 0x3db8aa3b, v248
	v_exp_f32_e32 v90, v90
	v_exp_f32_e32 v91, v91
	v_exp_f32_e32 v92, v92
	v_exp_f32_e32 v93, v93
	v_add_f32_e32 v249, v249, v86
	v_add_f32_e32 v249, v249, v87
	v_add_f32_e32 v249, v249, v88
	v_add_f32_e32 v249, v249, v89
	v_fmamk_f32 v94, v94, 0x3db8aa3b, v248
	v_fmamk_f32 v95, v95, 0x3db8aa3b, v248
	v_fmamk_f32 v96, v96, 0x3db8aa3b, v248
	v_fmamk_f32 v97, v97, 0x3db8aa3b, v248
	v_exp_f32_e32 v94, v94
	v_exp_f32_e32 v95, v95
	v_exp_f32_e32 v96, v96
	v_exp_f32_e32 v97, v97
	v_add_f32_e32 v249, v249, v90
	v_add_f32_e32 v249, v249, v91
	v_add_f32_e32 v249, v249, v92
	v_add_f32_e32 v249, v249, v93
	s_nop 0
	v_add_f32_e32 v249, v249, v94
	v_add_f32_e32 v249, v249, v95
	v_add_f32_e32 v249, v249, v96
	v_add_f32_e32 v249, v249, v97
	v_xor_b32_e32 v228, 16, v195
	v_lshlrev_b32_e32 v228, 2, v228
	ds_bpermute_b32 v228, v228, v249
	s_waitcnt lgkmcnt(0)
	v_add_f32_e32 v249, v249, v228
	v_xor_b32_e32 v228, 32, v195
	v_lshlrev_b32_e32 v228, 2, v228
	ds_bpermute_b32 v228, v228, v249
	s_waitcnt lgkmcnt(0)
	v_add_f32_e32 v249, v249, v228
	v_rcp_f32_e32 v134, v249
	v_cvt_pk_bf16_f32 v2, v34, v35
	v_cvt_pk_bf16_f32 v3, v36, v37
	v_cvt_pk_bf16_f32 v4, v38, v39
	v_cvt_pk_bf16_f32 v5, v40, v41
	v_cvt_pk_bf16_f32 v6, v42, v43
	v_cvt_pk_bf16_f32 v7, v44, v45
	v_cvt_pk_bf16_f32 v8, v46, v47
	v_cvt_pk_bf16_f32 v9, v48, v49
	v_cvt_pk_bf16_f32 v10, v50, v51
	v_cvt_pk_bf16_f32 v11, v52, v53
	v_cvt_pk_bf16_f32 v12, v54, v55
	v_cvt_pk_bf16_f32 v13, v56, v57
	v_cvt_pk_bf16_f32 v14, v58, v59
	v_cvt_pk_bf16_f32 v15, v60, v61
	v_cvt_pk_bf16_f32 v16, v62, v63
	v_cvt_pk_bf16_f32 v17, v64, v65
	v_cvt_pk_bf16_f32 v18, v66, v67
	v_cvt_pk_bf16_f32 v19, v68, v69
	v_cvt_pk_bf16_f32 v20, v70, v71
	v_cvt_pk_bf16_f32 v21, v72, v73
	v_cvt_pk_bf16_f32 v22, v74, v75
	v_cvt_pk_bf16_f32 v23, v76, v77
	v_cvt_pk_bf16_f32 v24, v78, v79
	v_cvt_pk_bf16_f32 v25, v80, v81
	v_cvt_pk_bf16_f32 v26, v82, v83
	v_cvt_pk_bf16_f32 v27, v84, v85
	v_cvt_pk_bf16_f32 v28, v86, v87
	v_cvt_pk_bf16_f32 v29, v88, v89
	v_cvt_pk_bf16_f32 v30, v90, v91
	v_cvt_pk_bf16_f32 v31, v92, v93
	v_cvt_pk_bf16_f32 v32, v94, v95
	v_cvt_pk_bf16_f32 v33, v96, v97
	s_waitcnt vmcnt(0)
	ds_read_b128 v[228:231], v244
	ds_read_b128 v[232:235], v244 offset:64
	ds_read_b128 v[236:239], v244 offset:128
	ds_read_b128 v[240:243], v244 offset:192
	s_waitcnt lgkmcnt(3)
	v_mfma_f32_16x16x32_bf16 v[34:37], v[228:231], v[98:101], 0
	ds_read_b128 v[228:231], v244 offset:256
	s_waitcnt lgkmcnt(3)
	v_mfma_f32_16x16x32_bf16 v[34:37], v[232:235], v[102:105], v[34:37]
	ds_read_b128 v[232:235], v244 offset:320
	s_waitcnt lgkmcnt(3)
	v_mfma_f32_16x16x32_bf16 v[34:37], v[236:239], v[106:109], v[34:37]
	ds_read_b128 v[236:239], v244 offset:384
	s_waitcnt lgkmcnt(3)
	v_mfma_f32_16x16x32_bf16 v[34:37], v[240:243], v[110:113], v[34:37]
	ds_read_b128 v[240:243], v244 offset:448
	s_waitcnt lgkmcnt(3)
	v_mfma_f32_16x16x32_bf16 v[34:37], v[228:231], v[114:117], v[34:37]
	ds_read_b128 v[228:231], v244 offset:8448
	s_waitcnt lgkmcnt(3)
	v_mfma_f32_16x16x32_bf16 v[34:37], v[232:235], v[118:121], v[34:37]
	ds_read_b128 v[232:235], v244 offset:8512
	s_waitcnt lgkmcnt(3)
	v_mfma_f32_16x16x32_bf16 v[34:37], v[236:239], v[122:125], v[34:37]
	ds_read_b128 v[236:239], v244 offset:8576
	s_waitcnt lgkmcnt(3)
	v_mfma_f32_16x16x32_bf16 v[34:37], v[240:243], v[224:227], v[34:37]
	ds_read_b128 v[240:243], v244 offset:8640
	s_waitcnt lgkmcnt(3)
	v_mfma_f32_16x16x32_bf16 v[38:41], v[228:231], v[98:101], 0
	ds_read_b128 v[228:231], v244 offset:8704
	s_waitcnt lgkmcnt(3)
	v_mfma_f32_16x16x32_bf16 v[38:41], v[232:235], v[102:105], v[38:41]
	ds_read_b128 v[232:235], v244 offset:8768
	s_waitcnt lgkmcnt(3)
	v_mfma_f32_16x16x32_bf16 v[38:41], v[236:239], v[106:109], v[38:41]
	ds_read_b128 v[236:239], v244 offset:8832
	s_waitcnt lgkmcnt(3)
	v_mfma_f32_16x16x32_bf16 v[38:41], v[240:243], v[110:113], v[38:41]
	ds_read_b128 v[240:243], v244 offset:8896
	s_waitcnt lgkmcnt(3)
	v_mfma_f32_16x16x32_bf16 v[38:41], v[228:231], v[114:117], v[38:41]
	ds_read_b128 v[228:231], v244 offset:16896
	s_waitcnt lgkmcnt(3)
	v_mfma_f32_16x16x32_bf16 v[38:41], v[232:235], v[118:121], v[38:41]
	ds_read_b128 v[232:235], v244 offset:16960
	s_waitcnt lgkmcnt(3)
	v_mfma_f32_16x16x32_bf16 v[38:41], v[236:239], v[122:125], v[38:41]
	ds_read_b128 v[236:239], v244 offset:17024
	s_waitcnt lgkmcnt(3)
	v_mfma_f32_16x16x32_bf16 v[38:41], v[240:243], v[224:227], v[38:41]
	ds_read_b128 v[240:243], v244 offset:17088
	s_waitcnt lgkmcnt(3)
	v_mfma_f32_16x16x32_bf16 v[42:45], v[228:231], v[98:101], 0
	ds_read_b128 v[228:231], v244 offset:17152
	s_waitcnt lgkmcnt(3)
	v_mfma_f32_16x16x32_bf16 v[42:45], v[232:235], v[102:105], v[42:45]
	ds_read_b128 v[232:235], v244 offset:17216
	s_waitcnt lgkmcnt(3)
	v_mfma_f32_16x16x32_bf16 v[42:45], v[236:239], v[106:109], v[42:45]
	ds_read_b128 v[236:239], v244 offset:17280
	s_waitcnt lgkmcnt(3)
	v_mfma_f32_16x16x32_bf16 v[42:45], v[240:243], v[110:113], v[42:45]
	ds_read_b128 v[240:243], v244 offset:17344
	s_waitcnt lgkmcnt(3)
	v_mfma_f32_16x16x32_bf16 v[42:45], v[228:231], v[114:117], v[42:45]
	ds_read_b128 v[228:231], v244 offset:25344
	s_waitcnt lgkmcnt(3)
	v_mfma_f32_16x16x32_bf16 v[42:45], v[232:235], v[118:121], v[42:45]
	ds_read_b128 v[232:235], v244 offset:25408
	s_waitcnt lgkmcnt(3)
	v_mfma_f32_16x16x32_bf16 v[42:45], v[236:239], v[122:125], v[42:45]
	ds_read_b128 v[236:239], v244 offset:25472
	s_waitcnt lgkmcnt(3)
	v_mfma_f32_16x16x32_bf16 v[42:45], v[240:243], v[224:227], v[42:45]
	ds_read_b128 v[240:243], v244 offset:25536
	s_waitcnt lgkmcnt(3)
	v_mfma_f32_16x16x32_bf16 v[46:49], v[228:231], v[98:101], 0
	ds_read_b128 v[228:231], v244 offset:25600
	s_waitcnt lgkmcnt(3)
	v_mfma_f32_16x16x32_bf16 v[46:49], v[232:235], v[102:105], v[46:49]
	ds_read_b128 v[232:235], v244 offset:25664
	s_waitcnt lgkmcnt(3)
	v_mfma_f32_16x16x32_bf16 v[46:49], v[236:239], v[106:109], v[46:49]
	ds_read_b128 v[236:239], v244 offset:25728
	s_waitcnt lgkmcnt(3)
	v_mfma_f32_16x16x32_bf16 v[46:49], v[240:243], v[110:113], v[46:49]
	ds_read_b128 v[240:243], v244 offset:25792
	s_waitcnt lgkmcnt(3)
	v_mfma_f32_16x16x32_bf16 v[46:49], v[228:231], v[114:117], v[46:49]
	ds_read_b128 v[228:231], v244 offset:33792
	s_waitcnt lgkmcnt(3)
	v_mfma_f32_16x16x32_bf16 v[46:49], v[232:235], v[118:121], v[46:49]
	ds_read_b128 v[232:235], v244 offset:33856
	s_waitcnt lgkmcnt(3)
	v_mfma_f32_16x16x32_bf16 v[46:49], v[236:239], v[122:125], v[46:49]
	ds_read_b128 v[236:239], v244 offset:33920
	s_waitcnt lgkmcnt(3)
	v_mfma_f32_16x16x32_bf16 v[46:49], v[240:243], v[224:227], v[46:49]
	ds_read_b128 v[240:243], v244 offset:33984
	s_waitcnt lgkmcnt(3)
	v_mfma_f32_16x16x32_bf16 v[50:53], v[228:231], v[98:101], 0
	ds_read_b128 v[228:231], v244 offset:34048
	s_waitcnt lgkmcnt(3)
	v_mfma_f32_16x16x32_bf16 v[50:53], v[232:235], v[102:105], v[50:53]
	ds_read_b128 v[232:235], v244 offset:34112
	s_waitcnt lgkmcnt(3)
	v_mfma_f32_16x16x32_bf16 v[50:53], v[236:239], v[106:109], v[50:53]
	ds_read_b128 v[236:239], v244 offset:34176
	s_waitcnt lgkmcnt(3)
	v_mfma_f32_16x16x32_bf16 v[50:53], v[240:243], v[110:113], v[50:53]
	ds_read_b128 v[240:243], v244 offset:34240
	s_waitcnt lgkmcnt(3)
	v_mfma_f32_16x16x32_bf16 v[50:53], v[228:231], v[114:117], v[50:53]
	ds_read_b128 v[228:231], v244 offset:42240
	s_waitcnt lgkmcnt(3)
	v_mfma_f32_16x16x32_bf16 v[50:53], v[232:235], v[118:121], v[50:53]
	ds_read_b128 v[232:235], v244 offset:42304
	s_waitcnt lgkmcnt(3)
	v_mfma_f32_16x16x32_bf16 v[50:53], v[236:239], v[122:125], v[50:53]
	ds_read_b128 v[236:239], v244 offset:42368
	s_waitcnt lgkmcnt(3)
	v_mfma_f32_16x16x32_bf16 v[50:53], v[240:243], v[224:227], v[50:53]
	ds_read_b128 v[240:243], v244 offset:42432
	s_waitcnt lgkmcnt(3)
	v_mfma_f32_16x16x32_bf16 v[54:57], v[228:231], v[98:101], 0
	ds_read_b128 v[228:231], v244 offset:42496
	s_waitcnt lgkmcnt(3)
	v_mfma_f32_16x16x32_bf16 v[54:57], v[232:235], v[102:105], v[54:57]
	ds_read_b128 v[232:235], v244 offset:42560
	s_waitcnt lgkmcnt(3)
	v_mfma_f32_16x16x32_bf16 v[54:57], v[236:239], v[106:109], v[54:57]
	ds_read_b128 v[236:239], v244 offset:42624
	s_waitcnt lgkmcnt(3)
	v_mfma_f32_16x16x32_bf16 v[54:57], v[240:243], v[110:113], v[54:57]
	ds_read_b128 v[240:243], v244 offset:42688
	s_waitcnt lgkmcnt(3)
	v_mfma_f32_16x16x32_bf16 v[54:57], v[228:231], v[114:117], v[54:57]
	ds_read_b128 v[228:231], v244 offset:50688
	s_waitcnt lgkmcnt(3)
	v_mfma_f32_16x16x32_bf16 v[54:57], v[232:235], v[118:121], v[54:57]
	ds_read_b128 v[232:235], v244 offset:50752
	s_waitcnt lgkmcnt(3)
	v_mfma_f32_16x16x32_bf16 v[54:57], v[236:239], v[122:125], v[54:57]
	ds_read_b128 v[236:239], v244 offset:50816
	s_waitcnt lgkmcnt(3)
	v_mfma_f32_16x16x32_bf16 v[54:57], v[240:243], v[224:227], v[54:57]
	ds_read_b128 v[240:243], v244 offset:50880
	s_waitcnt lgkmcnt(3)
	v_mfma_f32_16x16x32_bf16 v[58:61], v[228:231], v[98:101], 0
	ds_read_b128 v[228:231], v244 offset:50944
	s_waitcnt lgkmcnt(3)
	v_mfma_f32_16x16x32_bf16 v[58:61], v[232:235], v[102:105], v[58:61]
	ds_read_b128 v[232:235], v244 offset:51008
	s_waitcnt lgkmcnt(3)
	v_mfma_f32_16x16x32_bf16 v[58:61], v[236:239], v[106:109], v[58:61]
	ds_read_b128 v[236:239], v244 offset:51072
	s_waitcnt lgkmcnt(3)
	v_mfma_f32_16x16x32_bf16 v[58:61], v[240:243], v[110:113], v[58:61]
	ds_read_b128 v[240:243], v244 offset:51136
	s_waitcnt lgkmcnt(3)
	v_mfma_f32_16x16x32_bf16 v[58:61], v[228:231], v[114:117], v[58:61]
	ds_read_b128 v[228:231], v244 offset:59136
	s_waitcnt lgkmcnt(3)
	v_mfma_f32_16x16x32_bf16 v[58:61], v[232:235], v[118:121], v[58:61]
	ds_read_b128 v[232:235], v244 offset:59200
	s_waitcnt lgkmcnt(3)
	v_mfma_f32_16x16x32_bf16 v[58:61], v[236:239], v[122:125], v[58:61]
	ds_read_b128 v[236:239], v244 offset:59264
	s_waitcnt lgkmcnt(3)
	v_mfma_f32_16x16x32_bf16 v[58:61], v[240:243], v[224:227], v[58:61]
	ds_read_b128 v[240:243], v244 offset:59328
	s_waitcnt lgkmcnt(3)
	v_mfma_f32_16x16x32_bf16 v[62:65], v[228:231], v[98:101], 0
	ds_read_b128 v[228:231], v244 offset:59392
	s_waitcnt lgkmcnt(3)
	v_mfma_f32_16x16x32_bf16 v[62:65], v[232:235], v[102:105], v[62:65]
	ds_read_b128 v[232:235], v244 offset:59456
	s_waitcnt lgkmcnt(3)
	v_mfma_f32_16x16x32_bf16 v[62:65], v[236:239], v[106:109], v[62:65]
	ds_read_b128 v[236:239], v244 offset:59520
	s_waitcnt lgkmcnt(3)
	v_mfma_f32_16x16x32_bf16 v[62:65], v[240:243], v[110:113], v[62:65]
	ds_read_b128 v[240:243], v244 offset:59584
	s_waitcnt lgkmcnt(3)
	v_mfma_f32_16x16x32_bf16 v[62:65], v[228:231], v[114:117], v[62:65]
	ds_read_b128 v[228:231], v245
	s_waitcnt lgkmcnt(3)
	v_mfma_f32_16x16x32_bf16 v[62:65], v[232:235], v[118:121], v[62:65]
	ds_read_b128 v[232:235], v245 offset:64
	s_waitcnt lgkmcnt(3)
	v_mfma_f32_16x16x32_bf16 v[62:65], v[236:239], v[122:125], v[62:65]
	ds_read_b128 v[236:239], v245 offset:128
	s_waitcnt lgkmcnt(3)
	v_mfma_f32_16x16x32_bf16 v[62:65], v[240:243], v[224:227], v[62:65]
	ds_read_b128 v[240:243], v245 offset:192
	s_waitcnt lgkmcnt(3)
	v_mfma_f32_16x16x32_bf16 v[66:69], v[228:231], v[98:101], 0
	ds_read_b128 v[228:231], v245 offset:256
	s_waitcnt lgkmcnt(3)
	v_mfma_f32_16x16x32_bf16 v[66:69], v[232:235], v[102:105], v[66:69]
	ds_read_b128 v[232:235], v245 offset:320
	s_waitcnt lgkmcnt(3)
	v_mfma_f32_16x16x32_bf16 v[66:69], v[236:239], v[106:109], v[66:69]
	ds_read_b128 v[236:239], v245 offset:384
	s_waitcnt lgkmcnt(3)
	v_mfma_f32_16x16x32_bf16 v[66:69], v[240:243], v[110:113], v[66:69]
	ds_read_b128 v[240:243], v245 offset:448
	s_waitcnt lgkmcnt(3)
	v_mfma_f32_16x16x32_bf16 v[66:69], v[228:231], v[114:117], v[66:69]
	ds_read_b128 v[228:231], v245 offset:8448
	s_waitcnt lgkmcnt(3)
	v_mfma_f32_16x16x32_bf16 v[66:69], v[232:235], v[118:121], v[66:69]
	ds_read_b128 v[232:235], v245 offset:8512
	s_waitcnt lgkmcnt(3)
	v_mfma_f32_16x16x32_bf16 v[66:69], v[236:239], v[122:125], v[66:69]
	ds_read_b128 v[236:239], v245 offset:8576
	s_waitcnt lgkmcnt(3)
	v_mfma_f32_16x16x32_bf16 v[66:69], v[240:243], v[224:227], v[66:69]
	ds_read_b128 v[240:243], v245 offset:8640
	s_waitcnt lgkmcnt(3)
	v_mfma_f32_16x16x32_bf16 v[70:73], v[228:231], v[98:101], 0
	ds_read_b128 v[228:231], v245 offset:8704
	s_waitcnt lgkmcnt(3)
	v_mfma_f32_16x16x32_bf16 v[70:73], v[232:235], v[102:105], v[70:73]
	ds_read_b128 v[232:235], v245 offset:8768
	s_waitcnt lgkmcnt(3)
	v_mfma_f32_16x16x32_bf16 v[70:73], v[236:239], v[106:109], v[70:73]
	ds_read_b128 v[236:239], v245 offset:8832
	s_waitcnt lgkmcnt(3)
	v_mfma_f32_16x16x32_bf16 v[70:73], v[240:243], v[110:113], v[70:73]
	ds_read_b128 v[240:243], v245 offset:8896
	s_waitcnt lgkmcnt(3)
	v_mfma_f32_16x16x32_bf16 v[70:73], v[228:231], v[114:117], v[70:73]
	ds_read_b128 v[228:231], v245 offset:16896
	s_waitcnt lgkmcnt(3)
	v_mfma_f32_16x16x32_bf16 v[70:73], v[232:235], v[118:121], v[70:73]
	ds_read_b128 v[232:235], v245 offset:16960
	s_waitcnt lgkmcnt(3)
	v_mfma_f32_16x16x32_bf16 v[70:73], v[236:239], v[122:125], v[70:73]
	ds_read_b128 v[236:239], v245 offset:17024
	s_waitcnt lgkmcnt(3)
	v_mfma_f32_16x16x32_bf16 v[70:73], v[240:243], v[224:227], v[70:73]
	ds_read_b128 v[240:243], v245 offset:17088
	s_waitcnt lgkmcnt(3)
	v_mfma_f32_16x16x32_bf16 v[74:77], v[228:231], v[98:101], 0
	ds_read_b128 v[228:231], v245 offset:17152
	s_waitcnt lgkmcnt(3)
	v_mfma_f32_16x16x32_bf16 v[74:77], v[232:235], v[102:105], v[74:77]
	ds_read_b128 v[232:235], v245 offset:17216
	s_waitcnt lgkmcnt(3)
	v_mfma_f32_16x16x32_bf16 v[74:77], v[236:239], v[106:109], v[74:77]
	ds_read_b128 v[236:239], v245 offset:17280
	s_waitcnt lgkmcnt(3)
	v_mfma_f32_16x16x32_bf16 v[74:77], v[240:243], v[110:113], v[74:77]
	ds_read_b128 v[240:243], v245 offset:17344
	s_waitcnt lgkmcnt(3)
	v_mfma_f32_16x16x32_bf16 v[74:77], v[228:231], v[114:117], v[74:77]
	ds_read_b128 v[228:231], v245 offset:25344
	s_waitcnt lgkmcnt(3)
	v_mfma_f32_16x16x32_bf16 v[74:77], v[232:235], v[118:121], v[74:77]
	ds_read_b128 v[232:235], v245 offset:25408
	s_waitcnt lgkmcnt(3)
	v_mfma_f32_16x16x32_bf16 v[74:77], v[236:239], v[122:125], v[74:77]
	ds_read_b128 v[236:239], v245 offset:25472
	s_waitcnt lgkmcnt(3)
	v_mfma_f32_16x16x32_bf16 v[74:77], v[240:243], v[224:227], v[74:77]
	ds_read_b128 v[240:243], v245 offset:25536
	s_waitcnt lgkmcnt(3)
	v_mfma_f32_16x16x32_bf16 v[78:81], v[228:231], v[98:101], 0
	ds_read_b128 v[228:231], v245 offset:25600
	s_waitcnt lgkmcnt(3)
	v_mfma_f32_16x16x32_bf16 v[78:81], v[232:235], v[102:105], v[78:81]
	ds_read_b128 v[232:235], v245 offset:25664
	s_waitcnt lgkmcnt(3)
	v_mfma_f32_16x16x32_bf16 v[78:81], v[236:239], v[106:109], v[78:81]
	ds_read_b128 v[236:239], v245 offset:25728
	s_waitcnt lgkmcnt(3)
	v_mfma_f32_16x16x32_bf16 v[78:81], v[240:243], v[110:113], v[78:81]
	ds_read_b128 v[240:243], v245 offset:25792
	s_waitcnt lgkmcnt(3)
	v_mfma_f32_16x16x32_bf16 v[78:81], v[228:231], v[114:117], v[78:81]
	ds_read_b128 v[228:231], v245 offset:33792
	s_waitcnt lgkmcnt(3)
	v_mfma_f32_16x16x32_bf16 v[78:81], v[232:235], v[118:121], v[78:81]
	ds_read_b128 v[232:235], v245 offset:33856
	s_waitcnt lgkmcnt(3)
	v_mfma_f32_16x16x32_bf16 v[78:81], v[236:239], v[122:125], v[78:81]
	ds_read_b128 v[236:239], v245 offset:33920
	s_waitcnt lgkmcnt(3)
	v_mfma_f32_16x16x32_bf16 v[78:81], v[240:243], v[224:227], v[78:81]
	ds_read_b128 v[240:243], v245 offset:33984
	s_waitcnt lgkmcnt(3)
	v_mfma_f32_16x16x32_bf16 v[82:85], v[228:231], v[98:101], 0
	ds_read_b128 v[228:231], v245 offset:34048
	s_waitcnt lgkmcnt(3)
	v_mfma_f32_16x16x32_bf16 v[82:85], v[232:235], v[102:105], v[82:85]
	ds_read_b128 v[232:235], v245 offset:34112
	s_waitcnt lgkmcnt(3)
	v_mfma_f32_16x16x32_bf16 v[82:85], v[236:239], v[106:109], v[82:85]
	ds_read_b128 v[236:239], v245 offset:34176
	s_waitcnt lgkmcnt(3)
	v_mfma_f32_16x16x32_bf16 v[82:85], v[240:243], v[110:113], v[82:85]
	ds_read_b128 v[240:243], v245 offset:34240
	s_waitcnt lgkmcnt(3)
	v_mfma_f32_16x16x32_bf16 v[82:85], v[228:231], v[114:117], v[82:85]
	ds_read_b128 v[228:231], v245 offset:42240
	s_waitcnt lgkmcnt(3)
	v_mfma_f32_16x16x32_bf16 v[82:85], v[232:235], v[118:121], v[82:85]
	ds_read_b128 v[232:235], v245 offset:42304
	s_waitcnt lgkmcnt(3)
	v_mfma_f32_16x16x32_bf16 v[82:85], v[236:239], v[122:125], v[82:85]
	ds_read_b128 v[236:239], v245 offset:42368
	s_waitcnt lgkmcnt(3)
	v_mfma_f32_16x16x32_bf16 v[82:85], v[240:243], v[224:227], v[82:85]
	ds_read_b128 v[240:243], v245 offset:42432
	s_waitcnt lgkmcnt(3)
	v_mfma_f32_16x16x32_bf16 v[86:89], v[228:231], v[98:101], 0
	ds_read_b128 v[228:231], v245 offset:42496
	s_waitcnt lgkmcnt(3)
	v_mfma_f32_16x16x32_bf16 v[86:89], v[232:235], v[102:105], v[86:89]
	ds_read_b128 v[232:235], v245 offset:42560
	s_waitcnt lgkmcnt(3)
	v_mfma_f32_16x16x32_bf16 v[86:89], v[236:239], v[106:109], v[86:89]
	ds_read_b128 v[236:239], v245 offset:42624
	s_waitcnt lgkmcnt(3)
	v_mfma_f32_16x16x32_bf16 v[86:89], v[240:243], v[110:113], v[86:89]
	ds_read_b128 v[240:243], v245 offset:42688
	s_waitcnt lgkmcnt(3)
	v_mfma_f32_16x16x32_bf16 v[86:89], v[228:231], v[114:117], v[86:89]
	ds_read_b128 v[228:231], v245 offset:50688
	s_waitcnt lgkmcnt(3)
	v_mfma_f32_16x16x32_bf16 v[86:89], v[232:235], v[118:121], v[86:89]
	ds_read_b128 v[232:235], v245 offset:50752
	s_waitcnt lgkmcnt(3)
	v_mfma_f32_16x16x32_bf16 v[86:89], v[236:239], v[122:125], v[86:89]
	ds_read_b128 v[236:239], v245 offset:50816
	s_waitcnt lgkmcnt(3)
	v_mfma_f32_16x16x32_bf16 v[86:89], v[240:243], v[224:227], v[86:89]
	ds_read_b128 v[240:243], v245 offset:50880
	s_waitcnt lgkmcnt(3)
	v_mfma_f32_16x16x32_bf16 v[90:93], v[228:231], v[98:101], 0
	ds_read_b128 v[228:231], v245 offset:50944
	s_waitcnt lgkmcnt(3)
	v_mfma_f32_16x16x32_bf16 v[90:93], v[232:235], v[102:105], v[90:93]
	ds_read_b128 v[232:235], v245 offset:51008
	s_waitcnt lgkmcnt(3)
	v_mfma_f32_16x16x32_bf16 v[90:93], v[236:239], v[106:109], v[90:93]
	ds_read_b128 v[236:239], v245 offset:51072
	s_waitcnt lgkmcnt(3)
	v_mfma_f32_16x16x32_bf16 v[90:93], v[240:243], v[110:113], v[90:93]
	ds_read_b128 v[240:243], v245 offset:51136
	s_waitcnt lgkmcnt(3)
	v_mfma_f32_16x16x32_bf16 v[90:93], v[228:231], v[114:117], v[90:93]
	ds_read_b128 v[228:231], v245 offset:59136
	s_waitcnt lgkmcnt(3)
	v_mfma_f32_16x16x32_bf16 v[90:93], v[232:235], v[118:121], v[90:93]
	ds_read_b128 v[232:235], v245 offset:59200
	s_waitcnt lgkmcnt(3)
	v_mfma_f32_16x16x32_bf16 v[90:93], v[236:239], v[122:125], v[90:93]
	ds_read_b128 v[236:239], v245 offset:59264
	s_waitcnt lgkmcnt(3)
	v_mfma_f32_16x16x32_bf16 v[90:93], v[240:243], v[224:227], v[90:93]
	ds_read_b128 v[240:243], v245 offset:59328
	s_waitcnt lgkmcnt(3)
	v_mfma_f32_16x16x32_bf16 v[94:97], v[228:231], v[98:101], 0
	ds_read_b128 v[228:231], v245 offset:59392
	s_waitcnt lgkmcnt(3)
	v_mfma_f32_16x16x32_bf16 v[94:97], v[232:235], v[102:105], v[94:97]
	ds_read_b128 v[232:235], v245 offset:59456
	s_waitcnt lgkmcnt(3)
	v_mfma_f32_16x16x32_bf16 v[94:97], v[236:239], v[106:109], v[94:97]
	ds_read_b128 v[236:239], v245 offset:59520
	s_waitcnt lgkmcnt(3)
	v_mfma_f32_16x16x32_bf16 v[94:97], v[240:243], v[110:113], v[94:97]
	ds_read_b128 v[240:243], v245 offset:59584
	s_waitcnt lgkmcnt(3)
	v_mfma_f32_16x16x32_bf16 v[94:97], v[228:231], v[114:117], v[94:97]
	s_waitcnt lgkmcnt(2)
	v_mfma_f32_16x16x32_bf16 v[94:97], v[232:235], v[118:121], v[94:97]
	s_waitcnt lgkmcnt(1)
	v_mfma_f32_16x16x32_bf16 v[94:97], v[236:239], v[122:125], v[94:97]
	s_waitcnt lgkmcnt(0)
	v_mfma_f32_16x16x32_bf16 v[94:97], v[240:243], v[224:227], v[94:97]
	v_max3_f32 v248, v34, v35, v205
	v_max3_f32 v248, v248, v36, v37
	v_max3_f32 v248, v248, v38, v39
	v_max3_f32 v248, v248, v40, v41
	v_max3_f32 v248, v248, v42, v43
	v_max3_f32 v248, v248, v44, v45
	v_max3_f32 v248, v248, v46, v47
	v_max3_f32 v248, v248, v48, v49
	v_max3_f32 v248, v248, v50, v51
	v_max3_f32 v248, v248, v52, v53
	v_max3_f32 v248, v248, v54, v55
	v_max3_f32 v248, v248, v56, v57
	v_max3_f32 v248, v248, v58, v59
	v_max3_f32 v248, v248, v60, v61
	v_max3_f32 v248, v248, v62, v63
	v_max3_f32 v248, v248, v64, v65
	v_max3_f32 v248, v248, v66, v67
	v_max3_f32 v248, v248, v68, v69
	v_max3_f32 v248, v248, v70, v71
	v_max3_f32 v248, v248, v72, v73
	v_max3_f32 v248, v248, v74, v75
	v_max3_f32 v248, v248, v76, v77
	v_max3_f32 v248, v248, v78, v79
	v_max3_f32 v248, v248, v80, v81
	v_max3_f32 v248, v248, v82, v83
	v_max3_f32 v248, v248, v84, v85
	v_max3_f32 v248, v248, v86, v87
	v_max3_f32 v248, v248, v88, v89
	v_max3_f32 v248, v248, v90, v91
	v_max3_f32 v248, v248, v92, v93
	v_max3_f32 v248, v248, v94, v95
	v_max3_f32 v248, v248, v96, v97
	v_xor_b32_e32 v131, 16, v195
	v_lshlrev_b32_e32 v131, 2, v131
	ds_bpermute_b32 v131, v131, v248
	s_waitcnt lgkmcnt(0)
	v_max_f32_e32 v248, v248, v131
	v_xor_b32_e32 v131, 32, v195
	v_lshlrev_b32_e32 v131, 2, v131
	ds_bpermute_b32 v131, v131, v248
	s_waitcnt lgkmcnt(0)
	v_max_f32_e32 v248, v248, v131
	v_mul_f32_e32 v248, 0xbdb8aa3b, v248
	v_fmamk_f32 v34, v34, 0x3db8aa3b, v248
	v_fmamk_f32 v35, v35, 0x3db8aa3b, v248
	v_fmamk_f32 v36, v36, 0x3db8aa3b, v248
	v_fmamk_f32 v37, v37, 0x3db8aa3b, v248
	v_exp_f32_e32 v34, v34
	v_exp_f32_e32 v35, v35
	v_exp_f32_e32 v36, v36
	v_exp_f32_e32 v37, v37
	v_fmamk_f32 v38, v38, 0x3db8aa3b, v248
	v_fmamk_f32 v39, v39, 0x3db8aa3b, v248
	v_fmamk_f32 v40, v40, 0x3db8aa3b, v248
	v_fmamk_f32 v41, v41, 0x3db8aa3b, v248
	v_exp_f32_e32 v38, v38
	v_exp_f32_e32 v39, v39
	v_exp_f32_e32 v40, v40
	v_exp_f32_e32 v41, v41
	v_add_f32_e32 v249, 0, v34
	v_add_f32_e32 v249, v249, v35
	v_add_f32_e32 v249, v249, v36
	v_add_f32_e32 v249, v249, v37
	v_fmamk_f32 v42, v42, 0x3db8aa3b, v248
	v_fmamk_f32 v43, v43, 0x3db8aa3b, v248
	v_fmamk_f32 v44, v44, 0x3db8aa3b, v248
	v_fmamk_f32 v45, v45, 0x3db8aa3b, v248
	v_exp_f32_e32 v42, v42
	v_exp_f32_e32 v43, v43
	v_exp_f32_e32 v44, v44
	v_exp_f32_e32 v45, v45
	v_add_f32_e32 v249, v249, v38
	v_add_f32_e32 v249, v249, v39
	v_add_f32_e32 v249, v249, v40
	v_add_f32_e32 v249, v249, v41
	v_fmamk_f32 v46, v46, 0x3db8aa3b, v248
	v_fmamk_f32 v47, v47, 0x3db8aa3b, v248
	v_fmamk_f32 v48, v48, 0x3db8aa3b, v248
	v_fmamk_f32 v49, v49, 0x3db8aa3b, v248
	v_exp_f32_e32 v46, v46
	v_exp_f32_e32 v47, v47
	v_exp_f32_e32 v48, v48
	v_exp_f32_e32 v49, v49
	v_add_f32_e32 v249, v249, v42
	v_add_f32_e32 v249, v249, v43
	v_add_f32_e32 v249, v249, v44
	v_add_f32_e32 v249, v249, v45
	v_fmamk_f32 v50, v50, 0x3db8aa3b, v248
	v_fmamk_f32 v51, v51, 0x3db8aa3b, v248
	v_fmamk_f32 v52, v52, 0x3db8aa3b, v248
	v_fmamk_f32 v53, v53, 0x3db8aa3b, v248
	v_exp_f32_e32 v50, v50
	v_exp_f32_e32 v51, v51
	v_exp_f32_e32 v52, v52
	v_exp_f32_e32 v53, v53
	v_add_f32_e32 v249, v249, v46
	v_add_f32_e32 v249, v249, v47
	v_add_f32_e32 v249, v249, v48
	v_add_f32_e32 v249, v249, v49
	v_fmamk_f32 v54, v54, 0x3db8aa3b, v248
	v_fmamk_f32 v55, v55, 0x3db8aa3b, v248
	v_fmamk_f32 v56, v56, 0x3db8aa3b, v248
	v_fmamk_f32 v57, v57, 0x3db8aa3b, v248
	v_exp_f32_e32 v54, v54
	v_exp_f32_e32 v55, v55
	v_exp_f32_e32 v56, v56
	v_exp_f32_e32 v57, v57
	v_add_f32_e32 v249, v249, v50
	v_add_f32_e32 v249, v249, v51
	v_add_f32_e32 v249, v249, v52
	v_add_f32_e32 v249, v249, v53
	v_fmamk_f32 v58, v58, 0x3db8aa3b, v248
	v_fmamk_f32 v59, v59, 0x3db8aa3b, v248
	v_fmamk_f32 v60, v60, 0x3db8aa3b, v248
	v_fmamk_f32 v61, v61, 0x3db8aa3b, v248
	v_exp_f32_e32 v58, v58
	v_exp_f32_e32 v59, v59
	v_exp_f32_e32 v60, v60
	v_exp_f32_e32 v61, v61
	v_add_f32_e32 v249, v249, v54
	v_add_f32_e32 v249, v249, v55
	v_add_f32_e32 v249, v249, v56
	v_add_f32_e32 v249, v249, v57
	v_fmamk_f32 v62, v62, 0x3db8aa3b, v248
	v_fmamk_f32 v63, v63, 0x3db8aa3b, v248
	v_fmamk_f32 v64, v64, 0x3db8aa3b, v248
	v_fmamk_f32 v65, v65, 0x3db8aa3b, v248
	v_exp_f32_e32 v62, v62
	v_exp_f32_e32 v63, v63
	v_exp_f32_e32 v64, v64
	v_exp_f32_e32 v65, v65
	v_add_f32_e32 v249, v249, v58
	v_add_f32_e32 v249, v249, v59
	v_add_f32_e32 v249, v249, v60
	v_add_f32_e32 v249, v249, v61
	v_fmamk_f32 v66, v66, 0x3db8aa3b, v248
	v_fmamk_f32 v67, v67, 0x3db8aa3b, v248
	v_fmamk_f32 v68, v68, 0x3db8aa3b, v248
	v_fmamk_f32 v69, v69, 0x3db8aa3b, v248
	v_exp_f32_e32 v66, v66
	v_exp_f32_e32 v67, v67
	v_exp_f32_e32 v68, v68
	v_exp_f32_e32 v69, v69
	v_add_f32_e32 v249, v249, v62
	v_add_f32_e32 v249, v249, v63
	v_add_f32_e32 v249, v249, v64
	v_add_f32_e32 v249, v249, v65
	v_fmamk_f32 v70, v70, 0x3db8aa3b, v248
	v_fmamk_f32 v71, v71, 0x3db8aa3b, v248
	v_fmamk_f32 v72, v72, 0x3db8aa3b, v248
	v_fmamk_f32 v73, v73, 0x3db8aa3b, v248
	v_exp_f32_e32 v70, v70
	v_exp_f32_e32 v71, v71
	v_exp_f32_e32 v72, v72
	v_exp_f32_e32 v73, v73
	v_add_f32_e32 v249, v249, v66
	v_add_f32_e32 v249, v249, v67
	v_add_f32_e32 v249, v249, v68
	v_add_f32_e32 v249, v249, v69
	v_fmamk_f32 v74, v74, 0x3db8aa3b, v248
	v_fmamk_f32 v75, v75, 0x3db8aa3b, v248
	v_fmamk_f32 v76, v76, 0x3db8aa3b, v248
	v_fmamk_f32 v77, v77, 0x3db8aa3b, v248
	v_exp_f32_e32 v74, v74
	v_exp_f32_e32 v75, v75
	v_exp_f32_e32 v76, v76
	v_exp_f32_e32 v77, v77
	v_add_f32_e32 v249, v249, v70
	v_add_f32_e32 v249, v249, v71
	v_add_f32_e32 v249, v249, v72
	v_add_f32_e32 v249, v249, v73
	v_fmamk_f32 v78, v78, 0x3db8aa3b, v248
	v_fmamk_f32 v79, v79, 0x3db8aa3b, v248
	v_fmamk_f32 v80, v80, 0x3db8aa3b, v248
	v_fmamk_f32 v81, v81, 0x3db8aa3b, v248
	v_exp_f32_e32 v78, v78
	v_exp_f32_e32 v79, v79
	v_exp_f32_e32 v80, v80
	v_exp_f32_e32 v81, v81
	v_add_f32_e32 v249, v249, v74
	v_add_f32_e32 v249, v249, v75
	v_add_f32_e32 v249, v249, v76
	v_add_f32_e32 v249, v249, v77
	v_fmamk_f32 v82, v82, 0x3db8aa3b, v248
	v_fmamk_f32 v83, v83, 0x3db8aa3b, v248
	v_fmamk_f32 v84, v84, 0x3db8aa3b, v248
	v_fmamk_f32 v85, v85, 0x3db8aa3b, v248
	v_exp_f32_e32 v82, v82
	v_exp_f32_e32 v83, v83
	v_exp_f32_e32 v84, v84
	v_exp_f32_e32 v85, v85
	v_add_f32_e32 v249, v249, v78
	v_add_f32_e32 v249, v249, v79
	v_add_f32_e32 v249, v249, v80
	v_add_f32_e32 v249, v249, v81
	v_fmamk_f32 v86, v86, 0x3db8aa3b, v248
	v_fmamk_f32 v87, v87, 0x3db8aa3b, v248
	v_fmamk_f32 v88, v88, 0x3db8aa3b, v248
	v_fmamk_f32 v89, v89, 0x3db8aa3b, v248
	v_exp_f32_e32 v86, v86
	v_exp_f32_e32 v87, v87
	v_exp_f32_e32 v88, v88
	v_exp_f32_e32 v89, v89
	v_add_f32_e32 v249, v249, v82
	v_add_f32_e32 v249, v249, v83
	v_add_f32_e32 v249, v249, v84
	v_add_f32_e32 v249, v249, v85
	v_fmamk_f32 v90, v90, 0x3db8aa3b, v248
	v_fmamk_f32 v91, v91, 0x3db8aa3b, v248
	v_fmamk_f32 v92, v92, 0x3db8aa3b, v248
	v_fmamk_f32 v93, v93, 0x3db8aa3b, v248
	v_exp_f32_e32 v90, v90
	v_exp_f32_e32 v91, v91
	v_exp_f32_e32 v92, v92
	v_exp_f32_e32 v93, v93
	v_add_f32_e32 v249, v249, v86
	v_add_f32_e32 v249, v249, v87
	v_add_f32_e32 v249, v249, v88
	v_add_f32_e32 v249, v249, v89
	v_fmamk_f32 v94, v94, 0x3db8aa3b, v248
	v_fmamk_f32 v95, v95, 0x3db8aa3b, v248
	v_fmamk_f32 v96, v96, 0x3db8aa3b, v248
	v_fmamk_f32 v97, v97, 0x3db8aa3b, v248
	v_exp_f32_e32 v94, v94
	v_exp_f32_e32 v95, v95
	v_exp_f32_e32 v96, v96
	v_exp_f32_e32 v97, v97
	v_add_f32_e32 v249, v249, v90
	v_add_f32_e32 v249, v249, v91
	v_add_f32_e32 v249, v249, v92
	v_add_f32_e32 v249, v249, v93
	s_nop 0
	v_add_f32_e32 v249, v249, v94
	v_add_f32_e32 v249, v249, v95
	v_add_f32_e32 v249, v249, v96
	v_add_f32_e32 v249, v249, v97
	v_xor_b32_e32 v131, 16, v195
	v_lshlrev_b32_e32 v131, 2, v131
	ds_bpermute_b32 v131, v131, v249
	s_waitcnt lgkmcnt(0)
	v_add_f32_e32 v249, v249, v131
	v_xor_b32_e32 v131, 32, v195
	v_lshlrev_b32_e32 v131, 2, v131
	ds_bpermute_b32 v131, v131, v249
	s_waitcnt lgkmcnt(0)
	v_add_f32_e32 v249, v249, v131
	v_rcp_f32_e32 v135, v249
	v_cvt_pk_bf16_f32 v34, v34, v35
	v_cvt_pk_bf16_f32 v35, v36, v37
	v_cvt_pk_bf16_f32 v36, v38, v39
	v_cvt_pk_bf16_f32 v37, v40, v41
	v_cvt_pk_bf16_f32 v38, v42, v43
	v_cvt_pk_bf16_f32 v39, v44, v45
	v_cvt_pk_bf16_f32 v40, v46, v47
	v_cvt_pk_bf16_f32 v41, v48, v49
	v_cvt_pk_bf16_f32 v42, v50, v51
	v_cvt_pk_bf16_f32 v43, v52, v53
	v_cvt_pk_bf16_f32 v44, v54, v55
	v_cvt_pk_bf16_f32 v45, v56, v57
	v_cvt_pk_bf16_f32 v46, v58, v59
	v_cvt_pk_bf16_f32 v47, v60, v61
	v_cvt_pk_bf16_f32 v48, v62, v63
	v_cvt_pk_bf16_f32 v49, v64, v65
	v_cvt_pk_bf16_f32 v50, v66, v67
	v_cvt_pk_bf16_f32 v51, v68, v69
	v_cvt_pk_bf16_f32 v52, v70, v71
	v_cvt_pk_bf16_f32 v53, v72, v73
	v_cvt_pk_bf16_f32 v54, v74, v75
	v_cvt_pk_bf16_f32 v55, v76, v77
	v_cvt_pk_bf16_f32 v56, v78, v79
	v_cvt_pk_bf16_f32 v57, v80, v81
	v_cvt_pk_bf16_f32 v58, v82, v83
	v_cvt_pk_bf16_f32 v59, v84, v85
	v_cvt_pk_bf16_f32 v60, v86, v87
	v_cvt_pk_bf16_f32 v61, v88, v89
	v_cvt_pk_bf16_f32 v62, v90, v91
	v_cvt_pk_bf16_f32 v63, v92, v93
	v_cvt_pk_bf16_f32 v64, v94, v95
	v_cvt_pk_bf16_f32 v65, v96, v97
	v_mov_b32_e32 v131, v1
	s_mov_b32 s5, 0
	v_lshl_add_u64 v[86:87], s[0:1], 0, v[130:131]
	s_mov_b64 s[0:1], -1
	s_waitcnt lgkmcnt(0)
	s_barrier
.LBB0_162:
	v_cndmask_b32_e64 v66, 0, 1, s[0:1]
	v_cmp_ne_u32_e32 vcc, 1, v66
	v_add_u32_e32 v66, s5, v208
	v_ashrrev_i32_e32 v88, 5, v66
	v_ashrrev_i32_e32 v89, 31, v88
	v_lshlrev_b64 v[66:67], 9, v[88:89]
	v_lshl_add_u64 v[66:67], v[86:87], 0, v[66:67]
	v_add_u32_e32 v70, s5, v127
	flat_load_dwordx4 v[66:69], v[66:67]
	v_ashrrev_i32_e32 v90, 5, v70
	v_ashrrev_i32_e32 v91, 31, v90
	v_lshlrev_b64 v[70:71], 9, v[90:91]
	v_lshl_add_u64 v[70:71], v[86:87], 0, v[70:71]
	v_add_u32_e32 v74, s5, v136
	flat_load_dwordx4 v[70:73], v[70:71]
	v_ashrrev_i32_e32 v92, 5, v74
	v_ashrrev_i32_e32 v93, 31, v92
	v_lshlrev_b64 v[74:75], 9, v[92:93]
	v_lshl_add_u64 v[74:75], v[86:87], 0, v[74:75]
	v_add_u32_e32 v78, s5, v137
	flat_load_dwordx4 v[74:77], v[74:75]
	v_ashrrev_i32_e32 v94, 5, v78
	v_ashrrev_i32_e32 v95, 31, v94
	v_lshlrev_b64 v[78:79], 9, v[94:95]
	v_lshl_add_u64 v[78:79], v[86:87], 0, v[78:79]
	v_add_u32_e32 v82, s5, v141
	flat_load_dwordx4 v[78:81], v[78:79]
	v_ashrrev_i32_e32 v96, 5, v82
	v_ashrrev_i32_e32 v97, 31, v96
	v_lshlrev_b64 v[82:83], 9, v[96:97]
	v_lshl_add_u64 v[82:83], v[86:87], 0, v[82:83]
	v_add_u32_e32 v89, s5, v142
	flat_load_dwordx4 v[82:85], v[82:83]
	v_ashrrev_i32_e32 v112, 5, v89
	v_ashrrev_i32_e32 v113, 31, v112
	v_lshlrev_b64 v[100:101], 9, v[112:113]
	v_lshl_add_u64 v[100:101], v[86:87], 0, v[100:101]
	v_add_u32_e32 v89, s5, v143
	flat_load_dwordx4 v[100:103], v[100:101]
	v_ashrrev_i32_e32 v114, 5, v89
	v_ashrrev_i32_e32 v115, 31, v114
	v_lshlrev_b64 v[104:105], 9, v[114:115]
	v_lshl_add_u64 v[104:105], v[86:87], 0, v[104:105]
	flat_load_dwordx4 v[104:107], v[104:105]
	v_add_u32_e32 v89, s5, v144
	v_ashrrev_i32_e32 v116, 5, v89
	v_ashrrev_i32_e32 v117, 31, v116
	v_lshlrev_b64 v[108:109], 9, v[116:117]
	v_lshl_add_u64 v[108:109], v[86:87], 0, v[108:109]
	flat_load_dwordx4 v[108:111], v[108:109]
	v_lshlrev_b32_e32 v89, 2, v88
	v_lshrrev_b32_e32 v91, 1, v88
	v_and_b32_e32 v89, 16, v89
	v_and_b32_e32 v91, 12, v91
	v_and_b32_e32 v88, 0xfffffe3, v88
	v_or3_b32 v88, v88, v89, v91
	v_mad_u64_u32 v[88:89], s[0:1], v88, s85, v[126:127]
	s_movk_i32 s5, 0x1000
	s_and_b64 vcc, exec, vcc
	s_waitcnt vmcnt(0) lgkmcnt(0)
	ds_write_b128 v88, v[66:69]
	v_lshlrev_b32_e32 v66, 2, v90
	v_lshrrev_b32_e32 v67, 1, v90
	v_and_b32_e32 v66, 16, v66
	v_and_b32_e32 v67, 12, v67
	v_and_b32_e32 v68, 0xfffffe3, v90
	v_or3_b32 v66, v68, v66, v67
	v_mad_u64_u32 v[66:67], s[0:1], v66, s85, v[126:127]
	ds_write_b128 v66, v[70:73]
	v_lshlrev_b32_e32 v66, 2, v92
	v_lshrrev_b32_e32 v67, 1, v92
	v_and_b32_e32 v66, 16, v66
	v_and_b32_e32 v67, 12, v67
	v_and_b32_e32 v68, 0xfffffe3, v92
	v_or3_b32 v66, v68, v66, v67
	v_mad_u64_u32 v[66:67], s[0:1], v66, s85, v[126:127]
	ds_write_b128 v66, v[74:77]
	v_lshlrev_b32_e32 v66, 2, v94
	v_lshrrev_b32_e32 v67, 1, v94
	v_and_b32_e32 v66, 16, v66
	v_and_b32_e32 v67, 12, v67
	v_and_b32_e32 v68, 0xfffffe3, v94
	v_or3_b32 v66, v68, v66, v67
	v_mad_u64_u32 v[66:67], s[0:1], v66, s85, v[126:127]
	ds_write_b128 v66, v[78:81]
	v_lshlrev_b32_e32 v66, 2, v96
	v_lshrrev_b32_e32 v67, 1, v96
	v_and_b32_e32 v66, 16, v66
	v_and_b32_e32 v67, 12, v67
	v_and_b32_e32 v68, 0xfffffe3, v96
	v_or3_b32 v66, v68, v66, v67
	v_mad_u64_u32 v[66:67], s[0:1], v66, s85, v[126:127]
	ds_write_b128 v66, v[82:85]
	v_lshlrev_b32_e32 v66, 2, v112
	v_lshrrev_b32_e32 v67, 1, v112
	v_and_b32_e32 v66, 16, v66
	v_and_b32_e32 v67, 12, v67
	v_and_b32_e32 v68, 0xfffffe3, v112
	v_or3_b32 v66, v68, v66, v67
	v_mad_u64_u32 v[66:67], s[0:1], v66, s85, v[126:127]
	ds_write_b128 v66, v[100:103]
	v_lshlrev_b32_e32 v66, 2, v114
	v_lshrrev_b32_e32 v67, 1, v114
	v_and_b32_e32 v66, 16, v66
	v_and_b32_e32 v67, 12, v67
	v_and_b32_e32 v68, 0xfffffe3, v114
	v_or3_b32 v66, v68, v66, v67
	v_mad_u64_u32 v[66:67], s[0:1], v66, s85, v[126:127]
	ds_write_b128 v66, v[104:107]
	v_lshlrev_b32_e32 v66, 2, v116
	v_lshrrev_b32_e32 v67, 1, v116
	v_and_b32_e32 v66, 16, v66
	v_and_b32_e32 v67, 12, v67
	v_and_b32_e32 v68, 0xfffffe3, v116
	v_or3_b32 v66, v68, v66, v67
	v_mad_u64_u32 v[66:67], s[0:1], v66, s85, v[126:127]
	s_mov_b64 s[0:1], 0
	ds_write_b128 v66, v[108:111]
	s_cbranch_vccz .LBB0_162
	s_waitcnt lgkmcnt(0)
	s_barrier
	v_and_b32_e32 v114, 15, v195
	v_lshrrev_b32_e32 v115, 4, v195
	v_and_b32_e32 v115, 3, v115
	v_mul_u32_u24_e32 v114, 0x210, v114
	v_lshl_add_u32 v114, v115, 3, v114
	v_add_u32_e32 v115, 0x10800, v114
	ds_read_b64 v[82:83], v114
	ds_read_b64 v[84:85], v114 offset:32
	ds_read_b64 v[86:87], v114 offset:8448
	ds_read_b64 v[88:89], v114 offset:8480
	ds_read_b64 v[90:91], v114 offset:64
	ds_read_b64 v[92:93], v114 offset:96
	ds_read_b64 v[94:95], v114 offset:8512
	ds_read_b64 v[96:97], v114 offset:8544
	ds_read_b64 v[98:99], v114 offset:128
	ds_read_b64 v[100:101], v114 offset:160
	ds_read_b64 v[102:103], v114 offset:8576
	ds_read_b64 v[104:105], v114 offset:8608
	ds_read_b64 v[106:107], v114 offset:192
	ds_read_b64 v[108:109], v114 offset:224
	ds_read_b64 v[110:111], v114 offset:8640
	ds_read_b64 v[112:113], v114 offset:8672
	s_waitcnt lgkmcnt(12)
	v_mfma_f32_16x16x32_bf16 v[66:69], v[82:85], v[2:5], 0
	v_mfma_f32_16x16x32_bf16 v[70:73], v[82:85], v[34:37], 0
	v_mfma_f32_16x16x32_bf16 v[74:77], v[86:89], v[2:5], 0
	v_mfma_f32_16x16x32_bf16 v[78:81], v[86:89], v[34:37], 0
	ds_read_b64 v[82:83], v114 offset:256
	ds_read_b64 v[84:85], v114 offset:288
	ds_read_b64 v[86:87], v114 offset:8704
	ds_read_b64 v[88:89], v114 offset:8736
	s_waitcnt lgkmcnt(12)
	v_mfma_f32_16x16x32_bf16 v[66:69], v[90:93], v[6:9], v[66:69]
	v_mfma_f32_16x16x32_bf16 v[70:73], v[90:93], v[38:41], v[70:73]
	v_mfma_f32_16x16x32_bf16 v[74:77], v[94:97], v[6:9], v[74:77]
	v_mfma_f32_16x16x32_bf16 v[78:81], v[94:97], v[38:41], v[78:81]
	ds_read_b64 v[90:91], v114 offset:320
	ds_read_b64 v[92:93], v114 offset:352
	ds_read_b64 v[94:95], v114 offset:8768
	ds_read_b64 v[96:97], v114 offset:8800
	s_waitcnt lgkmcnt(12)
	v_mfma_f32_16x16x32_bf16 v[66:69], v[98:101], v[10:13], v[66:69]
	v_mfma_f32_16x16x32_bf16 v[70:73], v[98:101], v[42:45], v[70:73]
	v_mfma_f32_16x16x32_bf16 v[74:77], v[102:105], v[10:13], v[74:77]
	v_mfma_f32_16x16x32_bf16 v[78:81], v[102:105], v[42:45], v[78:81]
	ds_read_b64 v[98:99], v114 offset:384
	ds_read_b64 v[100:101], v114 offset:416
	ds_read_b64 v[102:103], v114 offset:8832
	ds_read_b64 v[104:105], v114 offset:8864
	s_waitcnt lgkmcnt(12)
	v_mfma_f32_16x16x32_bf16 v[66:69], v[106:109], v[14:17], v[66:69]
	v_mfma_f32_16x16x32_bf16 v[70:73], v[106:109], v[46:49], v[70:73]
	v_mfma_f32_16x16x32_bf16 v[74:77], v[110:113], v[14:17], v[74:77]
	v_mfma_f32_16x16x32_bf16 v[78:81], v[110:113], v[46:49], v[78:81]
	ds_read_b64 v[106:107], v114 offset:448
	ds_read_b64 v[108:109], v114 offset:480
	ds_read_b64 v[110:111], v114 offset:8896
	ds_read_b64 v[112:113], v114 offset:8928
	s_waitcnt lgkmcnt(12)
	v_mfma_f32_16x16x32_bf16 v[66:69], v[82:85], v[18:21], v[66:69]
	v_mfma_f32_16x16x32_bf16 v[70:73], v[82:85], v[50:53], v[70:73]
	v_mfma_f32_16x16x32_bf16 v[74:77], v[86:89], v[18:21], v[74:77]
	v_mfma_f32_16x16x32_bf16 v[78:81], v[86:89], v[50:53], v[78:81]
	ds_read_b64 v[82:83], v114 offset:16896
	ds_read_b64 v[84:85], v114 offset:16928
	ds_read_b64 v[86:87], v114 offset:25344
	ds_read_b64 v[88:89], v114 offset:25376
	s_waitcnt lgkmcnt(12)
	v_mfma_f32_16x16x32_bf16 v[66:69], v[90:93], v[22:25], v[66:69]
	v_mfma_f32_16x16x32_bf16 v[70:73], v[90:93], v[54:57], v[70:73]
	v_mfma_f32_16x16x32_bf16 v[74:77], v[94:97], v[22:25], v[74:77]
	v_mfma_f32_16x16x32_bf16 v[78:81], v[94:97], v[54:57], v[78:81]
	ds_read_b64 v[90:91], v114 offset:16960
	ds_read_b64 v[92:93], v114 offset:16992
	ds_read_b64 v[94:95], v114 offset:25408
	ds_read_b64 v[96:97], v114 offset:25440
	s_waitcnt lgkmcnt(12)
	v_mfma_f32_16x16x32_bf16 v[66:69], v[98:101], v[26:29], v[66:69]
	v_mfma_f32_16x16x32_bf16 v[70:73], v[98:101], v[58:61], v[70:73]
	v_mfma_f32_16x16x32_bf16 v[74:77], v[102:105], v[26:29], v[74:77]
	v_mfma_f32_16x16x32_bf16 v[78:81], v[102:105], v[58:61], v[78:81]
	ds_read_b64 v[98:99], v114 offset:17024
	ds_read_b64 v[100:101], v114 offset:17056
	ds_read_b64 v[102:103], v114 offset:25472
	ds_read_b64 v[104:105], v114 offset:25504
	s_waitcnt lgkmcnt(12)
	v_mfma_f32_16x16x32_bf16 v[66:69], v[106:109], v[30:33], v[66:69]
	v_mfma_f32_16x16x32_bf16 v[70:73], v[106:109], v[62:65], v[70:73]
	v_mfma_f32_16x16x32_bf16 v[74:77], v[110:113], v[30:33], v[74:77]
	v_mfma_f32_16x16x32_bf16 v[78:81], v[110:113], v[62:65], v[78:81]
	ds_read_b64 v[106:107], v114 offset:17088
	ds_read_b64 v[108:109], v114 offset:17120
	ds_read_b64 v[110:111], v114 offset:25536
	ds_read_b64 v[112:113], v114 offset:25568
	s_waitcnt lgkmcnt(12)
	v_mfma_f32_16x16x32_bf16 v[224:227], v[82:85], v[2:5], 0
	v_mfma_f32_16x16x32_bf16 v[228:231], v[82:85], v[34:37], 0
	v_mfma_f32_16x16x32_bf16 v[232:235], v[86:89], v[2:5], 0
	v_mfma_f32_16x16x32_bf16 v[236:239], v[86:89], v[34:37], 0
	ds_read_b64 v[82:83], v114 offset:17152
	ds_read_b64 v[84:85], v114 offset:17184
	ds_read_b64 v[86:87], v114 offset:25600
	ds_read_b64 v[88:89], v114 offset:25632
	s_waitcnt lgkmcnt(12)
	v_mfma_f32_16x16x32_bf16 v[224:227], v[90:93], v[6:9], v[224:227]
	v_mfma_f32_16x16x32_bf16 v[228:231], v[90:93], v[38:41], v[228:231]
	v_mfma_f32_16x16x32_bf16 v[232:235], v[94:97], v[6:9], v[232:235]
	v_mfma_f32_16x16x32_bf16 v[236:239], v[94:97], v[38:41], v[236:239]
	ds_read_b64 v[90:91], v114 offset:17216
	ds_read_b64 v[92:93], v114 offset:17248
	ds_read_b64 v[94:95], v114 offset:25664
	ds_read_b64 v[96:97], v114 offset:25696
	s_waitcnt lgkmcnt(12)
	v_mfma_f32_16x16x32_bf16 v[224:227], v[98:101], v[10:13], v[224:227]
	v_mfma_f32_16x16x32_bf16 v[228:231], v[98:101], v[42:45], v[228:231]
	v_mfma_f32_16x16x32_bf16 v[232:235], v[102:105], v[10:13], v[232:235]
	v_mfma_f32_16x16x32_bf16 v[236:239], v[102:105], v[42:45], v[236:239]
	v_mul_f32_e32 v66, v134, v66
	v_mul_f32_e32 v67, v134, v67
	v_mul_f32_e32 v68, v134, v68
	v_mul_f32_e32 v69, v134, v69
	v_mul_f32_e32 v74, v134, v74
	v_mul_f32_e32 v75, v134, v75
	v_mul_f32_e32 v76, v134, v76
	v_mul_f32_e32 v77, v134, v77
	v_cvt_pk_bf16_f32 v116, v66, v67
	v_cvt_pk_bf16_f32 v117, v68, v69
	v_cvt_pk_bf16_f32 v118, v74, v75
	v_cvt_pk_bf16_f32 v119, v76, v77
	global_store_dwordx4 v[132:133], v[116:119], off
	v_mul_f32_e32 v70, v135, v70
	v_mul_f32_e32 v71, v135, v71
	v_mul_f32_e32 v72, v135, v72
	v_mul_f32_e32 v73, v135, v73
	v_mul_f32_e32 v78, v135, v78
	v_mul_f32_e32 v79, v135, v79
	v_mul_f32_e32 v80, v135, v80
	v_mul_f32_e32 v81, v135, v81
	v_cvt_pk_bf16_f32 v120, v70, v71
	v_cvt_pk_bf16_f32 v121, v72, v73
	v_cvt_pk_bf16_f32 v122, v78, v79
	v_cvt_pk_bf16_f32 v123, v80, v81
	global_store_dwordx4 v[246:247], v[120:123], off
	ds_read_b64 v[98:99], v114 offset:17280
	ds_read_b64 v[100:101], v114 offset:17312
	ds_read_b64 v[102:103], v114 offset:25728
	ds_read_b64 v[104:105], v114 offset:25760
	s_waitcnt lgkmcnt(12)
	v_mfma_f32_16x16x32_bf16 v[224:227], v[106:109], v[14:17], v[224:227]
	v_mfma_f32_16x16x32_bf16 v[228:231], v[106:109], v[46:49], v[228:231]
	v_mfma_f32_16x16x32_bf16 v[232:235], v[110:113], v[14:17], v[232:235]
	v_mfma_f32_16x16x32_bf16 v[236:239], v[110:113], v[46:49], v[236:239]
	ds_read_b64 v[106:107], v114 offset:17344
	ds_read_b64 v[108:109], v114 offset:17376
	ds_read_b64 v[110:111], v114 offset:25792
	ds_read_b64 v[112:113], v114 offset:25824
	s_waitcnt lgkmcnt(12)
	v_mfma_f32_16x16x32_bf16 v[224:227], v[82:85], v[18:21], v[224:227]
	v_mfma_f32_16x16x32_bf16 v[228:231], v[82:85], v[50:53], v[228:231]
	v_mfma_f32_16x16x32_bf16 v[232:235], v[86:89], v[18:21], v[232:235]
	v_mfma_f32_16x16x32_bf16 v[236:239], v[86:89], v[50:53], v[236:239]
	ds_read_b64 v[82:83], v114 offset:33792
	ds_read_b64 v[84:85], v114 offset:33824
	ds_read_b64 v[86:87], v114 offset:42240
	ds_read_b64 v[88:89], v114 offset:42272
	s_waitcnt lgkmcnt(12)
	v_mfma_f32_16x16x32_bf16 v[224:227], v[90:93], v[22:25], v[224:227]
	v_mfma_f32_16x16x32_bf16 v[228:231], v[90:93], v[54:57], v[228:231]
	v_mfma_f32_16x16x32_bf16 v[232:235], v[94:97], v[22:25], v[232:235]
	v_mfma_f32_16x16x32_bf16 v[236:239], v[94:97], v[54:57], v[236:239]
	ds_read_b64 v[90:91], v114 offset:33856
	ds_read_b64 v[92:93], v114 offset:33888
	ds_read_b64 v[94:95], v114 offset:42304
	ds_read_b64 v[96:97], v114 offset:42336
	s_waitcnt lgkmcnt(12)
	v_mfma_f32_16x16x32_bf16 v[224:227], v[98:101], v[26:29], v[224:227]
	v_mfma_f32_16x16x32_bf16 v[228:231], v[98:101], v[58:61], v[228:231]
	v_mfma_f32_16x16x32_bf16 v[232:235], v[102:105], v[26:29], v[232:235]
	v_mfma_f32_16x16x32_bf16 v[236:239], v[102:105], v[58:61], v[236:239]
	ds_read_b64 v[98:99], v114 offset:33920
	ds_read_b64 v[100:101], v114 offset:33952
	ds_read_b64 v[102:103], v114 offset:42368
	ds_read_b64 v[104:105], v114 offset:42400
	s_waitcnt lgkmcnt(12)
	v_mfma_f32_16x16x32_bf16 v[224:227], v[106:109], v[30:33], v[224:227]
	v_mfma_f32_16x16x32_bf16 v[228:231], v[106:109], v[62:65], v[228:231]
	v_mfma_f32_16x16x32_bf16 v[232:235], v[110:113], v[30:33], v[232:235]
	v_mfma_f32_16x16x32_bf16 v[236:239], v[110:113], v[62:65], v[236:239]
	ds_read_b64 v[106:107], v114 offset:33984
	ds_read_b64 v[108:109], v114 offset:34016
	ds_read_b64 v[110:111], v114 offset:42432
	ds_read_b64 v[112:113], v114 offset:42464
	s_waitcnt lgkmcnt(12)
	v_mfma_f32_16x16x32_bf16 v[66:69], v[82:85], v[2:5], 0
	v_mfma_f32_16x16x32_bf16 v[70:73], v[82:85], v[34:37], 0
	v_mfma_f32_16x16x32_bf16 v[74:77], v[86:89], v[2:5], 0
	v_mfma_f32_16x16x32_bf16 v[78:81], v[86:89], v[34:37], 0
	ds_read_b64 v[82:83], v114 offset:34048
	ds_read_b64 v[84:85], v114 offset:34080
	ds_read_b64 v[86:87], v114 offset:42496
	ds_read_b64 v[88:89], v114 offset:42528
	s_waitcnt lgkmcnt(12)
	v_mfma_f32_16x16x32_bf16 v[66:69], v[90:93], v[6:9], v[66:69]
	v_mfma_f32_16x16x32_bf16 v[70:73], v[90:93], v[38:41], v[70:73]
	v_mfma_f32_16x16x32_bf16 v[74:77], v[94:97], v[6:9], v[74:77]
	v_mfma_f32_16x16x32_bf16 v[78:81], v[94:97], v[38:41], v[78:81]
	ds_read_b64 v[90:91], v114 offset:34112
	ds_read_b64 v[92:93], v114 offset:34144
	ds_read_b64 v[94:95], v114 offset:42560
	ds_read_b64 v[96:97], v114 offset:42592
	s_waitcnt lgkmcnt(12)
	v_mfma_f32_16x16x32_bf16 v[66:69], v[98:101], v[10:13], v[66:69]
	v_mfma_f32_16x16x32_bf16 v[70:73], v[98:101], v[42:45], v[70:73]
	v_mfma_f32_16x16x32_bf16 v[74:77], v[102:105], v[10:13], v[74:77]
	v_mfma_f32_16x16x32_bf16 v[78:81], v[102:105], v[42:45], v[78:81]
	v_mul_f32_e32 v224, v134, v224
	v_mul_f32_e32 v225, v134, v225
	v_mul_f32_e32 v226, v134, v226
	v_mul_f32_e32 v227, v134, v227
	v_mul_f32_e32 v232, v134, v232
	v_mul_f32_e32 v233, v134, v233
	v_mul_f32_e32 v234, v134, v234
	v_mul_f32_e32 v235, v134, v235
	v_cvt_pk_bf16_f32 v116, v224, v225
	v_cvt_pk_bf16_f32 v117, v226, v227
	v_cvt_pk_bf16_f32 v118, v232, v233
	v_cvt_pk_bf16_f32 v119, v234, v235
	global_store_dwordx4 v[132:133], v[116:119], off offset:64
	v_mul_f32_e32 v228, v135, v228
	v_mul_f32_e32 v229, v135, v229
	v_mul_f32_e32 v230, v135, v230
	v_mul_f32_e32 v231, v135, v231
	v_mul_f32_e32 v236, v135, v236
	v_mul_f32_e32 v237, v135, v237
	v_mul_f32_e32 v238, v135, v238
	v_mul_f32_e32 v239, v135, v239
	v_cvt_pk_bf16_f32 v120, v228, v229
	v_cvt_pk_bf16_f32 v121, v230, v231
	v_cvt_pk_bf16_f32 v122, v236, v237
	v_cvt_pk_bf16_f32 v123, v238, v239
	global_store_dwordx4 v[246:247], v[120:123], off offset:64
	ds_read_b64 v[98:99], v114 offset:34176
	ds_read_b64 v[100:101], v114 offset:34208
	ds_read_b64 v[102:103], v114 offset:42624
	ds_read_b64 v[104:105], v114 offset:42656
	s_waitcnt lgkmcnt(12)
	v_mfma_f32_16x16x32_bf16 v[66:69], v[106:109], v[14:17], v[66:69]
	v_mfma_f32_16x16x32_bf16 v[70:73], v[106:109], v[46:49], v[70:73]
	v_mfma_f32_16x16x32_bf16 v[74:77], v[110:113], v[14:17], v[74:77]
	v_mfma_f32_16x16x32_bf16 v[78:81], v[110:113], v[46:49], v[78:81]
	ds_read_b64 v[106:107], v114 offset:34240
	ds_read_b64 v[108:109], v114 offset:34272
	ds_read_b64 v[110:111], v114 offset:42688
	ds_read_b64 v[112:113], v114 offset:42720
	s_waitcnt lgkmcnt(12)
	v_mfma_f32_16x16x32_bf16 v[66:69], v[82:85], v[18:21], v[66:69]
	v_mfma_f32_16x16x32_bf16 v[70:73], v[82:85], v[50:53], v[70:73]
	v_mfma_f32_16x16x32_bf16 v[74:77], v[86:89], v[18:21], v[74:77]
	v_mfma_f32_16x16x32_bf16 v[78:81], v[86:89], v[50:53], v[78:81]
	ds_read_b64 v[82:83], v114 offset:50688
	ds_read_b64 v[84:85], v114 offset:50720
	ds_read_b64 v[86:87], v114 offset:59136
	ds_read_b64 v[88:89], v114 offset:59168
	s_waitcnt lgkmcnt(12)
	v_mfma_f32_16x16x32_bf16 v[66:69], v[90:93], v[22:25], v[66:69]
	v_mfma_f32_16x16x32_bf16 v[70:73], v[90:93], v[54:57], v[70:73]
	v_mfma_f32_16x16x32_bf16 v[74:77], v[94:97], v[22:25], v[74:77]
	v_mfma_f32_16x16x32_bf16 v[78:81], v[94:97], v[54:57], v[78:81]
	ds_read_b64 v[90:91], v114 offset:50752
	ds_read_b64 v[92:93], v114 offset:50784
	ds_read_b64 v[94:95], v114 offset:59200
	ds_read_b64 v[96:97], v114 offset:59232
	s_waitcnt lgkmcnt(12)
	v_mfma_f32_16x16x32_bf16 v[66:69], v[98:101], v[26:29], v[66:69]
	v_mfma_f32_16x16x32_bf16 v[70:73], v[98:101], v[58:61], v[70:73]
	v_mfma_f32_16x16x32_bf16 v[74:77], v[102:105], v[26:29], v[74:77]
	v_mfma_f32_16x16x32_bf16 v[78:81], v[102:105], v[58:61], v[78:81]
	ds_read_b64 v[98:99], v114 offset:50816
	ds_read_b64 v[100:101], v114 offset:50848
	ds_read_b64 v[102:103], v114 offset:59264
	ds_read_b64 v[104:105], v114 offset:59296
	s_waitcnt lgkmcnt(12)
	v_mfma_f32_16x16x32_bf16 v[66:69], v[106:109], v[30:33], v[66:69]
	v_mfma_f32_16x16x32_bf16 v[70:73], v[106:109], v[62:65], v[70:73]
	v_mfma_f32_16x16x32_bf16 v[74:77], v[110:113], v[30:33], v[74:77]
	v_mfma_f32_16x16x32_bf16 v[78:81], v[110:113], v[62:65], v[78:81]
	ds_read_b64 v[106:107], v114 offset:50880
	ds_read_b64 v[108:109], v114 offset:50912
	ds_read_b64 v[110:111], v114 offset:59328
	ds_read_b64 v[112:113], v114 offset:59360
	s_waitcnt lgkmcnt(12)
	v_mfma_f32_16x16x32_bf16 v[224:227], v[82:85], v[2:5], 0
	v_mfma_f32_16x16x32_bf16 v[228:231], v[82:85], v[34:37], 0
	v_mfma_f32_16x16x32_bf16 v[232:235], v[86:89], v[2:5], 0
	v_mfma_f32_16x16x32_bf16 v[236:239], v[86:89], v[34:37], 0
	ds_read_b64 v[82:83], v114 offset:50944
	ds_read_b64 v[84:85], v114 offset:50976
	ds_read_b64 v[86:87], v114 offset:59392
	ds_read_b64 v[88:89], v114 offset:59424
	s_waitcnt lgkmcnt(12)
	v_mfma_f32_16x16x32_bf16 v[224:227], v[90:93], v[6:9], v[224:227]
	v_mfma_f32_16x16x32_bf16 v[228:231], v[90:93], v[38:41], v[228:231]
	v_mfma_f32_16x16x32_bf16 v[232:235], v[94:97], v[6:9], v[232:235]
	v_mfma_f32_16x16x32_bf16 v[236:239], v[94:97], v[38:41], v[236:239]
	ds_read_b64 v[90:91], v114 offset:51008
	ds_read_b64 v[92:93], v114 offset:51040
	ds_read_b64 v[94:95], v114 offset:59456
	ds_read_b64 v[96:97], v114 offset:59488
	s_waitcnt lgkmcnt(12)
	v_mfma_f32_16x16x32_bf16 v[224:227], v[98:101], v[10:13], v[224:227]
	v_mfma_f32_16x16x32_bf16 v[228:231], v[98:101], v[42:45], v[228:231]
	v_mfma_f32_16x16x32_bf16 v[232:235], v[102:105], v[10:13], v[232:235]
	v_mfma_f32_16x16x32_bf16 v[236:239], v[102:105], v[42:45], v[236:239]
	v_mul_f32_e32 v66, v134, v66
	v_mul_f32_e32 v67, v134, v67
	v_mul_f32_e32 v68, v134, v68
	v_mul_f32_e32 v69, v134, v69
	v_mul_f32_e32 v74, v134, v74
	v_mul_f32_e32 v75, v134, v75
	v_mul_f32_e32 v76, v134, v76
	v_mul_f32_e32 v77, v134, v77
	v_cvt_pk_bf16_f32 v116, v66, v67
	v_cvt_pk_bf16_f32 v117, v68, v69
	v_cvt_pk_bf16_f32 v118, v74, v75
	v_cvt_pk_bf16_f32 v119, v76, v77
	global_store_dwordx4 v[132:133], v[116:119], off offset:128
	v_mul_f32_e32 v70, v135, v70
	v_mul_f32_e32 v71, v135, v71
	v_mul_f32_e32 v72, v135, v72
	v_mul_f32_e32 v73, v135, v73
	v_mul_f32_e32 v78, v135, v78
	v_mul_f32_e32 v79, v135, v79
	v_mul_f32_e32 v80, v135, v80
	v_mul_f32_e32 v81, v135, v81
	v_cvt_pk_bf16_f32 v120, v70, v71
	v_cvt_pk_bf16_f32 v121, v72, v73
	v_cvt_pk_bf16_f32 v122, v78, v79
	v_cvt_pk_bf16_f32 v123, v80, v81
	global_store_dwordx4 v[246:247], v[120:123], off offset:128
	ds_read_b64 v[98:99], v114 offset:51072
	ds_read_b64 v[100:101], v114 offset:51104
	ds_read_b64 v[102:103], v114 offset:59520
	ds_read_b64 v[104:105], v114 offset:59552
	s_waitcnt lgkmcnt(12)
	v_mfma_f32_16x16x32_bf16 v[224:227], v[106:109], v[14:17], v[224:227]
	v_mfma_f32_16x16x32_bf16 v[228:231], v[106:109], v[46:49], v[228:231]
	v_mfma_f32_16x16x32_bf16 v[232:235], v[110:113], v[14:17], v[232:235]
	v_mfma_f32_16x16x32_bf16 v[236:239], v[110:113], v[46:49], v[236:239]
	ds_read_b64 v[106:107], v114 offset:51136
	ds_read_b64 v[108:109], v114 offset:51168
	ds_read_b64 v[110:111], v114 offset:59584
	ds_read_b64 v[112:113], v114 offset:59616
	s_waitcnt lgkmcnt(12)
	v_mfma_f32_16x16x32_bf16 v[224:227], v[82:85], v[18:21], v[224:227]
	v_mfma_f32_16x16x32_bf16 v[228:231], v[82:85], v[50:53], v[228:231]
	v_mfma_f32_16x16x32_bf16 v[232:235], v[86:89], v[18:21], v[232:235]
	v_mfma_f32_16x16x32_bf16 v[236:239], v[86:89], v[50:53], v[236:239]
	ds_read_b64 v[82:83], v115
	ds_read_b64 v[84:85], v115 offset:32
	ds_read_b64 v[86:87], v115 offset:8448
	ds_read_b64 v[88:89], v115 offset:8480
	s_waitcnt lgkmcnt(12)
	v_mfma_f32_16x16x32_bf16 v[224:227], v[90:93], v[22:25], v[224:227]
	v_mfma_f32_16x16x32_bf16 v[228:231], v[90:93], v[54:57], v[228:231]
	v_mfma_f32_16x16x32_bf16 v[232:235], v[94:97], v[22:25], v[232:235]
	v_mfma_f32_16x16x32_bf16 v[236:239], v[94:97], v[54:57], v[236:239]
	ds_read_b64 v[90:91], v115 offset:64
	ds_read_b64 v[92:93], v115 offset:96
	ds_read_b64 v[94:95], v115 offset:8512
	ds_read_b64 v[96:97], v115 offset:8544
	s_waitcnt lgkmcnt(12)
	v_mfma_f32_16x16x32_bf16 v[224:227], v[98:101], v[26:29], v[224:227]
	v_mfma_f32_16x16x32_bf16 v[228:231], v[98:101], v[58:61], v[228:231]
	v_mfma_f32_16x16x32_bf16 v[232:235], v[102:105], v[26:29], v[232:235]
	v_mfma_f32_16x16x32_bf16 v[236:239], v[102:105], v[58:61], v[236:239]
	ds_read_b64 v[98:99], v115 offset:128
	ds_read_b64 v[100:101], v115 offset:160
	ds_read_b64 v[102:103], v115 offset:8576
	ds_read_b64 v[104:105], v115 offset:8608
	s_waitcnt lgkmcnt(12)
	v_mfma_f32_16x16x32_bf16 v[224:227], v[106:109], v[30:33], v[224:227]
	v_mfma_f32_16x16x32_bf16 v[228:231], v[106:109], v[62:65], v[228:231]
	v_mfma_f32_16x16x32_bf16 v[232:235], v[110:113], v[30:33], v[232:235]
	v_mfma_f32_16x16x32_bf16 v[236:239], v[110:113], v[62:65], v[236:239]
	ds_read_b64 v[106:107], v115 offset:192
	ds_read_b64 v[108:109], v115 offset:224
	ds_read_b64 v[110:111], v115 offset:8640
	ds_read_b64 v[112:113], v115 offset:8672
	s_waitcnt lgkmcnt(12)
	v_mfma_f32_16x16x32_bf16 v[66:69], v[82:85], v[2:5], 0
	v_mfma_f32_16x16x32_bf16 v[70:73], v[82:85], v[34:37], 0
	v_mfma_f32_16x16x32_bf16 v[74:77], v[86:89], v[2:5], 0
	v_mfma_f32_16x16x32_bf16 v[78:81], v[86:89], v[34:37], 0
	ds_read_b64 v[82:83], v115 offset:256
	ds_read_b64 v[84:85], v115 offset:288
	ds_read_b64 v[86:87], v115 offset:8704
	ds_read_b64 v[88:89], v115 offset:8736
	s_waitcnt lgkmcnt(12)
	v_mfma_f32_16x16x32_bf16 v[66:69], v[90:93], v[6:9], v[66:69]
	v_mfma_f32_16x16x32_bf16 v[70:73], v[90:93], v[38:41], v[70:73]
	v_mfma_f32_16x16x32_bf16 v[74:77], v[94:97], v[6:9], v[74:77]
	v_mfma_f32_16x16x32_bf16 v[78:81], v[94:97], v[38:41], v[78:81]
	ds_read_b64 v[90:91], v115 offset:320
	ds_read_b64 v[92:93], v115 offset:352
	ds_read_b64 v[94:95], v115 offset:8768
	ds_read_b64 v[96:97], v115 offset:8800
	s_waitcnt lgkmcnt(12)
	v_mfma_f32_16x16x32_bf16 v[66:69], v[98:101], v[10:13], v[66:69]
	v_mfma_f32_16x16x32_bf16 v[70:73], v[98:101], v[42:45], v[70:73]
	v_mfma_f32_16x16x32_bf16 v[74:77], v[102:105], v[10:13], v[74:77]
	v_mfma_f32_16x16x32_bf16 v[78:81], v[102:105], v[42:45], v[78:81]
	v_mul_f32_e32 v224, v134, v224
	v_mul_f32_e32 v225, v134, v225
	v_mul_f32_e32 v226, v134, v226
	v_mul_f32_e32 v227, v134, v227
	v_mul_f32_e32 v232, v134, v232
	v_mul_f32_e32 v233, v134, v233
	v_mul_f32_e32 v234, v134, v234
	v_mul_f32_e32 v235, v134, v235
	v_cvt_pk_bf16_f32 v116, v224, v225
	v_cvt_pk_bf16_f32 v117, v226, v227
	v_cvt_pk_bf16_f32 v118, v232, v233
	v_cvt_pk_bf16_f32 v119, v234, v235
	global_store_dwordx4 v[132:133], v[116:119], off offset:192
	v_mul_f32_e32 v228, v135, v228
	v_mul_f32_e32 v229, v135, v229
	v_mul_f32_e32 v230, v135, v230
	v_mul_f32_e32 v231, v135, v231
	v_mul_f32_e32 v236, v135, v236
	v_mul_f32_e32 v237, v135, v237
	v_mul_f32_e32 v238, v135, v238
	v_mul_f32_e32 v239, v135, v239
	v_cvt_pk_bf16_f32 v120, v228, v229
	v_cvt_pk_bf16_f32 v121, v230, v231
	v_cvt_pk_bf16_f32 v122, v236, v237
	v_cvt_pk_bf16_f32 v123, v238, v239
	global_store_dwordx4 v[246:247], v[120:123], off offset:192
	ds_read_b64 v[98:99], v115 offset:384
	ds_read_b64 v[100:101], v115 offset:416
	ds_read_b64 v[102:103], v115 offset:8832
	ds_read_b64 v[104:105], v115 offset:8864
	s_waitcnt lgkmcnt(12)
	v_mfma_f32_16x16x32_bf16 v[66:69], v[106:109], v[14:17], v[66:69]
	v_mfma_f32_16x16x32_bf16 v[70:73], v[106:109], v[46:49], v[70:73]
	v_mfma_f32_16x16x32_bf16 v[74:77], v[110:113], v[14:17], v[74:77]
	v_mfma_f32_16x16x32_bf16 v[78:81], v[110:113], v[46:49], v[78:81]
	ds_read_b64 v[106:107], v115 offset:448
	ds_read_b64 v[108:109], v115 offset:480
	ds_read_b64 v[110:111], v115 offset:8896
	ds_read_b64 v[112:113], v115 offset:8928
	s_waitcnt lgkmcnt(12)
	v_mfma_f32_16x16x32_bf16 v[66:69], v[82:85], v[18:21], v[66:69]
	v_mfma_f32_16x16x32_bf16 v[70:73], v[82:85], v[50:53], v[70:73]
	v_mfma_f32_16x16x32_bf16 v[74:77], v[86:89], v[18:21], v[74:77]
	v_mfma_f32_16x16x32_bf16 v[78:81], v[86:89], v[50:53], v[78:81]
	ds_read_b64 v[82:83], v115 offset:16896
	ds_read_b64 v[84:85], v115 offset:16928
	ds_read_b64 v[86:87], v115 offset:25344
	ds_read_b64 v[88:89], v115 offset:25376
	s_waitcnt lgkmcnt(12)
	v_mfma_f32_16x16x32_bf16 v[66:69], v[90:93], v[22:25], v[66:69]
	v_mfma_f32_16x16x32_bf16 v[70:73], v[90:93], v[54:57], v[70:73]
	v_mfma_f32_16x16x32_bf16 v[74:77], v[94:97], v[22:25], v[74:77]
	v_mfma_f32_16x16x32_bf16 v[78:81], v[94:97], v[54:57], v[78:81]
	ds_read_b64 v[90:91], v115 offset:16960
	ds_read_b64 v[92:93], v115 offset:16992
	ds_read_b64 v[94:95], v115 offset:25408
	ds_read_b64 v[96:97], v115 offset:25440
	s_waitcnt lgkmcnt(12)
	v_mfma_f32_16x16x32_bf16 v[66:69], v[98:101], v[26:29], v[66:69]
	v_mfma_f32_16x16x32_bf16 v[70:73], v[98:101], v[58:61], v[70:73]
	v_mfma_f32_16x16x32_bf16 v[74:77], v[102:105], v[26:29], v[74:77]
	v_mfma_f32_16x16x32_bf16 v[78:81], v[102:105], v[58:61], v[78:81]
	ds_read_b64 v[98:99], v115 offset:17024
	ds_read_b64 v[100:101], v115 offset:17056
	ds_read_b64 v[102:103], v115 offset:25472
	ds_read_b64 v[104:105], v115 offset:25504
	s_waitcnt lgkmcnt(12)
	v_mfma_f32_16x16x32_bf16 v[66:69], v[106:109], v[30:33], v[66:69]
	v_mfma_f32_16x16x32_bf16 v[70:73], v[106:109], v[62:65], v[70:73]
	v_mfma_f32_16x16x32_bf16 v[74:77], v[110:113], v[30:33], v[74:77]
	v_mfma_f32_16x16x32_bf16 v[78:81], v[110:113], v[62:65], v[78:81]
	ds_read_b64 v[106:107], v115 offset:17088
	ds_read_b64 v[108:109], v115 offset:17120
	ds_read_b64 v[110:111], v115 offset:25536
	ds_read_b64 v[112:113], v115 offset:25568
	s_waitcnt lgkmcnt(12)
	v_mfma_f32_16x16x32_bf16 v[224:227], v[82:85], v[2:5], 0
	v_mfma_f32_16x16x32_bf16 v[228:231], v[82:85], v[34:37], 0
	v_mfma_f32_16x16x32_bf16 v[232:235], v[86:89], v[2:5], 0
	v_mfma_f32_16x16x32_bf16 v[236:239], v[86:89], v[34:37], 0
	ds_read_b64 v[82:83], v115 offset:17152
	ds_read_b64 v[84:85], v115 offset:17184
	ds_read_b64 v[86:87], v115 offset:25600
	ds_read_b64 v[88:89], v115 offset:25632
	s_waitcnt lgkmcnt(12)
	v_mfma_f32_16x16x32_bf16 v[224:227], v[90:93], v[6:9], v[224:227]
	v_mfma_f32_16x16x32_bf16 v[228:231], v[90:93], v[38:41], v[228:231]
	v_mfma_f32_16x16x32_bf16 v[232:235], v[94:97], v[6:9], v[232:235]
	v_mfma_f32_16x16x32_bf16 v[236:239], v[94:97], v[38:41], v[236:239]
	ds_read_b64 v[90:91], v115 offset:17216
	ds_read_b64 v[92:93], v115 offset:17248
	ds_read_b64 v[94:95], v115 offset:25664
	ds_read_b64 v[96:97], v115 offset:25696
	s_waitcnt lgkmcnt(12)
	v_mfma_f32_16x16x32_bf16 v[224:227], v[98:101], v[10:13], v[224:227]
	v_mfma_f32_16x16x32_bf16 v[228:231], v[98:101], v[42:45], v[228:231]
	v_mfma_f32_16x16x32_bf16 v[232:235], v[102:105], v[10:13], v[232:235]
	v_mfma_f32_16x16x32_bf16 v[236:239], v[102:105], v[42:45], v[236:239]
	v_mul_f32_e32 v66, v134, v66
	v_mul_f32_e32 v67, v134, v67
	v_mul_f32_e32 v68, v134, v68
	v_mul_f32_e32 v69, v134, v69
	v_mul_f32_e32 v74, v134, v74
	v_mul_f32_e32 v75, v134, v75
	v_mul_f32_e32 v76, v134, v76
	v_mul_f32_e32 v77, v134, v77
	v_cvt_pk_bf16_f32 v116, v66, v67
	v_cvt_pk_bf16_f32 v117, v68, v69
	v_cvt_pk_bf16_f32 v118, v74, v75
	v_cvt_pk_bf16_f32 v119, v76, v77
	global_store_dwordx4 v[132:133], v[116:119], off offset:256
	v_mul_f32_e32 v70, v135, v70
	v_mul_f32_e32 v71, v135, v71
	v_mul_f32_e32 v72, v135, v72
	v_mul_f32_e32 v73, v135, v73
	v_mul_f32_e32 v78, v135, v78
	v_mul_f32_e32 v79, v135, v79
	v_mul_f32_e32 v80, v135, v80
	v_mul_f32_e32 v81, v135, v81
	v_cvt_pk_bf16_f32 v120, v70, v71
	v_cvt_pk_bf16_f32 v121, v72, v73
	v_cvt_pk_bf16_f32 v122, v78, v79
	v_cvt_pk_bf16_f32 v123, v80, v81
	global_store_dwordx4 v[246:247], v[120:123], off offset:256
	ds_read_b64 v[98:99], v115 offset:17280
	ds_read_b64 v[100:101], v115 offset:17312
	ds_read_b64 v[102:103], v115 offset:25728
	ds_read_b64 v[104:105], v115 offset:25760
	s_waitcnt lgkmcnt(12)
	v_mfma_f32_16x16x32_bf16 v[224:227], v[106:109], v[14:17], v[224:227]
	v_mfma_f32_16x16x32_bf16 v[228:231], v[106:109], v[46:49], v[228:231]
	v_mfma_f32_16x16x32_bf16 v[232:235], v[110:113], v[14:17], v[232:235]
	v_mfma_f32_16x16x32_bf16 v[236:239], v[110:113], v[46:49], v[236:239]
	ds_read_b64 v[106:107], v115 offset:17344
	ds_read_b64 v[108:109], v115 offset:17376
	ds_read_b64 v[110:111], v115 offset:25792
	ds_read_b64 v[112:113], v115 offset:25824
	s_waitcnt lgkmcnt(12)
	v_mfma_f32_16x16x32_bf16 v[224:227], v[82:85], v[18:21], v[224:227]
	v_mfma_f32_16x16x32_bf16 v[228:231], v[82:85], v[50:53], v[228:231]
	v_mfma_f32_16x16x32_bf16 v[232:235], v[86:89], v[18:21], v[232:235]
	v_mfma_f32_16x16x32_bf16 v[236:239], v[86:89], v[50:53], v[236:239]
	ds_read_b64 v[82:83], v115 offset:33792
	ds_read_b64 v[84:85], v115 offset:33824
	ds_read_b64 v[86:87], v115 offset:42240
	ds_read_b64 v[88:89], v115 offset:42272
	s_waitcnt lgkmcnt(12)
	v_mfma_f32_16x16x32_bf16 v[224:227], v[90:93], v[22:25], v[224:227]
	v_mfma_f32_16x16x32_bf16 v[228:231], v[90:93], v[54:57], v[228:231]
	v_mfma_f32_16x16x32_bf16 v[232:235], v[94:97], v[22:25], v[232:235]
	v_mfma_f32_16x16x32_bf16 v[236:239], v[94:97], v[54:57], v[236:239]
	ds_read_b64 v[90:91], v115 offset:33856
	ds_read_b64 v[92:93], v115 offset:33888
	ds_read_b64 v[94:95], v115 offset:42304
	ds_read_b64 v[96:97], v115 offset:42336
	s_waitcnt lgkmcnt(12)
	v_mfma_f32_16x16x32_bf16 v[224:227], v[98:101], v[26:29], v[224:227]
	v_mfma_f32_16x16x32_bf16 v[228:231], v[98:101], v[58:61], v[228:231]
	v_mfma_f32_16x16x32_bf16 v[232:235], v[102:105], v[26:29], v[232:235]
	v_mfma_f32_16x16x32_bf16 v[236:239], v[102:105], v[58:61], v[236:239]
	ds_read_b64 v[98:99], v115 offset:33920
	ds_read_b64 v[100:101], v115 offset:33952
	ds_read_b64 v[102:103], v115 offset:42368
	ds_read_b64 v[104:105], v115 offset:42400
	s_waitcnt lgkmcnt(12)
	v_mfma_f32_16x16x32_bf16 v[224:227], v[106:109], v[30:33], v[224:227]
	v_mfma_f32_16x16x32_bf16 v[228:231], v[106:109], v[62:65], v[228:231]
	v_mfma_f32_16x16x32_bf16 v[232:235], v[110:113], v[30:33], v[232:235]
	v_mfma_f32_16x16x32_bf16 v[236:239], v[110:113], v[62:65], v[236:239]
	ds_read_b64 v[106:107], v115 offset:33984
	ds_read_b64 v[108:109], v115 offset:34016
	ds_read_b64 v[110:111], v115 offset:42432
	ds_read_b64 v[112:113], v115 offset:42464
	s_waitcnt lgkmcnt(12)
	v_mfma_f32_16x16x32_bf16 v[66:69], v[82:85], v[2:5], 0
	v_mfma_f32_16x16x32_bf16 v[70:73], v[82:85], v[34:37], 0
	v_mfma_f32_16x16x32_bf16 v[74:77], v[86:89], v[2:5], 0
	v_mfma_f32_16x16x32_bf16 v[78:81], v[86:89], v[34:37], 0
	ds_read_b64 v[82:83], v115 offset:34048
	ds_read_b64 v[84:85], v115 offset:34080
	ds_read_b64 v[86:87], v115 offset:42496
	ds_read_b64 v[88:89], v115 offset:42528
	s_waitcnt lgkmcnt(12)
	v_mfma_f32_16x16x32_bf16 v[66:69], v[90:93], v[6:9], v[66:69]
	v_mfma_f32_16x16x32_bf16 v[70:73], v[90:93], v[38:41], v[70:73]
	v_mfma_f32_16x16x32_bf16 v[74:77], v[94:97], v[6:9], v[74:77]
	v_mfma_f32_16x16x32_bf16 v[78:81], v[94:97], v[38:41], v[78:81]
	ds_read_b64 v[90:91], v115 offset:34112
	ds_read_b64 v[92:93], v115 offset:34144
	ds_read_b64 v[94:95], v115 offset:42560
	ds_read_b64 v[96:97], v115 offset:42592
	s_waitcnt lgkmcnt(12)
	v_mfma_f32_16x16x32_bf16 v[66:69], v[98:101], v[10:13], v[66:69]
	v_mfma_f32_16x16x32_bf16 v[70:73], v[98:101], v[42:45], v[70:73]
	v_mfma_f32_16x16x32_bf16 v[74:77], v[102:105], v[10:13], v[74:77]
	v_mfma_f32_16x16x32_bf16 v[78:81], v[102:105], v[42:45], v[78:81]
	v_mul_f32_e32 v224, v134, v224
	v_mul_f32_e32 v225, v134, v225
	v_mul_f32_e32 v226, v134, v226
	v_mul_f32_e32 v227, v134, v227
	v_mul_f32_e32 v232, v134, v232
	v_mul_f32_e32 v233, v134, v233
	v_mul_f32_e32 v234, v134, v234
	v_mul_f32_e32 v235, v134, v235
	v_cvt_pk_bf16_f32 v116, v224, v225
	v_cvt_pk_bf16_f32 v117, v226, v227
	v_cvt_pk_bf16_f32 v118, v232, v233
	v_cvt_pk_bf16_f32 v119, v234, v235
	global_store_dwordx4 v[132:133], v[116:119], off offset:320
	v_mul_f32_e32 v228, v135, v228
	v_mul_f32_e32 v229, v135, v229
	v_mul_f32_e32 v230, v135, v230
	v_mul_f32_e32 v231, v135, v231
	v_mul_f32_e32 v236, v135, v236
	v_mul_f32_e32 v237, v135, v237
	v_mul_f32_e32 v238, v135, v238
	v_mul_f32_e32 v239, v135, v239
	v_cvt_pk_bf16_f32 v120, v228, v229
	v_cvt_pk_bf16_f32 v121, v230, v231
	v_cvt_pk_bf16_f32 v122, v236, v237
	v_cvt_pk_bf16_f32 v123, v238, v239
	global_store_dwordx4 v[246:247], v[120:123], off offset:320
	ds_read_b64 v[98:99], v115 offset:34176
	ds_read_b64 v[100:101], v115 offset:34208
	ds_read_b64 v[102:103], v115 offset:42624
	ds_read_b64 v[104:105], v115 offset:42656
	s_waitcnt lgkmcnt(12)
	v_mfma_f32_16x16x32_bf16 v[66:69], v[106:109], v[14:17], v[66:69]
	v_mfma_f32_16x16x32_bf16 v[70:73], v[106:109], v[46:49], v[70:73]
	v_mfma_f32_16x16x32_bf16 v[74:77], v[110:113], v[14:17], v[74:77]
	v_mfma_f32_16x16x32_bf16 v[78:81], v[110:113], v[46:49], v[78:81]
	ds_read_b64 v[106:107], v115 offset:34240
	ds_read_b64 v[108:109], v115 offset:34272
	ds_read_b64 v[110:111], v115 offset:42688
	ds_read_b64 v[112:113], v115 offset:42720
	s_waitcnt lgkmcnt(12)
	v_mfma_f32_16x16x32_bf16 v[66:69], v[82:85], v[18:21], v[66:69]
	v_mfma_f32_16x16x32_bf16 v[70:73], v[82:85], v[50:53], v[70:73]
	v_mfma_f32_16x16x32_bf16 v[74:77], v[86:89], v[18:21], v[74:77]
	v_mfma_f32_16x16x32_bf16 v[78:81], v[86:89], v[50:53], v[78:81]
	ds_read_b64 v[82:83], v115 offset:50688
	ds_read_b64 v[84:85], v115 offset:50720
	ds_read_b64 v[86:87], v115 offset:59136
	ds_read_b64 v[88:89], v115 offset:59168
	s_waitcnt lgkmcnt(12)
	v_mfma_f32_16x16x32_bf16 v[66:69], v[90:93], v[22:25], v[66:69]
	v_mfma_f32_16x16x32_bf16 v[70:73], v[90:93], v[54:57], v[70:73]
	v_mfma_f32_16x16x32_bf16 v[74:77], v[94:97], v[22:25], v[74:77]
	v_mfma_f32_16x16x32_bf16 v[78:81], v[94:97], v[54:57], v[78:81]
	ds_read_b64 v[90:91], v115 offset:50752
	ds_read_b64 v[92:93], v115 offset:50784
	ds_read_b64 v[94:95], v115 offset:59200
	ds_read_b64 v[96:97], v115 offset:59232
	s_waitcnt lgkmcnt(12)
	v_mfma_f32_16x16x32_bf16 v[66:69], v[98:101], v[26:29], v[66:69]
	v_mfma_f32_16x16x32_bf16 v[70:73], v[98:101], v[58:61], v[70:73]
	v_mfma_f32_16x16x32_bf16 v[74:77], v[102:105], v[26:29], v[74:77]
	v_mfma_f32_16x16x32_bf16 v[78:81], v[102:105], v[58:61], v[78:81]
	ds_read_b64 v[98:99], v115 offset:50816
	ds_read_b64 v[100:101], v115 offset:50848
	ds_read_b64 v[102:103], v115 offset:59264
	ds_read_b64 v[104:105], v115 offset:59296
	s_waitcnt lgkmcnt(12)
	v_mfma_f32_16x16x32_bf16 v[66:69], v[106:109], v[30:33], v[66:69]
	v_mfma_f32_16x16x32_bf16 v[70:73], v[106:109], v[62:65], v[70:73]
	v_mfma_f32_16x16x32_bf16 v[74:77], v[110:113], v[30:33], v[74:77]
	v_mfma_f32_16x16x32_bf16 v[78:81], v[110:113], v[62:65], v[78:81]
	ds_read_b64 v[106:107], v115 offset:50880
	ds_read_b64 v[108:109], v115 offset:50912
	ds_read_b64 v[110:111], v115 offset:59328
	ds_read_b64 v[112:113], v115 offset:59360
	s_waitcnt lgkmcnt(12)
	v_mfma_f32_16x16x32_bf16 v[224:227], v[82:85], v[2:5], 0
	v_mfma_f32_16x16x32_bf16 v[228:231], v[82:85], v[34:37], 0
	v_mfma_f32_16x16x32_bf16 v[232:235], v[86:89], v[2:5], 0
	v_mfma_f32_16x16x32_bf16 v[236:239], v[86:89], v[34:37], 0
	ds_read_b64 v[82:83], v115 offset:50944
	ds_read_b64 v[84:85], v115 offset:50976
	ds_read_b64 v[86:87], v115 offset:59392
	ds_read_b64 v[88:89], v115 offset:59424
	s_waitcnt lgkmcnt(12)
	v_mfma_f32_16x16x32_bf16 v[224:227], v[90:93], v[6:9], v[224:227]
	v_mfma_f32_16x16x32_bf16 v[228:231], v[90:93], v[38:41], v[228:231]
	v_mfma_f32_16x16x32_bf16 v[232:235], v[94:97], v[6:9], v[232:235]
	v_mfma_f32_16x16x32_bf16 v[236:239], v[94:97], v[38:41], v[236:239]
	ds_read_b64 v[90:91], v115 offset:51008
	ds_read_b64 v[92:93], v115 offset:51040
	ds_read_b64 v[94:95], v115 offset:59456
	ds_read_b64 v[96:97], v115 offset:59488
	s_waitcnt lgkmcnt(12)
	v_mfma_f32_16x16x32_bf16 v[224:227], v[98:101], v[10:13], v[224:227]
	v_mfma_f32_16x16x32_bf16 v[228:231], v[98:101], v[42:45], v[228:231]
	v_mfma_f32_16x16x32_bf16 v[232:235], v[102:105], v[10:13], v[232:235]
	v_mfma_f32_16x16x32_bf16 v[236:239], v[102:105], v[42:45], v[236:239]
	v_mul_f32_e32 v66, v134, v66
	v_mul_f32_e32 v67, v134, v67
	v_mul_f32_e32 v68, v134, v68
	v_mul_f32_e32 v69, v134, v69
	v_mul_f32_e32 v74, v134, v74
	v_mul_f32_e32 v75, v134, v75
	v_mul_f32_e32 v76, v134, v76
	v_mul_f32_e32 v77, v134, v77
	v_cvt_pk_bf16_f32 v116, v66, v67
	v_cvt_pk_bf16_f32 v117, v68, v69
	v_cvt_pk_bf16_f32 v118, v74, v75
	v_cvt_pk_bf16_f32 v119, v76, v77
	global_store_dwordx4 v[132:133], v[116:119], off offset:384
	v_mul_f32_e32 v70, v135, v70
	v_mul_f32_e32 v71, v135, v71
	v_mul_f32_e32 v72, v135, v72
	v_mul_f32_e32 v73, v135, v73
	v_mul_f32_e32 v78, v135, v78
	v_mul_f32_e32 v79, v135, v79
	v_mul_f32_e32 v80, v135, v80
	v_mul_f32_e32 v81, v135, v81
	v_cvt_pk_bf16_f32 v120, v70, v71
	v_cvt_pk_bf16_f32 v121, v72, v73
	v_cvt_pk_bf16_f32 v122, v78, v79
	v_cvt_pk_bf16_f32 v123, v80, v81
	global_store_dwordx4 v[246:247], v[120:123], off offset:384
	ds_read_b64 v[98:99], v115 offset:51072
	ds_read_b64 v[100:101], v115 offset:51104
	ds_read_b64 v[102:103], v115 offset:59520
	ds_read_b64 v[104:105], v115 offset:59552
	s_waitcnt lgkmcnt(12)
	v_mfma_f32_16x16x32_bf16 v[224:227], v[106:109], v[14:17], v[224:227]
	v_mfma_f32_16x16x32_bf16 v[228:231], v[106:109], v[46:49], v[228:231]
	v_mfma_f32_16x16x32_bf16 v[232:235], v[110:113], v[14:17], v[232:235]
	v_mfma_f32_16x16x32_bf16 v[236:239], v[110:113], v[46:49], v[236:239]
	ds_read_b64 v[106:107], v115 offset:51136
	ds_read_b64 v[108:109], v115 offset:51168
	ds_read_b64 v[110:111], v115 offset:59584
	ds_read_b64 v[112:113], v115 offset:59616
	s_waitcnt lgkmcnt(12)
	v_mfma_f32_16x16x32_bf16 v[224:227], v[82:85], v[18:21], v[224:227]
	v_mfma_f32_16x16x32_bf16 v[228:231], v[82:85], v[50:53], v[228:231]
	v_mfma_f32_16x16x32_bf16 v[232:235], v[86:89], v[18:21], v[232:235]
	v_mfma_f32_16x16x32_bf16 v[236:239], v[86:89], v[50:53], v[236:239]
	s_waitcnt lgkmcnt(8)
	v_mfma_f32_16x16x32_bf16 v[224:227], v[90:93], v[22:25], v[224:227]
	v_mfma_f32_16x16x32_bf16 v[228:231], v[90:93], v[54:57], v[228:231]
	v_mfma_f32_16x16x32_bf16 v[232:235], v[94:97], v[22:25], v[232:235]
	v_mfma_f32_16x16x32_bf16 v[236:239], v[94:97], v[54:57], v[236:239]
	s_waitcnt lgkmcnt(4)
	v_mfma_f32_16x16x32_bf16 v[224:227], v[98:101], v[26:29], v[224:227]
	v_mfma_f32_16x16x32_bf16 v[228:231], v[98:101], v[58:61], v[228:231]
	v_mfma_f32_16x16x32_bf16 v[232:235], v[102:105], v[26:29], v[232:235]
	v_mfma_f32_16x16x32_bf16 v[236:239], v[102:105], v[58:61], v[236:239]
	s_waitcnt lgkmcnt(0)
	v_mfma_f32_16x16x32_bf16 v[224:227], v[106:109], v[30:33], v[224:227]
	v_mfma_f32_16x16x32_bf16 v[228:231], v[106:109], v[62:65], v[228:231]
	v_mfma_f32_16x16x32_bf16 v[232:235], v[110:113], v[30:33], v[232:235]
	v_mfma_f32_16x16x32_bf16 v[236:239], v[110:113], v[62:65], v[236:239]
	s_nop 7
	s_nop 1
	v_mul_f32_e32 v224, v134, v224
	v_mul_f32_e32 v225, v134, v225
	v_mul_f32_e32 v226, v134, v226
	v_mul_f32_e32 v227, v134, v227
	v_mul_f32_e32 v232, v134, v232
	v_mul_f32_e32 v233, v134, v233
	v_mul_f32_e32 v234, v134, v234
	v_mul_f32_e32 v235, v134, v235
	v_cvt_pk_bf16_f32 v116, v224, v225
	v_cvt_pk_bf16_f32 v117, v226, v227
	v_cvt_pk_bf16_f32 v118, v232, v233
	v_cvt_pk_bf16_f32 v119, v234, v235
	global_store_dwordx4 v[132:133], v[116:119], off offset:448
	v_mul_f32_e32 v228, v135, v228
	v_mul_f32_e32 v229, v135, v229
	v_mul_f32_e32 v230, v135, v230
	v_mul_f32_e32 v231, v135, v231
	v_mul_f32_e32 v236, v135, v236
	v_mul_f32_e32 v237, v135, v237
	v_mul_f32_e32 v238, v135, v238
	v_mul_f32_e32 v239, v135, v239
	v_cvt_pk_bf16_f32 v120, v228, v229
	v_cvt_pk_bf16_f32 v121, v230, v231
	v_cvt_pk_bf16_f32 v122, v236, v237
	v_cvt_pk_bf16_f32 v123, v238, v239
	global_store_dwordx4 v[246:247], v[120:123], off offset:448
	s_branch .LBB0_158

.LBB0_207:
	s_add_u32 s0, s50, 0x210080
	s_addc_u32 s1, s51, 0
	s_mov_b32 m0, s72
	s_nop 0
	global_load_lds_dwordx4 v0, s[0:1]
	s_cmp_lg_u32 s78, 2
	s_mov_b32 m0, s74
	s_nop 0
	global_load_lds_dwordx4 v149, s[0:1]
	v_lshl_or_b32 v246, s4, 8, v152
	v_lshl_add_u32 v248, s79, 8, v151
	v_ashrrev_i32_e32 v247, 31, v246
	v_ashrrev_i32_e32 v249, 31, v248
	s_cmp_lg_u32 s78, 2
	s_cselect_b64 s[0:1], -1, 0
	s_cmp_lg_u32 s4, 3
	s_cselect_b64 s[4:5], -1, 0
	s_or_b64 s[0:1], s[0:1], s[4:5]
	s_and_b64 vcc, exec, s[0:1]
	s_cbranch_vccz .Leg_gl2
	v_mov_b64_e32 v[144:145], s[28:29]
	v_mad_i64_i32 v[144:145], s[4:5], v248, s83, v[144:145]
	s_lshl_b32 s4, s78, 10
	s_ashr_i32 s5, s4, 31
	v_lshl_add_u64 v[144:145], s[4:5], 1, v[144:145]
	v_lshl_add_u64 v[138:139], v[246:247], 1, v[144:145]
	s_mov_b64 s[0:1], 0x42000
	s_mov_b64 s[4:5], 0x14a000
	s_branch .Leg_cont
.Leg_gl2:
	v_lshlrev_b64 v[144:145], 9, v[248:249]
	v_lshl_add_u64 v[144:145], s[42:43], 0, v[144:145]
	v_lshl_add_u64 v[144:145], v[246:247], 1, v[144:145]
	s_movk_i32 s8, 0xfa00
	s_mov_b32 s9, -1
	v_lshl_add_u64 v[138:139], v[144:145], 0, s[8:9]
	s_mov_b64 s[0:1], 0x2000
	s_mov_b64 s[4:5], 0xa000
.Leg_cont:
	v_lshlrev_b64 v[144:145], 11, v[248:249]
	v_lshl_add_u64 v[144:145], s[22:23], 0, v[144:145]
	v_lshl_add_u64 v[140:141], v[246:247], 1, v[144:145]
	v_mov_b64_e32 v[142:143], v[140:141]
	s_mov_b64 s[34:35], 0x8000
	s_mov_b64 s[38:39], 0x28000
	s_cmp_gt_i32 s78, 0
	s_cselect_b64 s[6:7], -1, 0
	global_load_dwordx4 v[210:213], v[138:139], off
	global_load_dwordx4 v[214:217], v[140:141], off
	global_load_dwordx4 v[218:221], v[138:139], off offset:256
	global_load_dwordx4 v[222:225], v[140:141], off offset:256
	v_lshl_add_u64 v[138:139], v[138:139], 0, s[0:1]
	v_lshl_add_u64 v[140:141], v[140:141], 0, s[34:35]
	global_load_dwordx4 v[226:229], v[138:139], off
	global_load_dwordx4 v[230:233], v[140:141], off
	global_load_dwordx4 v[234:237], v[138:139], off offset:256
	global_load_dwordx4 v[238:241], v[140:141], off offset:256
	v_lshl_add_u64 v[138:139], v[138:139], 0, s[0:1]
	v_lshl_add_u64 v[140:141], v[140:141], 0, s[34:35]
	global_load_dwordx4 v[182:185], v[138:139], off
	global_load_dwordx4 v[186:189], v[140:141], off
	global_load_dwordx4 v[190:193], v[138:139], off offset:256
	global_load_dwordx4 v[242:245], v[140:141], off offset:256
	v_lshl_add_u64 v[138:139], v[138:139], 0, s[0:1]
	v_lshl_add_u64 v[140:141], v[140:141], 0, s[34:35]
	s_waitcnt vmcnt(8)
	v_cndmask_b32_e64 v214, 0, v214, s[6:7]
	v_cndmask_b32_e64 v215, 0, v215, s[6:7]
	v_cndmask_b32_e64 v216, 0, v216, s[6:7]
	v_cndmask_b32_e64 v217, 0, v217, s[6:7]
	v_lshlrev_b32_e32 v130, 16, v210
	v_and_b32_e32 v131, 0xffff0000, v210
	v_lshlrev_b32_e32 v132, 16, v211
	v_and_b32_e32 v133, 0xffff0000, v211
	v_mul_f32_e32 v130, 0xbfb8aa3b, v130
	v_mul_f32_e32 v131, 0xbfb8aa3b, v131
	v_mul_f32_e32 v132, 0xbfb8aa3b, v132
	v_mul_f32_e32 v133, 0xbfb8aa3b, v133
	v_exp_f32_e32 v130, v130
	v_exp_f32_e32 v131, v131
	v_exp_f32_e32 v132, v132
	v_exp_f32_e32 v133, v133
	v_lshlrev_b32_e32 v134, 16, v214
	v_and_b32_e32 v135, 0xffff0000, v214
	v_lshlrev_b32_e32 v136, 16, v215
	v_and_b32_e32 v137, 0xffff0000, v215
	v_add_f32_e32 v130, 1.0, v130
	v_add_f32_e32 v131, 1.0, v131
	v_add_f32_e32 v132, 1.0, v132
	v_add_f32_e32 v133, 1.0, v133
	v_rcp_f32_e32 v130, v130
	v_rcp_f32_e32 v131, v131
	v_rcp_f32_e32 v132, v132
	v_rcp_f32_e32 v133, v133
	s_nop 0
	v_fmac_f32_e32 v134, v126, v130
	v_fmac_f32_e32 v135, v127, v131
	v_fmac_f32_e32 v136, v128, v132
	v_fmac_f32_e32 v137, v129, v133
	v_cvt_pk_bf16_f32 v126, v134, v135
	v_cvt_pk_bf16_f32 v127, v136, v137
	v_lshlrev_b32_e32 v130, 16, v212
	v_and_b32_e32 v131, 0xffff0000, v212
	v_lshlrev_b32_e32 v132, 16, v213
	v_and_b32_e32 v133, 0xffff0000, v213
	v_mul_f32_e32 v130, 0xbfb8aa3b, v130
	v_mul_f32_e32 v131, 0xbfb8aa3b, v131
	v_mul_f32_e32 v132, 0xbfb8aa3b, v132
	v_mul_f32_e32 v133, 0xbfb8aa3b, v133
	v_exp_f32_e32 v130, v130
	v_exp_f32_e32 v131, v131
	v_exp_f32_e32 v132, v132
	v_exp_f32_e32 v133, v133
	v_lshlrev_b32_e32 v134, 16, v216
	v_and_b32_e32 v135, 0xffff0000, v216
	v_lshlrev_b32_e32 v136, 16, v217
	v_and_b32_e32 v137, 0xffff0000, v217
	v_add_f32_e32 v130, 1.0, v130
	v_add_f32_e32 v131, 1.0, v131
	v_add_f32_e32 v132, 1.0, v132
	v_add_f32_e32 v133, 1.0, v133
	v_rcp_f32_e32 v130, v130
	v_rcp_f32_e32 v131, v131
	v_rcp_f32_e32 v132, v132
	v_rcp_f32_e32 v133, v133
	s_nop 0
	v_fmac_f32_e32 v134, v122, v130
	v_fmac_f32_e32 v135, v123, v131
	v_fmac_f32_e32 v136, v124, v132
	v_fmac_f32_e32 v137, v125, v133
	v_cvt_pk_bf16_f32 v128, v134, v135
	v_cvt_pk_bf16_f32 v129, v136, v137
	v_cndmask_b32_e64 v222, 0, v222, s[6:7]
	v_cndmask_b32_e64 v223, 0, v223, s[6:7]
	v_cndmask_b32_e64 v224, 0, v224, s[6:7]
	v_cndmask_b32_e64 v225, 0, v225, s[6:7]
	v_lshlrev_b32_e32 v130, 16, v218
	v_and_b32_e32 v131, 0xffff0000, v218
	v_lshlrev_b32_e32 v132, 16, v219
	v_and_b32_e32 v133, 0xffff0000, v219
	v_mul_f32_e32 v130, 0xbfb8aa3b, v130
	v_mul_f32_e32 v131, 0xbfb8aa3b, v131
	v_mul_f32_e32 v132, 0xbfb8aa3b, v132
	v_mul_f32_e32 v133, 0xbfb8aa3b, v133
	v_exp_f32_e32 v130, v130
	v_exp_f32_e32 v131, v131
	v_exp_f32_e32 v132, v132
	v_exp_f32_e32 v133, v133
	v_lshlrev_b32_e32 v134, 16, v222
	v_and_b32_e32 v135, 0xffff0000, v222
	v_lshlrev_b32_e32 v136, 16, v223
	v_and_b32_e32 v137, 0xffff0000, v223
	v_add_f32_e32 v130, 1.0, v130
	v_add_f32_e32 v131, 1.0, v131
	v_add_f32_e32 v132, 1.0, v132
	v_add_f32_e32 v133, 1.0, v133
	v_rcp_f32_e32 v130, v130
	v_rcp_f32_e32 v131, v131
	v_rcp_f32_e32 v132, v132
	v_rcp_f32_e32 v133, v133
	s_nop 0
	v_fmac_f32_e32 v134, v118, v130
	v_fmac_f32_e32 v135, v119, v131
	v_fmac_f32_e32 v136, v120, v132
	v_fmac_f32_e32 v137, v121, v133
	v_cvt_pk_bf16_f32 v118, v134, v135
	v_cvt_pk_bf16_f32 v119, v136, v137
	v_lshlrev_b32_e32 v130, 16, v220
	v_and_b32_e32 v131, 0xffff0000, v220
	v_lshlrev_b32_e32 v132, 16, v221
	v_and_b32_e32 v133, 0xffff0000, v221
	v_mul_f32_e32 v130, 0xbfb8aa3b, v130
	v_mul_f32_e32 v131, 0xbfb8aa3b, v131
	v_mul_f32_e32 v132, 0xbfb8aa3b, v132
	v_mul_f32_e32 v133, 0xbfb8aa3b, v133
	v_exp_f32_e32 v130, v130
	v_exp_f32_e32 v131, v131
	v_exp_f32_e32 v132, v132
	v_exp_f32_e32 v133, v133
	v_lshlrev_b32_e32 v134, 16, v224
	v_and_b32_e32 v135, 0xffff0000, v224
	v_lshlrev_b32_e32 v136, 16, v225
	v_and_b32_e32 v137, 0xffff0000, v225
	v_add_f32_e32 v130, 1.0, v130
	v_add_f32_e32 v131, 1.0, v131
	v_add_f32_e32 v132, 1.0, v132
	v_add_f32_e32 v133, 1.0, v133
	v_rcp_f32_e32 v130, v130
	v_rcp_f32_e32 v131, v131
	v_rcp_f32_e32 v132, v132
	v_rcp_f32_e32 v133, v133
	s_nop 0
	v_fmac_f32_e32 v134, v114, v130
	v_fmac_f32_e32 v135, v115, v131
	v_fmac_f32_e32 v136, v116, v132
	v_fmac_f32_e32 v137, v117, v133
	v_cvt_pk_bf16_f32 v120, v134, v135
	v_cvt_pk_bf16_f32 v121, v136, v137
	global_load_dwordx4 v[210:213], v[138:139], off
	global_load_dwordx4 v[214:217], v[140:141], off
	global_load_dwordx4 v[218:221], v[138:139], off offset:256
	global_load_dwordx4 v[222:225], v[140:141], off offset:256
	v_lshl_add_u64 v[138:139], v[138:139], 0, s[4:5]
	v_lshl_add_u64 v[140:141], v[140:141], 0, s[38:39]
	global_store_dwordx4 v[142:143], v[126:129], off
	global_store_dwordx4 v[142:143], v[118:121], off offset:256
	v_lshl_add_u64 v[142:143], v[142:143], 0, s[34:35]
	s_waitcnt vmcnt(10)
	v_cndmask_b32_e64 v230, 0, v230, s[6:7]
	v_cndmask_b32_e64 v231, 0, v231, s[6:7]
	v_cndmask_b32_e64 v232, 0, v232, s[6:7]
	v_cndmask_b32_e64 v233, 0, v233, s[6:7]
	v_lshlrev_b32_e32 v130, 16, v226
	v_and_b32_e32 v131, 0xffff0000, v226
	v_lshlrev_b32_e32 v132, 16, v227
	v_and_b32_e32 v133, 0xffff0000, v227
	v_mul_f32_e32 v130, 0xbfb8aa3b, v130
	v_mul_f32_e32 v131, 0xbfb8aa3b, v131
	v_mul_f32_e32 v132, 0xbfb8aa3b, v132
	v_mul_f32_e32 v133, 0xbfb8aa3b, v133
	v_exp_f32_e32 v130, v130
	v_exp_f32_e32 v131, v131
	v_exp_f32_e32 v132, v132
	v_exp_f32_e32 v133, v133
	v_lshlrev_b32_e32 v134, 16, v230
	v_and_b32_e32 v135, 0xffff0000, v230
	v_lshlrev_b32_e32 v136, 16, v231
	v_and_b32_e32 v137, 0xffff0000, v231
	v_add_f32_e32 v130, 1.0, v130
	v_add_f32_e32 v131, 1.0, v131
	v_add_f32_e32 v132, 1.0, v132
	v_add_f32_e32 v133, 1.0, v133
	v_rcp_f32_e32 v130, v130
	v_rcp_f32_e32 v131, v131
	v_rcp_f32_e32 v132, v132
	v_rcp_f32_e32 v133, v133
	s_nop 0
	v_fmac_f32_e32 v134, v110, v130
	v_fmac_f32_e32 v135, v111, v131
	v_fmac_f32_e32 v136, v112, v132
	v_fmac_f32_e32 v137, v113, v133
	v_cvt_pk_bf16_f32 v110, v134, v135
	v_cvt_pk_bf16_f32 v111, v136, v137
	v_lshlrev_b32_e32 v130, 16, v228
	v_and_b32_e32 v131, 0xffff0000, v228
	v_lshlrev_b32_e32 v132, 16, v229
	v_and_b32_e32 v133, 0xffff0000, v229
	v_mul_f32_e32 v130, 0xbfb8aa3b, v130
	v_mul_f32_e32 v131, 0xbfb8aa3b, v131
	v_mul_f32_e32 v132, 0xbfb8aa3b, v132
	v_mul_f32_e32 v133, 0xbfb8aa3b, v133
	v_exp_f32_e32 v130, v130
	v_exp_f32_e32 v131, v131
	v_exp_f32_e32 v132, v132
	v_exp_f32_e32 v133, v133
	v_lshlrev_b32_e32 v134, 16, v232
	v_and_b32_e32 v135, 0xffff0000, v232
	v_lshlrev_b32_e32 v136, 16, v233
	v_and_b32_e32 v137, 0xffff0000, v233
	v_add_f32_e32 v130, 1.0, v130
	v_add_f32_e32 v131, 1.0, v131
	v_add_f32_e32 v132, 1.0, v132
	v_add_f32_e32 v133, 1.0, v133
	v_rcp_f32_e32 v130, v130
	v_rcp_f32_e32 v131, v131
	v_rcp_f32_e32 v132, v132
	v_rcp_f32_e32 v133, v133
	s_nop 0
	v_fmac_f32_e32 v134, v106, v130
	v_fmac_f32_e32 v135, v107, v131
	v_fmac_f32_e32 v136, v108, v132
	v_fmac_f32_e32 v137, v109, v133
	v_cvt_pk_bf16_f32 v112, v134, v135
	v_cvt_pk_bf16_f32 v113, v136, v137
	v_cndmask_b32_e64 v238, 0, v238, s[6:7]
	v_cndmask_b32_e64 v239, 0, v239, s[6:7]
	v_cndmask_b32_e64 v240, 0, v240, s[6:7]
	v_cndmask_b32_e64 v241, 0, v241, s[6:7]
	v_lshlrev_b32_e32 v130, 16, v234
	v_and_b32_e32 v131, 0xffff0000, v234
	v_lshlrev_b32_e32 v132, 16, v235
	v_and_b32_e32 v133, 0xffff0000, v235
	v_mul_f32_e32 v130, 0xbfb8aa3b, v130
	v_mul_f32_e32 v131, 0xbfb8aa3b, v131
	v_mul_f32_e32 v132, 0xbfb8aa3b, v132
	v_mul_f32_e32 v133, 0xbfb8aa3b, v133
	v_exp_f32_e32 v130, v130
	v_exp_f32_e32 v131, v131
	v_exp_f32_e32 v132, v132
	v_exp_f32_e32 v133, v133
	v_lshlrev_b32_e32 v134, 16, v238
	v_and_b32_e32 v135, 0xffff0000, v238
	v_lshlrev_b32_e32 v136, 16, v239
	v_and_b32_e32 v137, 0xffff0000, v239
	v_add_f32_e32 v130, 1.0, v130
	v_add_f32_e32 v131, 1.0, v131
	v_add_f32_e32 v132, 1.0, v132
	v_add_f32_e32 v133, 1.0, v133
	v_rcp_f32_e32 v130, v130
	v_rcp_f32_e32 v131, v131
	v_rcp_f32_e32 v132, v132
	v_rcp_f32_e32 v133, v133
	s_nop 0
	v_fmac_f32_e32 v134, v102, v130
	v_fmac_f32_e32 v135, v103, v131
	v_fmac_f32_e32 v136, v104, v132
	v_fmac_f32_e32 v137, v105, v133
	v_cvt_pk_bf16_f32 v102, v134, v135
	v_cvt_pk_bf16_f32 v103, v136, v137
	v_lshlrev_b32_e32 v130, 16, v236
	v_and_b32_e32 v131, 0xffff0000, v236
	v_lshlrev_b32_e32 v132, 16, v237
	v_and_b32_e32 v133, 0xffff0000, v237
	v_mul_f32_e32 v130, 0xbfb8aa3b, v130
	v_mul_f32_e32 v131, 0xbfb8aa3b, v131
	v_mul_f32_e32 v132, 0xbfb8aa3b, v132
	v_mul_f32_e32 v133, 0xbfb8aa3b, v133
	v_exp_f32_e32 v130, v130
	v_exp_f32_e32 v131, v131
	v_exp_f32_e32 v132, v132
	v_exp_f32_e32 v133, v133
	v_lshlrev_b32_e32 v134, 16, v240
	v_and_b32_e32 v135, 0xffff0000, v240
	v_lshlrev_b32_e32 v136, 16, v241
	v_and_b32_e32 v137, 0xffff0000, v241
	v_add_f32_e32 v130, 1.0, v130
	v_add_f32_e32 v131, 1.0, v131
	v_add_f32_e32 v132, 1.0, v132
	v_add_f32_e32 v133, 1.0, v133
	v_rcp_f32_e32 v130, v130
	v_rcp_f32_e32 v131, v131
	v_rcp_f32_e32 v132, v132
	v_rcp_f32_e32 v133, v133
	s_nop 0
	v_fmac_f32_e32 v134, v98, v130
	v_fmac_f32_e32 v135, v99, v131
	v_fmac_f32_e32 v136, v100, v132
	v_fmac_f32_e32 v137, v101, v133
	v_cvt_pk_bf16_f32 v104, v134, v135
	v_cvt_pk_bf16_f32 v105, v136, v137
	global_load_dwordx4 v[226:229], v[138:139], off
	global_load_dwordx4 v[230:233], v[140:141], off
	global_load_dwordx4 v[234:237], v[138:139], off offset:256
	global_load_dwordx4 v[238:241], v[140:141], off offset:256
	v_lshl_add_u64 v[138:139], v[138:139], 0, s[0:1]
	v_lshl_add_u64 v[140:141], v[140:141], 0, s[34:35]
	global_store_dwordx4 v[142:143], v[110:113], off
	global_store_dwordx4 v[142:143], v[102:105], off offset:256
	v_lshl_add_u64 v[142:143], v[142:143], 0, s[34:35]
	s_waitcnt vmcnt(12)
	v_cndmask_b32_e64 v186, 0, v186, s[6:7]
	v_cndmask_b32_e64 v187, 0, v187, s[6:7]
	v_cndmask_b32_e64 v188, 0, v188, s[6:7]
	v_cndmask_b32_e64 v189, 0, v189, s[6:7]
	v_lshlrev_b32_e32 v130, 16, v182
	v_and_b32_e32 v131, 0xffff0000, v182
	v_lshlrev_b32_e32 v132, 16, v183
	v_and_b32_e32 v133, 0xffff0000, v183
	v_mul_f32_e32 v130, 0xbfb8aa3b, v130
	v_mul_f32_e32 v131, 0xbfb8aa3b, v131
	v_mul_f32_e32 v132, 0xbfb8aa3b, v132
	v_mul_f32_e32 v133, 0xbfb8aa3b, v133
	v_exp_f32_e32 v130, v130
	v_exp_f32_e32 v131, v131
	v_exp_f32_e32 v132, v132
	v_exp_f32_e32 v133, v133
	v_lshlrev_b32_e32 v134, 16, v186
	v_and_b32_e32 v135, 0xffff0000, v186
	v_lshlrev_b32_e32 v136, 16, v187
	v_and_b32_e32 v137, 0xffff0000, v187
	v_add_f32_e32 v130, 1.0, v130
	v_add_f32_e32 v131, 1.0, v131
	v_add_f32_e32 v132, 1.0, v132
	v_add_f32_e32 v133, 1.0, v133
	v_rcp_f32_e32 v130, v130
	v_rcp_f32_e32 v131, v131
	v_rcp_f32_e32 v132, v132
	v_rcp_f32_e32 v133, v133
	s_nop 0
	v_fmac_f32_e32 v134, v94, v130
	v_fmac_f32_e32 v135, v95, v131
	v_fmac_f32_e32 v136, v96, v132
	v_fmac_f32_e32 v137, v97, v133
	v_cvt_pk_bf16_f32 v94, v134, v135
	v_cvt_pk_bf16_f32 v95, v136, v137
	v_lshlrev_b32_e32 v130, 16, v184
	v_and_b32_e32 v131, 0xffff0000, v184
	v_lshlrev_b32_e32 v132, 16, v185
	v_and_b32_e32 v133, 0xffff0000, v185
	v_mul_f32_e32 v130, 0xbfb8aa3b, v130
	v_mul_f32_e32 v131, 0xbfb8aa3b, v131
	v_mul_f32_e32 v132, 0xbfb8aa3b, v132
	v_mul_f32_e32 v133, 0xbfb8aa3b, v133
	v_exp_f32_e32 v130, v130
	v_exp_f32_e32 v131, v131
	v_exp_f32_e32 v132, v132
	v_exp_f32_e32 v133, v133
	v_lshlrev_b32_e32 v134, 16, v188
	v_and_b32_e32 v135, 0xffff0000, v188
	v_lshlrev_b32_e32 v136, 16, v189
	v_and_b32_e32 v137, 0xffff0000, v189
	v_add_f32_e32 v130, 1.0, v130
	v_add_f32_e32 v131, 1.0, v131
	v_add_f32_e32 v132, 1.0, v132
	v_add_f32_e32 v133, 1.0, v133
	v_rcp_f32_e32 v130, v130
	v_rcp_f32_e32 v131, v131
	v_rcp_f32_e32 v132, v132
	v_rcp_f32_e32 v133, v133
	s_nop 0
	v_fmac_f32_e32 v134, v90, v130
	v_fmac_f32_e32 v135, v91, v131
	v_fmac_f32_e32 v136, v92, v132
	v_fmac_f32_e32 v137, v93, v133
	v_cvt_pk_bf16_f32 v96, v134, v135
	v_cvt_pk_bf16_f32 v97, v136, v137
	v_cndmask_b32_e64 v242, 0, v242, s[6:7]
	v_cndmask_b32_e64 v243, 0, v243, s[6:7]
	v_cndmask_b32_e64 v244, 0, v244, s[6:7]
	v_cndmask_b32_e64 v245, 0, v245, s[6:7]
	v_lshlrev_b32_e32 v130, 16, v190
	v_and_b32_e32 v131, 0xffff0000, v190
	v_lshlrev_b32_e32 v132, 16, v191
	v_and_b32_e32 v133, 0xffff0000, v191
	v_mul_f32_e32 v130, 0xbfb8aa3b, v130
	v_mul_f32_e32 v131, 0xbfb8aa3b, v131
	v_mul_f32_e32 v132, 0xbfb8aa3b, v132
	v_mul_f32_e32 v133, 0xbfb8aa3b, v133
	v_exp_f32_e32 v130, v130
	v_exp_f32_e32 v131, v131
	v_exp_f32_e32 v132, v132
	v_exp_f32_e32 v133, v133
	v_lshlrev_b32_e32 v134, 16, v242
	v_and_b32_e32 v135, 0xffff0000, v242
	v_lshlrev_b32_e32 v136, 16, v243
	v_and_b32_e32 v137, 0xffff0000, v243
	v_add_f32_e32 v130, 1.0, v130
	v_add_f32_e32 v131, 1.0, v131
	v_add_f32_e32 v132, 1.0, v132
	v_add_f32_e32 v133, 1.0, v133
	v_rcp_f32_e32 v130, v130
	v_rcp_f32_e32 v131, v131
	v_rcp_f32_e32 v132, v132
	v_rcp_f32_e32 v133, v133
	s_nop 0
	v_fmac_f32_e32 v134, v86, v130
	v_fmac_f32_e32 v135, v87, v131
	v_fmac_f32_e32 v136, v88, v132
	v_fmac_f32_e32 v137, v89, v133
	v_cvt_pk_bf16_f32 v86, v134, v135
	v_cvt_pk_bf16_f32 v87, v136, v137
	v_lshlrev_b32_e32 v130, 16, v192
	v_and_b32_e32 v131, 0xffff0000, v192
	v_lshlrev_b32_e32 v132, 16, v193
	v_and_b32_e32 v133, 0xffff0000, v193
	v_mul_f32_e32 v130, 0xbfb8aa3b, v130
	v_mul_f32_e32 v131, 0xbfb8aa3b, v131
	v_mul_f32_e32 v132, 0xbfb8aa3b, v132
	v_mul_f32_e32 v133, 0xbfb8aa3b, v133
	v_exp_f32_e32 v130, v130
	v_exp_f32_e32 v131, v131
	v_exp_f32_e32 v132, v132
	v_exp_f32_e32 v133, v133
	v_lshlrev_b32_e32 v134, 16, v244
	v_and_b32_e32 v135, 0xffff0000, v244
	v_lshlrev_b32_e32 v136, 16, v245
	v_and_b32_e32 v137, 0xffff0000, v245
	v_add_f32_e32 v130, 1.0, v130
	v_add_f32_e32 v131, 1.0, v131
	v_add_f32_e32 v132, 1.0, v132
	v_add_f32_e32 v133, 1.0, v133
	v_rcp_f32_e32 v130, v130
	v_rcp_f32_e32 v131, v131
	v_rcp_f32_e32 v132, v132
	v_rcp_f32_e32 v133, v133
	s_nop 0
	v_fmac_f32_e32 v134, v82, v130
	v_fmac_f32_e32 v135, v83, v131
	v_fmac_f32_e32 v136, v84, v132
	v_fmac_f32_e32 v137, v85, v133
	v_cvt_pk_bf16_f32 v88, v134, v135
	v_cvt_pk_bf16_f32 v89, v136, v137
	global_load_dwordx4 v[182:185], v[138:139], off
	global_load_dwordx4 v[186:189], v[140:141], off
	global_load_dwordx4 v[190:193], v[138:139], off offset:256
	global_load_dwordx4 v[242:245], v[140:141], off offset:256
	v_lshl_add_u64 v[138:139], v[138:139], 0, s[0:1]
	v_lshl_add_u64 v[140:141], v[140:141], 0, s[34:35]
	global_store_dwordx4 v[142:143], v[94:97], off
	global_store_dwordx4 v[142:143], v[86:89], off offset:256
	v_lshl_add_u64 v[142:143], v[142:143], 0, s[34:35]
	s_waitcnt vmcnt(14)
	v_cndmask_b32_e64 v214, 0, v214, s[6:7]
	v_cndmask_b32_e64 v215, 0, v215, s[6:7]
	v_cndmask_b32_e64 v216, 0, v216, s[6:7]
	v_cndmask_b32_e64 v217, 0, v217, s[6:7]
	v_lshlrev_b32_e32 v130, 16, v210
	v_and_b32_e32 v131, 0xffff0000, v210
	v_lshlrev_b32_e32 v132, 16, v211
	v_and_b32_e32 v133, 0xffff0000, v211
	v_mul_f32_e32 v130, 0xbfb8aa3b, v130
	v_mul_f32_e32 v131, 0xbfb8aa3b, v131
	v_mul_f32_e32 v132, 0xbfb8aa3b, v132
	v_mul_f32_e32 v133, 0xbfb8aa3b, v133
	v_exp_f32_e32 v130, v130
	v_exp_f32_e32 v131, v131
	v_exp_f32_e32 v132, v132
	v_exp_f32_e32 v133, v133
	v_lshlrev_b32_e32 v134, 16, v214
	v_and_b32_e32 v135, 0xffff0000, v214
	v_lshlrev_b32_e32 v136, 16, v215
	v_and_b32_e32 v137, 0xffff0000, v215
	v_add_f32_e32 v130, 1.0, v130
	v_add_f32_e32 v131, 1.0, v131
	v_add_f32_e32 v132, 1.0, v132
	v_add_f32_e32 v133, 1.0, v133
	v_rcp_f32_e32 v130, v130
	v_rcp_f32_e32 v131, v131
	v_rcp_f32_e32 v132, v132
	v_rcp_f32_e32 v133, v133
	s_nop 0
	v_fmac_f32_e32 v134, v78, v130
	v_fmac_f32_e32 v135, v79, v131
	v_fmac_f32_e32 v136, v80, v132
	v_fmac_f32_e32 v137, v81, v133
	v_cvt_pk_bf16_f32 v78, v134, v135
	v_cvt_pk_bf16_f32 v79, v136, v137
	v_lshlrev_b32_e32 v130, 16, v212
	v_and_b32_e32 v131, 0xffff0000, v212
	v_lshlrev_b32_e32 v132, 16, v213
	v_and_b32_e32 v133, 0xffff0000, v213
	v_mul_f32_e32 v130, 0xbfb8aa3b, v130
	v_mul_f32_e32 v131, 0xbfb8aa3b, v131
	v_mul_f32_e32 v132, 0xbfb8aa3b, v132
	v_mul_f32_e32 v133, 0xbfb8aa3b, v133
	v_exp_f32_e32 v130, v130
	v_exp_f32_e32 v131, v131
	v_exp_f32_e32 v132, v132
	v_exp_f32_e32 v133, v133
	v_lshlrev_b32_e32 v134, 16, v216
	v_and_b32_e32 v135, 0xffff0000, v216
	v_lshlrev_b32_e32 v136, 16, v217
	v_and_b32_e32 v137, 0xffff0000, v217
	v_add_f32_e32 v130, 1.0, v130
	v_add_f32_e32 v131, 1.0, v131
	v_add_f32_e32 v132, 1.0, v132
	v_add_f32_e32 v133, 1.0, v133
	v_rcp_f32_e32 v130, v130
	v_rcp_f32_e32 v131, v131
	v_rcp_f32_e32 v132, v132
	v_rcp_f32_e32 v133, v133
	s_nop 0
	v_fmac_f32_e32 v134, v74, v130
	v_fmac_f32_e32 v135, v75, v131
	v_fmac_f32_e32 v136, v76, v132
	v_fmac_f32_e32 v137, v77, v133
	v_cvt_pk_bf16_f32 v80, v134, v135
	v_cvt_pk_bf16_f32 v81, v136, v137
	v_cndmask_b32_e64 v222, 0, v222, s[6:7]
	v_cndmask_b32_e64 v223, 0, v223, s[6:7]
	v_cndmask_b32_e64 v224, 0, v224, s[6:7]
	v_cndmask_b32_e64 v225, 0, v225, s[6:7]
	v_lshlrev_b32_e32 v130, 16, v218
	v_and_b32_e32 v131, 0xffff0000, v218
	v_lshlrev_b32_e32 v132, 16, v219
	v_and_b32_e32 v133, 0xffff0000, v219
	v_mul_f32_e32 v130, 0xbfb8aa3b, v130
	v_mul_f32_e32 v131, 0xbfb8aa3b, v131
	v_mul_f32_e32 v132, 0xbfb8aa3b, v132
	v_mul_f32_e32 v133, 0xbfb8aa3b, v133
	v_exp_f32_e32 v130, v130
	v_exp_f32_e32 v131, v131
	v_exp_f32_e32 v132, v132
	v_exp_f32_e32 v133, v133
	v_lshlrev_b32_e32 v134, 16, v222
	v_and_b32_e32 v135, 0xffff0000, v222
	v_lshlrev_b32_e32 v136, 16, v223
	v_and_b32_e32 v137, 0xffff0000, v223
	v_add_f32_e32 v130, 1.0, v130
	v_add_f32_e32 v131, 1.0, v131
	v_add_f32_e32 v132, 1.0, v132
	v_add_f32_e32 v133, 1.0, v133
	v_rcp_f32_e32 v130, v130
	v_rcp_f32_e32 v131, v131
	v_rcp_f32_e32 v132, v132
	v_rcp_f32_e32 v133, v133
	s_nop 0
	v_fmac_f32_e32 v134, v70, v130
	v_fmac_f32_e32 v135, v71, v131
	v_fmac_f32_e32 v136, v72, v132
	v_fmac_f32_e32 v137, v73, v133
	v_cvt_pk_bf16_f32 v70, v134, v135
	v_cvt_pk_bf16_f32 v71, v136, v137
	v_lshlrev_b32_e32 v130, 16, v220
	v_and_b32_e32 v131, 0xffff0000, v220
	v_lshlrev_b32_e32 v132, 16, v221
	v_and_b32_e32 v133, 0xffff0000, v221
	v_mul_f32_e32 v130, 0xbfb8aa3b, v130
	v_mul_f32_e32 v131, 0xbfb8aa3b, v131
	v_mul_f32_e32 v132, 0xbfb8aa3b, v132
	v_mul_f32_e32 v133, 0xbfb8aa3b, v133
	v_exp_f32_e32 v130, v130
	v_exp_f32_e32 v131, v131
	v_exp_f32_e32 v132, v132
	v_exp_f32_e32 v133, v133
	v_lshlrev_b32_e32 v134, 16, v224
	v_and_b32_e32 v135, 0xffff0000, v224
	v_lshlrev_b32_e32 v136, 16, v225
	v_and_b32_e32 v137, 0xffff0000, v225
	v_add_f32_e32 v130, 1.0, v130
	v_add_f32_e32 v131, 1.0, v131
	v_add_f32_e32 v132, 1.0, v132
	v_add_f32_e32 v133, 1.0, v133
	v_rcp_f32_e32 v130, v130
	v_rcp_f32_e32 v131, v131
	v_rcp_f32_e32 v132, v132
	v_rcp_f32_e32 v133, v133
	s_nop 0
	v_fmac_f32_e32 v134, v66, v130
	v_fmac_f32_e32 v135, v67, v131
	v_fmac_f32_e32 v136, v68, v132
	v_fmac_f32_e32 v137, v69, v133
	v_cvt_pk_bf16_f32 v72, v134, v135
	v_cvt_pk_bf16_f32 v73, v136, v137
	global_load_dwordx4 v[210:213], v[138:139], off
	global_load_dwordx4 v[214:217], v[140:141], off
	global_load_dwordx4 v[218:221], v[138:139], off offset:256
	global_load_dwordx4 v[222:225], v[140:141], off offset:256
	v_lshl_add_u64 v[138:139], v[138:139], 0, s[0:1]
	v_lshl_add_u64 v[140:141], v[140:141], 0, s[34:35]
	global_store_dwordx4 v[142:143], v[78:81], off
	global_store_dwordx4 v[142:143], v[70:73], off offset:256
	v_lshl_add_u64 v[142:143], v[142:143], 0, s[38:39]
	s_waitcnt vmcnt(14)
	v_cndmask_b32_e64 v230, 0, v230, s[6:7]
	v_cndmask_b32_e64 v231, 0, v231, s[6:7]
	v_cndmask_b32_e64 v232, 0, v232, s[6:7]
	v_cndmask_b32_e64 v233, 0, v233, s[6:7]
	v_lshlrev_b32_e32 v130, 16, v226
	v_and_b32_e32 v131, 0xffff0000, v226
	v_lshlrev_b32_e32 v132, 16, v227
	v_and_b32_e32 v133, 0xffff0000, v227
	v_mul_f32_e32 v130, 0xbfb8aa3b, v130
	v_mul_f32_e32 v131, 0xbfb8aa3b, v131
	v_mul_f32_e32 v132, 0xbfb8aa3b, v132
	v_mul_f32_e32 v133, 0xbfb8aa3b, v133
	v_exp_f32_e32 v130, v130
	v_exp_f32_e32 v131, v131
	v_exp_f32_e32 v132, v132
	v_exp_f32_e32 v133, v133
	v_lshlrev_b32_e32 v134, 16, v230
	v_and_b32_e32 v135, 0xffff0000, v230
	v_lshlrev_b32_e32 v136, 16, v231
	v_and_b32_e32 v137, 0xffff0000, v231
	v_add_f32_e32 v130, 1.0, v130
	v_add_f32_e32 v131, 1.0, v131
	v_add_f32_e32 v132, 1.0, v132
	v_add_f32_e32 v133, 1.0, v133
	v_rcp_f32_e32 v130, v130
	v_rcp_f32_e32 v131, v131
	v_rcp_f32_e32 v132, v132
	v_rcp_f32_e32 v133, v133
	s_nop 0
	v_fmac_f32_e32 v134, v62, v130
	v_fmac_f32_e32 v135, v63, v131
	v_fmac_f32_e32 v136, v64, v132
	v_fmac_f32_e32 v137, v65, v133
	v_cvt_pk_bf16_f32 v62, v134, v135
	v_cvt_pk_bf16_f32 v63, v136, v137
	v_lshlrev_b32_e32 v130, 16, v228
	v_and_b32_e32 v131, 0xffff0000, v228
	v_lshlrev_b32_e32 v132, 16, v229
	v_and_b32_e32 v133, 0xffff0000, v229
	v_mul_f32_e32 v130, 0xbfb8aa3b, v130
	v_mul_f32_e32 v131, 0xbfb8aa3b, v131
	v_mul_f32_e32 v132, 0xbfb8aa3b, v132
	v_mul_f32_e32 v133, 0xbfb8aa3b, v133
	v_exp_f32_e32 v130, v130
	v_exp_f32_e32 v131, v131
	v_exp_f32_e32 v132, v132
	v_exp_f32_e32 v133, v133
	v_lshlrev_b32_e32 v134, 16, v232
	v_and_b32_e32 v135, 0xffff0000, v232
	v_lshlrev_b32_e32 v136, 16, v233
	v_and_b32_e32 v137, 0xffff0000, v233
	v_add_f32_e32 v130, 1.0, v130
	v_add_f32_e32 v131, 1.0, v131
	v_add_f32_e32 v132, 1.0, v132
	v_add_f32_e32 v133, 1.0, v133
	v_rcp_f32_e32 v130, v130
	v_rcp_f32_e32 v131, v131
	v_rcp_f32_e32 v132, v132
	v_rcp_f32_e32 v133, v133
	s_nop 0
	v_fmac_f32_e32 v134, v58, v130
	v_fmac_f32_e32 v135, v59, v131
	v_fmac_f32_e32 v136, v60, v132
	v_fmac_f32_e32 v137, v61, v133
	v_cvt_pk_bf16_f32 v64, v134, v135
	v_cvt_pk_bf16_f32 v65, v136, v137
	v_cndmask_b32_e64 v238, 0, v238, s[6:7]
	v_cndmask_b32_e64 v239, 0, v239, s[6:7]
	v_cndmask_b32_e64 v240, 0, v240, s[6:7]
	v_cndmask_b32_e64 v241, 0, v241, s[6:7]
	v_lshlrev_b32_e32 v130, 16, v234
	v_and_b32_e32 v131, 0xffff0000, v234
	v_lshlrev_b32_e32 v132, 16, v235
	v_and_b32_e32 v133, 0xffff0000, v235
	v_mul_f32_e32 v130, 0xbfb8aa3b, v130
	v_mul_f32_e32 v131, 0xbfb8aa3b, v131
	v_mul_f32_e32 v132, 0xbfb8aa3b, v132
	v_mul_f32_e32 v133, 0xbfb8aa3b, v133
	v_exp_f32_e32 v130, v130
	v_exp_f32_e32 v131, v131
	v_exp_f32_e32 v132, v132
	v_exp_f32_e32 v133, v133
	v_lshlrev_b32_e32 v134, 16, v238
	v_and_b32_e32 v135, 0xffff0000, v238
	v_lshlrev_b32_e32 v136, 16, v239
	v_and_b32_e32 v137, 0xffff0000, v239
	v_add_f32_e32 v130, 1.0, v130
	v_add_f32_e32 v131, 1.0, v131
	v_add_f32_e32 v132, 1.0, v132
	v_add_f32_e32 v133, 1.0, v133
	v_rcp_f32_e32 v130, v130
	v_rcp_f32_e32 v131, v131
	v_rcp_f32_e32 v132, v132
	v_rcp_f32_e32 v133, v133
	s_nop 0
	v_fmac_f32_e32 v134, v54, v130
	v_fmac_f32_e32 v135, v55, v131
	v_fmac_f32_e32 v136, v56, v132
	v_fmac_f32_e32 v137, v57, v133
	v_cvt_pk_bf16_f32 v54, v134, v135
	v_cvt_pk_bf16_f32 v55, v136, v137
	v_lshlrev_b32_e32 v130, 16, v236
	v_and_b32_e32 v131, 0xffff0000, v236
	v_lshlrev_b32_e32 v132, 16, v237
	v_and_b32_e32 v133, 0xffff0000, v237
	v_mul_f32_e32 v130, 0xbfb8aa3b, v130
	v_mul_f32_e32 v131, 0xbfb8aa3b, v131
	v_mul_f32_e32 v132, 0xbfb8aa3b, v132
	v_mul_f32_e32 v133, 0xbfb8aa3b, v133
	v_exp_f32_e32 v130, v130
	v_exp_f32_e32 v131, v131
	v_exp_f32_e32 v132, v132
	v_exp_f32_e32 v133, v133
	v_lshlrev_b32_e32 v134, 16, v240
	v_and_b32_e32 v135, 0xffff0000, v240
	v_lshlrev_b32_e32 v136, 16, v241
	v_and_b32_e32 v137, 0xffff0000, v241
	v_add_f32_e32 v130, 1.0, v130
	v_add_f32_e32 v131, 1.0, v131
	v_add_f32_e32 v132, 1.0, v132
	v_add_f32_e32 v133, 1.0, v133
	v_rcp_f32_e32 v130, v130
	v_rcp_f32_e32 v131, v131
	v_rcp_f32_e32 v132, v132
	v_rcp_f32_e32 v133, v133
	s_nop 0
	v_fmac_f32_e32 v134, v50, v130
	v_fmac_f32_e32 v135, v51, v131
	v_fmac_f32_e32 v136, v52, v132
	v_fmac_f32_e32 v137, v53, v133
	v_cvt_pk_bf16_f32 v56, v134, v135
	v_cvt_pk_bf16_f32 v57, v136, v137
	global_load_dwordx4 v[226:229], v[138:139], off
	global_load_dwordx4 v[230:233], v[140:141], off
	global_load_dwordx4 v[234:237], v[138:139], off offset:256
	global_load_dwordx4 v[238:241], v[140:141], off offset:256
	global_store_dwordx4 v[142:143], v[62:65], off
	global_store_dwordx4 v[142:143], v[54:57], off offset:256
	v_lshl_add_u64 v[142:143], v[142:143], 0, s[34:35]
	s_waitcnt vmcnt(14)
	v_cndmask_b32_e64 v186, 0, v186, s[6:7]
	v_cndmask_b32_e64 v187, 0, v187, s[6:7]
	v_cndmask_b32_e64 v188, 0, v188, s[6:7]
	v_cndmask_b32_e64 v189, 0, v189, s[6:7]
	v_lshlrev_b32_e32 v130, 16, v182
	v_and_b32_e32 v131, 0xffff0000, v182
	v_lshlrev_b32_e32 v132, 16, v183
	v_and_b32_e32 v133, 0xffff0000, v183
	v_mul_f32_e32 v130, 0xbfb8aa3b, v130
	v_mul_f32_e32 v131, 0xbfb8aa3b, v131
	v_mul_f32_e32 v132, 0xbfb8aa3b, v132
	v_mul_f32_e32 v133, 0xbfb8aa3b, v133
	v_exp_f32_e32 v130, v130
	v_exp_f32_e32 v131, v131
	v_exp_f32_e32 v132, v132
	v_exp_f32_e32 v133, v133
	v_lshlrev_b32_e32 v134, 16, v186
	v_and_b32_e32 v135, 0xffff0000, v186
	v_lshlrev_b32_e32 v136, 16, v187
	v_and_b32_e32 v137, 0xffff0000, v187
	v_add_f32_e32 v130, 1.0, v130
	v_add_f32_e32 v131, 1.0, v131
	v_add_f32_e32 v132, 1.0, v132
	v_add_f32_e32 v133, 1.0, v133
	v_rcp_f32_e32 v130, v130
	v_rcp_f32_e32 v131, v131
	v_rcp_f32_e32 v132, v132
	v_rcp_f32_e32 v133, v133
	s_nop 0
	v_fmac_f32_e32 v134, v46, v130
	v_fmac_f32_e32 v135, v47, v131
	v_fmac_f32_e32 v136, v48, v132
	v_fmac_f32_e32 v137, v49, v133
	v_cvt_pk_bf16_f32 v46, v134, v135
	v_cvt_pk_bf16_f32 v47, v136, v137
	v_lshlrev_b32_e32 v130, 16, v184
	v_and_b32_e32 v131, 0xffff0000, v184
	v_lshlrev_b32_e32 v132, 16, v185
	v_and_b32_e32 v133, 0xffff0000, v185
	v_mul_f32_e32 v130, 0xbfb8aa3b, v130
	v_mul_f32_e32 v131, 0xbfb8aa3b, v131
	v_mul_f32_e32 v132, 0xbfb8aa3b, v132
	v_mul_f32_e32 v133, 0xbfb8aa3b, v133
	v_exp_f32_e32 v130, v130
	v_exp_f32_e32 v131, v131
	v_exp_f32_e32 v132, v132
	v_exp_f32_e32 v133, v133
	v_lshlrev_b32_e32 v134, 16, v188
	v_and_b32_e32 v135, 0xffff0000, v188
	v_lshlrev_b32_e32 v136, 16, v189
	v_and_b32_e32 v137, 0xffff0000, v189
	v_add_f32_e32 v130, 1.0, v130
	v_add_f32_e32 v131, 1.0, v131
	v_add_f32_e32 v132, 1.0, v132
	v_add_f32_e32 v133, 1.0, v133
	v_rcp_f32_e32 v130, v130
	v_rcp_f32_e32 v131, v131
	v_rcp_f32_e32 v132, v132
	v_rcp_f32_e32 v133, v133
	s_nop 0
	v_fmac_f32_e32 v134, v42, v130
	v_fmac_f32_e32 v135, v43, v131
	v_fmac_f32_e32 v136, v44, v132
	v_fmac_f32_e32 v137, v45, v133
	v_cvt_pk_bf16_f32 v48, v134, v135
	v_cvt_pk_bf16_f32 v49, v136, v137
	v_cndmask_b32_e64 v242, 0, v242, s[6:7]
	v_cndmask_b32_e64 v243, 0, v243, s[6:7]
	v_cndmask_b32_e64 v244, 0, v244, s[6:7]
	v_cndmask_b32_e64 v245, 0, v245, s[6:7]
	v_lshlrev_b32_e32 v130, 16, v190
	v_and_b32_e32 v131, 0xffff0000, v190
	v_lshlrev_b32_e32 v132, 16, v191
	v_and_b32_e32 v133, 0xffff0000, v191
	v_mul_f32_e32 v130, 0xbfb8aa3b, v130
	v_mul_f32_e32 v131, 0xbfb8aa3b, v131
	v_mul_f32_e32 v132, 0xbfb8aa3b, v132
	v_mul_f32_e32 v133, 0xbfb8aa3b, v133
	v_exp_f32_e32 v130, v130
	v_exp_f32_e32 v131, v131
	v_exp_f32_e32 v132, v132
	v_exp_f32_e32 v133, v133
	v_lshlrev_b32_e32 v134, 16, v242
	v_and_b32_e32 v135, 0xffff0000, v242
	v_lshlrev_b32_e32 v136, 16, v243
	v_and_b32_e32 v137, 0xffff0000, v243
	v_add_f32_e32 v130, 1.0, v130
	v_add_f32_e32 v131, 1.0, v131
	v_add_f32_e32 v132, 1.0, v132
	v_add_f32_e32 v133, 1.0, v133
	v_rcp_f32_e32 v130, v130
	v_rcp_f32_e32 v131, v131
	v_rcp_f32_e32 v132, v132
	v_rcp_f32_e32 v133, v133
	s_nop 0
	v_fmac_f32_e32 v134, v38, v130
	v_fmac_f32_e32 v135, v39, v131
	v_fmac_f32_e32 v136, v40, v132
	v_fmac_f32_e32 v137, v41, v133
	v_cvt_pk_bf16_f32 v38, v134, v135
	v_cvt_pk_bf16_f32 v39, v136, v137
	v_lshlrev_b32_e32 v130, 16, v192
	v_and_b32_e32 v131, 0xffff0000, v192
	v_lshlrev_b32_e32 v132, 16, v193
	v_and_b32_e32 v133, 0xffff0000, v193
	v_mul_f32_e32 v130, 0xbfb8aa3b, v130
	v_mul_f32_e32 v131, 0xbfb8aa3b, v131
	v_mul_f32_e32 v132, 0xbfb8aa3b, v132
	v_mul_f32_e32 v133, 0xbfb8aa3b, v133
	v_exp_f32_e32 v130, v130
	v_exp_f32_e32 v131, v131
	v_exp_f32_e32 v132, v132
	v_exp_f32_e32 v133, v133
	v_lshlrev_b32_e32 v134, 16, v244
	v_and_b32_e32 v135, 0xffff0000, v244
	v_lshlrev_b32_e32 v136, 16, v245
	v_and_b32_e32 v137, 0xffff0000, v245
	v_add_f32_e32 v130, 1.0, v130
	v_add_f32_e32 v131, 1.0, v131
	v_add_f32_e32 v132, 1.0, v132
	v_add_f32_e32 v133, 1.0, v133
	v_rcp_f32_e32 v130, v130
	v_rcp_f32_e32 v131, v131
	v_rcp_f32_e32 v132, v132
	v_rcp_f32_e32 v133, v133
	s_nop 0
	v_fmac_f32_e32 v134, v34, v130
	v_fmac_f32_e32 v135, v35, v131
	v_fmac_f32_e32 v136, v36, v132
	v_fmac_f32_e32 v137, v37, v133
	v_cvt_pk_bf16_f32 v40, v134, v135
	v_cvt_pk_bf16_f32 v41, v136, v137
	global_store_dwordx4 v[142:143], v[46:49], off
	global_store_dwordx4 v[142:143], v[38:41], off offset:256
	v_lshl_add_u64 v[142:143], v[142:143], 0, s[34:35]
	s_waitcnt vmcnt(10)
	v_cndmask_b32_e64 v214, 0, v214, s[6:7]
	v_cndmask_b32_e64 v215, 0, v215, s[6:7]
	v_cndmask_b32_e64 v216, 0, v216, s[6:7]
	v_cndmask_b32_e64 v217, 0, v217, s[6:7]
	v_lshlrev_b32_e32 v130, 16, v210
	v_and_b32_e32 v131, 0xffff0000, v210
	v_lshlrev_b32_e32 v132, 16, v211
	v_and_b32_e32 v133, 0xffff0000, v211
	v_mul_f32_e32 v130, 0xbfb8aa3b, v130
	v_mul_f32_e32 v131, 0xbfb8aa3b, v131
	v_mul_f32_e32 v132, 0xbfb8aa3b, v132
	v_mul_f32_e32 v133, 0xbfb8aa3b, v133
	v_exp_f32_e32 v130, v130
	v_exp_f32_e32 v131, v131
	v_exp_f32_e32 v132, v132
	v_exp_f32_e32 v133, v133
	v_lshlrev_b32_e32 v134, 16, v214
	v_and_b32_e32 v135, 0xffff0000, v214
	v_lshlrev_b32_e32 v136, 16, v215
	v_and_b32_e32 v137, 0xffff0000, v215
	v_add_f32_e32 v130, 1.0, v130
	v_add_f32_e32 v131, 1.0, v131
	v_add_f32_e32 v132, 1.0, v132
	v_add_f32_e32 v133, 1.0, v133
	v_rcp_f32_e32 v130, v130
	v_rcp_f32_e32 v131, v131
	v_rcp_f32_e32 v132, v132
	v_rcp_f32_e32 v133, v133
	s_nop 0
	v_fmac_f32_e32 v134, v30, v130
	v_fmac_f32_e32 v135, v31, v131
	v_fmac_f32_e32 v136, v32, v132
	v_fmac_f32_e32 v137, v33, v133
	v_cvt_pk_bf16_f32 v30, v134, v135
	v_cvt_pk_bf16_f32 v31, v136, v137
	v_lshlrev_b32_e32 v130, 16, v212
	v_and_b32_e32 v131, 0xffff0000, v212
	v_lshlrev_b32_e32 v132, 16, v213
	v_and_b32_e32 v133, 0xffff0000, v213
	v_mul_f32_e32 v130, 0xbfb8aa3b, v130
	v_mul_f32_e32 v131, 0xbfb8aa3b, v131
	v_mul_f32_e32 v132, 0xbfb8aa3b, v132
	v_mul_f32_e32 v133, 0xbfb8aa3b, v133
	v_exp_f32_e32 v130, v130
	v_exp_f32_e32 v131, v131
	v_exp_f32_e32 v132, v132
	v_exp_f32_e32 v133, v133
	v_lshlrev_b32_e32 v134, 16, v216
	v_and_b32_e32 v135, 0xffff0000, v216
	v_lshlrev_b32_e32 v136, 16, v217
	v_and_b32_e32 v137, 0xffff0000, v217
	v_add_f32_e32 v130, 1.0, v130
	v_add_f32_e32 v131, 1.0, v131
	v_add_f32_e32 v132, 1.0, v132
	v_add_f32_e32 v133, 1.0, v133
	v_rcp_f32_e32 v130, v130
	v_rcp_f32_e32 v131, v131
	v_rcp_f32_e32 v132, v132
	v_rcp_f32_e32 v133, v133
	s_nop 0
	v_fmac_f32_e32 v134, v26, v130
	v_fmac_f32_e32 v135, v27, v131
	v_fmac_f32_e32 v136, v28, v132
	v_fmac_f32_e32 v137, v29, v133
	v_cvt_pk_bf16_f32 v32, v134, v135
	v_cvt_pk_bf16_f32 v33, v136, v137
	v_cndmask_b32_e64 v222, 0, v222, s[6:7]
	v_cndmask_b32_e64 v223, 0, v223, s[6:7]
	v_cndmask_b32_e64 v224, 0, v224, s[6:7]
	v_cndmask_b32_e64 v225, 0, v225, s[6:7]
	v_lshlrev_b32_e32 v130, 16, v218
	v_and_b32_e32 v131, 0xffff0000, v218
	v_lshlrev_b32_e32 v132, 16, v219
	v_and_b32_e32 v133, 0xffff0000, v219
	v_mul_f32_e32 v130, 0xbfb8aa3b, v130
	v_mul_f32_e32 v131, 0xbfb8aa3b, v131
	v_mul_f32_e32 v132, 0xbfb8aa3b, v132
	v_mul_f32_e32 v133, 0xbfb8aa3b, v133
	v_exp_f32_e32 v130, v130
	v_exp_f32_e32 v131, v131
	v_exp_f32_e32 v132, v132
	v_exp_f32_e32 v133, v133
	v_lshlrev_b32_e32 v134, 16, v222
	v_and_b32_e32 v135, 0xffff0000, v222
	v_lshlrev_b32_e32 v136, 16, v223
	v_and_b32_e32 v137, 0xffff0000, v223
	v_add_f32_e32 v130, 1.0, v130
	v_add_f32_e32 v131, 1.0, v131
	v_add_f32_e32 v132, 1.0, v132
	v_add_f32_e32 v133, 1.0, v133
	v_rcp_f32_e32 v130, v130
	v_rcp_f32_e32 v131, v131
	v_rcp_f32_e32 v132, v132
	v_rcp_f32_e32 v133, v133
	s_nop 0
	v_fmac_f32_e32 v134, v22, v130
	v_fmac_f32_e32 v135, v23, v131
	v_fmac_f32_e32 v136, v24, v132
	v_fmac_f32_e32 v137, v25, v133
	v_cvt_pk_bf16_f32 v22, v134, v135
	v_cvt_pk_bf16_f32 v23, v136, v137
	v_lshlrev_b32_e32 v130, 16, v220
	v_and_b32_e32 v131, 0xffff0000, v220
	v_lshlrev_b32_e32 v132, 16, v221
	v_and_b32_e32 v133, 0xffff0000, v221
	v_mul_f32_e32 v130, 0xbfb8aa3b, v130
	v_mul_f32_e32 v131, 0xbfb8aa3b, v131
	v_mul_f32_e32 v132, 0xbfb8aa3b, v132
	v_mul_f32_e32 v133, 0xbfb8aa3b, v133
	v_exp_f32_e32 v130, v130
	v_exp_f32_e32 v131, v131
	v_exp_f32_e32 v132, v132
	v_exp_f32_e32 v133, v133
	v_lshlrev_b32_e32 v134, 16, v224
	v_and_b32_e32 v135, 0xffff0000, v224
	v_lshlrev_b32_e32 v136, 16, v225
	v_and_b32_e32 v137, 0xffff0000, v225
	v_add_f32_e32 v130, 1.0, v130
	v_add_f32_e32 v131, 1.0, v131
	v_add_f32_e32 v132, 1.0, v132
	v_add_f32_e32 v133, 1.0, v133
	v_rcp_f32_e32 v130, v130
	v_rcp_f32_e32 v131, v131
	v_rcp_f32_e32 v132, v132
	v_rcp_f32_e32 v133, v133
	s_nop 0
	v_fmac_f32_e32 v134, v18, v130
	v_fmac_f32_e32 v135, v19, v131
	v_fmac_f32_e32 v136, v20, v132
	v_fmac_f32_e32 v137, v21, v133
	v_cvt_pk_bf16_f32 v24, v134, v135
	v_cvt_pk_bf16_f32 v25, v136, v137
	global_store_dwordx4 v[142:143], v[30:33], off
	global_store_dwordx4 v[142:143], v[22:25], off offset:256
	v_lshl_add_u64 v[142:143], v[142:143], 0, s[34:35]
	s_waitcnt vmcnt(6)
	v_cndmask_b32_e64 v230, 0, v230, s[6:7]
	v_cndmask_b32_e64 v231, 0, v231, s[6:7]
	v_cndmask_b32_e64 v232, 0, v232, s[6:7]
	v_cndmask_b32_e64 v233, 0, v233, s[6:7]
	v_lshlrev_b32_e32 v130, 16, v226
	v_and_b32_e32 v131, 0xffff0000, v226
	v_lshlrev_b32_e32 v132, 16, v227
	v_and_b32_e32 v133, 0xffff0000, v227
	v_mul_f32_e32 v130, 0xbfb8aa3b, v130
	v_mul_f32_e32 v131, 0xbfb8aa3b, v131
	v_mul_f32_e32 v132, 0xbfb8aa3b, v132
	v_mul_f32_e32 v133, 0xbfb8aa3b, v133
	v_exp_f32_e32 v130, v130
	v_exp_f32_e32 v131, v131
	v_exp_f32_e32 v132, v132
	v_exp_f32_e32 v133, v133
	v_lshlrev_b32_e32 v134, 16, v230
	v_and_b32_e32 v135, 0xffff0000, v230
	v_lshlrev_b32_e32 v136, 16, v231
	v_and_b32_e32 v137, 0xffff0000, v231
	v_add_f32_e32 v130, 1.0, v130
	v_add_f32_e32 v131, 1.0, v131
	v_add_f32_e32 v132, 1.0, v132
	v_add_f32_e32 v133, 1.0, v133
	v_rcp_f32_e32 v130, v130
	v_rcp_f32_e32 v131, v131
	v_rcp_f32_e32 v132, v132
	v_rcp_f32_e32 v133, v133
	s_nop 0
	v_fmac_f32_e32 v134, v14, v130
	v_fmac_f32_e32 v135, v15, v131
	v_fmac_f32_e32 v136, v16, v132
	v_fmac_f32_e32 v137, v17, v133
	v_cvt_pk_bf16_f32 v14, v134, v135
	v_cvt_pk_bf16_f32 v15, v136, v137
	v_lshlrev_b32_e32 v130, 16, v228
	v_and_b32_e32 v131, 0xffff0000, v228
	v_lshlrev_b32_e32 v132, 16, v229
	v_and_b32_e32 v133, 0xffff0000, v229
	v_mul_f32_e32 v130, 0xbfb8aa3b, v130
	v_mul_f32_e32 v131, 0xbfb8aa3b, v131
	v_mul_f32_e32 v132, 0xbfb8aa3b, v132
	v_mul_f32_e32 v133, 0xbfb8aa3b, v133
	v_exp_f32_e32 v130, v130
	v_exp_f32_e32 v131, v131
	v_exp_f32_e32 v132, v132
	v_exp_f32_e32 v133, v133
	v_lshlrev_b32_e32 v134, 16, v232
	v_and_b32_e32 v135, 0xffff0000, v232
	v_lshlrev_b32_e32 v136, 16, v233
	v_and_b32_e32 v137, 0xffff0000, v233
	v_add_f32_e32 v130, 1.0, v130
	v_add_f32_e32 v131, 1.0, v131
	v_add_f32_e32 v132, 1.0, v132
	v_add_f32_e32 v133, 1.0, v133
	v_rcp_f32_e32 v130, v130
	v_rcp_f32_e32 v131, v131
	v_rcp_f32_e32 v132, v132
	v_rcp_f32_e32 v133, v133
	s_nop 0
	v_fmac_f32_e32 v134, v10, v130
	v_fmac_f32_e32 v135, v11, v131
	v_fmac_f32_e32 v136, v12, v132
	v_fmac_f32_e32 v137, v13, v133
	v_cvt_pk_bf16_f32 v16, v134, v135
	v_cvt_pk_bf16_f32 v17, v136, v137
	v_cndmask_b32_e64 v238, 0, v238, s[6:7]
	v_cndmask_b32_e64 v239, 0, v239, s[6:7]
	v_cndmask_b32_e64 v240, 0, v240, s[6:7]
	v_cndmask_b32_e64 v241, 0, v241, s[6:7]
	v_lshlrev_b32_e32 v130, 16, v234
	v_and_b32_e32 v131, 0xffff0000, v234
	v_lshlrev_b32_e32 v132, 16, v235
	v_and_b32_e32 v133, 0xffff0000, v235
	v_mul_f32_e32 v130, 0xbfb8aa3b, v130
	v_mul_f32_e32 v131, 0xbfb8aa3b, v131
	v_mul_f32_e32 v132, 0xbfb8aa3b, v132
	v_mul_f32_e32 v133, 0xbfb8aa3b, v133
	v_exp_f32_e32 v130, v130
	v_exp_f32_e32 v131, v131
	v_exp_f32_e32 v132, v132
	v_exp_f32_e32 v133, v133
	v_lshlrev_b32_e32 v134, 16, v238
	v_and_b32_e32 v135, 0xffff0000, v238
	v_lshlrev_b32_e32 v136, 16, v239
	v_and_b32_e32 v137, 0xffff0000, v239
	v_add_f32_e32 v130, 1.0, v130
	v_add_f32_e32 v131, 1.0, v131
	v_add_f32_e32 v132, 1.0, v132
	v_add_f32_e32 v133, 1.0, v133
	v_rcp_f32_e32 v130, v130
	v_rcp_f32_e32 v131, v131
	v_rcp_f32_e32 v132, v132
	v_rcp_f32_e32 v133, v133
	s_nop 0
	v_fmac_f32_e32 v134, v6, v130
	v_fmac_f32_e32 v135, v7, v131
	v_fmac_f32_e32 v136, v8, v132
	v_fmac_f32_e32 v137, v9, v133
	v_cvt_pk_bf16_f32 v6, v134, v135
	v_cvt_pk_bf16_f32 v7, v136, v137
	v_lshlrev_b32_e32 v130, 16, v236
	v_and_b32_e32 v131, 0xffff0000, v236
	v_lshlrev_b32_e32 v132, 16, v237
	v_and_b32_e32 v133, 0xffff0000, v237
	v_mul_f32_e32 v130, 0xbfb8aa3b, v130
	v_mul_f32_e32 v131, 0xbfb8aa3b, v131
	v_mul_f32_e32 v132, 0xbfb8aa3b, v132
	v_mul_f32_e32 v133, 0xbfb8aa3b, v133
	v_exp_f32_e32 v130, v130
	v_exp_f32_e32 v131, v131
	v_exp_f32_e32 v132, v132
	v_exp_f32_e32 v133, v133
	v_lshlrev_b32_e32 v134, 16, v240
	v_and_b32_e32 v135, 0xffff0000, v240
	v_lshlrev_b32_e32 v136, 16, v241
	v_and_b32_e32 v137, 0xffff0000, v241
	v_add_f32_e32 v130, 1.0, v130
	v_add_f32_e32 v131, 1.0, v131
	v_add_f32_e32 v132, 1.0, v132
	v_add_f32_e32 v133, 1.0, v133
	v_rcp_f32_e32 v130, v130
	v_rcp_f32_e32 v131, v131
	v_rcp_f32_e32 v132, v132
	v_rcp_f32_e32 v133, v133
	s_nop 0
	v_fmac_f32_e32 v134, v2, v130
	v_fmac_f32_e32 v135, v3, v131
	v_fmac_f32_e32 v136, v4, v132
	v_fmac_f32_e32 v137, v5, v133
	v_cvt_pk_bf16_f32 v8, v134, v135
	v_cvt_pk_bf16_f32 v9, v136, v137
	global_store_dwordx4 v[142:143], v[14:17], off
	global_store_dwordx4 v[142:143], v[6:9], off offset:256
	s_movk_i32 s8, 0xfa00
	s_mov_b32 s9, -1
	s_mov_b64 s[0:1], -1
	s_and_b64 vcc, exec, s[40:41]
	s_cbranch_vccnz .LBB0_194
	s_andn2_b64 vcc, exec, s[24:25]
	v_mov_b64 v[126:127], 0
	v_mov_b64 v[128:129], 0
	v_mov_b64 v[122:123], 0
	v_mov_b64 v[124:125], 0
	v_mov_b64 v[110:111], 0
	v_mov_b64 v[112:113], 0
	v_mov_b64 v[106:107], 0
	v_mov_b64 v[108:109], 0
	v_mov_b64 v[94:95], 0
	v_mov_b64 v[96:97], 0
	v_mov_b64 v[90:91], 0
	v_mov_b64 v[92:93], 0
	v_mov_b64 v[78:79], 0
	v_mov_b64 v[80:81], 0
	v_mov_b64 v[74:75], 0
	v_mov_b64 v[76:77], 0
	v_mov_b64 v[118:119], 0
	v_mov_b64 v[120:121], 0
	v_mov_b64 v[114:115], 0
	v_mov_b64 v[116:117], 0
	v_mov_b64 v[102:103], 0
	v_mov_b64 v[104:105], 0
	v_mov_b64 v[98:99], 0
	v_mov_b64 v[100:101], 0
	v_mov_b64 v[86:87], 0
	v_mov_b64 v[88:89], 0
	v_mov_b64 v[82:83], 0
	v_mov_b64 v[84:85], 0
	v_mov_b64 v[70:71], 0
	v_mov_b64 v[72:73], 0
	v_mov_b64 v[66:67], 0
	v_mov_b64 v[68:69], 0
	v_mov_b64 v[62:63], 0
	v_mov_b64 v[64:65], 0
	v_mov_b64 v[58:59], 0
	v_mov_b64 v[60:61], 0
	v_mov_b64 v[46:47], 0
	v_mov_b64 v[48:49], 0
	v_mov_b64 v[42:43], 0
	v_mov_b64 v[44:45], 0
	v_mov_b64 v[30:31], 0
	v_mov_b64 v[32:33], 0
	v_mov_b64 v[26:27], 0
	v_mov_b64 v[28:29], 0
	v_mov_b64 v[14:15], 0
	v_mov_b64 v[16:17], 0
	v_mov_b64 v[10:11], 0
	v_mov_b64 v[12:13], 0
	v_mov_b64 v[54:55], 0
	v_mov_b64 v[56:57], 0
	v_mov_b64 v[50:51], 0
	v_mov_b64 v[52:53], 0
	v_mov_b64 v[38:39], 0
	v_mov_b64 v[40:41], 0
	v_mov_b64 v[34:35], 0
	v_mov_b64 v[36:37], 0
	v_mov_b64 v[22:23], 0
	v_mov_b64 v[24:25], 0
	v_mov_b64 v[18:19], 0
	v_mov_b64 v[20:21], 0
	v_mov_b64 v[6:7], 0
	v_mov_b64 v[8:9], 0
	v_mov_b64 v[2:3], 0
	v_mov_b64 v[4:5], 0
	s_cbranch_vccnz .LBB0_193
	s_barrier
	s_branch .LBB0_193
